# strategy 9 (back-edge rotation): the scalar loop-carried updates and exit compare of all ten GEMM K-loops moved in front of the iteration's last barrier
# baseline (speedup 1.0000x reference)
; #define PG8_STAGE(bufoff, gbase, voff) do { _Pragma("unroll") for (int _i = 0; _i < 2; ++_i) \
;         __builtin_amdgcn_global_load_lds((const unsigned*)((const char*)(gbase) + (voff)[_i]), (PG8_LAS unsigned*)(lds + (bufoff) + ldsw + _i * 8192), 16, 0, 0); } while (0)
; #define PG8_STAGEB(bufoff, gbase, voff) do { _Pragma("unroll") for (int _i = 0; _i < 2; ++_i) \
;         __builtin_amdgcn_global_load_lds((const unsigned*)((const char*)(gbase) + (voff)[_i]), (PG8_LAS unsigned*)(lds + (bufoff) + ldsw + _i * 8192), 16, 0, PG8_BAUX); } while (0)
; #define PG8_LDA(dst, b, h) do { _Pragma("unroll") for (int m = 0; m < 4; ++m) _Pragma("unroll") for (int k = 0; k < 2; ++k) dst[m][k] = *(const PG8_LAS bf16x8*)(lds + PG8_SA(b, h) + aoff + m * 2048 + k * 1024); } while (0)
; #define PG8_LDB(dst, b, h) do { _Pragma("unroll") for (int n = 0; n < 2; ++n) _Pragma("unroll") for (int k = 0; k < 2; ++k) dst[n][k] = *(const PG8_LAS bf16x8*)(lds + PG8_SB(b, h) + boff + n * 2048 + k * 1024); } while (0)
; #define PG8_MMA(ai, bj, At, Bt) do { __builtin_amdgcn_s_setprio(1); _Pragma("unroll") for (int m = 0; m < 4; ++m) _Pragma("unroll") for (int n = 0; n < 2; ++n) _Pragma("unroll") for (int k = 0; k < 2; ++k) \
;         acc[ai][bj][m][n] = __builtin_amdgcn_mfma_f32_16x16x32_bf16(Bt[n][k], At[m][k], acc[ai][bj][m][n], 0, 0, 0); __builtin_amdgcn_s_setprio(0); } while (0)
; #define PG8_WAIT_V(n) asm volatile("s_waitcnt vmcnt(" #n ")" ::: "memory")
; #define PG8_WAIT_L(n) asm volatile("s_waitcnt lgkmcnt(" #n ")" ::: "memory")
; #define PG8_BAR __builtin_amdgcn_s_barrier()
; #define PG8_SCHED __builtin_amdgcn_sched_barrier(0)
; template <class Epi, class Sched, bool ALIGN_EPI = false, bool SP2 = false>
; __device__ __forceinline__ void gemm_phase(PG8_LAS unsigned char* lds, const Gemm g, const Sched& S, const Epi& E) {
;     ...
;             PG8_LDB(B0, 0, 0); PG8_LDB(B1, 0, 1); PG8_SCHED; PG8_LDA(At, 0, 0); PG8_STAGE(PG8_SA(1, 1), a1 + hstep, voffA);
;             PG8_WAIT_V(8); PG8_WAIT_L(0); PG8_BAR; PG8_MMA(0, 0, At, B0); PG8_MMA(0, 1, At, B1); PG8_BAR; PG8_SCHED;
;             PG8_LDA(At, 0, 1); PG8_STAGEB(PG8_SB(0, 0), b2, voffB); PG8_STAGEB(PG8_SB(0, 1), b2 + hstep, voffB); PG8_STAGE(PG8_SA(0, 0), a2, voffA);
.LBB0_365:
	ds_read_b128 v[162:165], v158
	ds_read_b128 v[166:169], v158 offset:1024
	ds_read_b128 v[170:173], v158 offset:2048
	ds_read_b128 v[174:177], v158 offset:3072
	ds_read_b128 v[178:181], v159
	ds_read_b128 v[182:185], v159 offset:1024
	ds_read_b128 v[186:189], v159 offset:2048
	ds_read_b128 v[192:195], v159 offset:3072
	s_add_u32 s30, s28, 0xfff80080
	s_addc_u32 s31, s29, -1
	s_cmp_eq_u32 s55, 28
	s_cselect_b32 s35, s21, s31
	s_cselect_b32 s34, s51, s30
	s_cselect_b32 s31, s19, s54
	s_cselect_b32 s30, s52, s53
	v_lshl_add_u64 v[228:229], s[28:29], 0, v[138:139]
	s_add_i32 m0, s40, 0xc000
	ds_read_b128 v[196:199], v160
	ds_read_b128 v[200:203], v160 offset:1024
	ds_read_b128 v[204:207], v160 offset:2048
	ds_read_b128 v[208:211], v160 offset:3072
	ds_read_b128 v[212:215], v160 offset:4096
	ds_read_b128 v[216:219], v160 offset:5120
	ds_read_b128 v[220:223], v160 offset:6144
	ds_read_b128 v[224:227], v160 offset:7168
	global_load_lds_dwordx4 v[228:229], off
	v_lshl_add_u64 v[228:229], s[28:29], 0, v[140:141]
	s_add_i32 m0, s40, 0xe000
	s_nop 0
	global_load_lds_dwordx4 v[228:229], off
	s_waitcnt vmcnt(8)
	s_waitcnt lgkmcnt(0)
	s_barrier
	s_setprio 1
	s_waitcnt lgkmcnt(0)
	v_mfma_f32_16x16x32_bf16 v[122:125], v[162:165], v[196:199], v[122:125]
	v_mfma_f32_16x16x32_bf16 v[118:121], v[170:173], v[196:199], v[118:121]
	v_mfma_f32_16x16x32_bf16 v[110:113], v[162:165], v[204:207], v[110:113]
	v_mfma_f32_16x16x32_bf16 v[102:105], v[170:173], v[204:207], v[102:105]
	v_mfma_f32_16x16x32_bf16 v[94:97], v[162:165], v[212:215], v[94:97]
	v_mfma_f32_16x16x32_bf16 v[86:89], v[170:173], v[212:215], v[86:89]
	v_mfma_f32_16x16x32_bf16 v[78:81], v[162:165], v[220:223], v[78:81]
	v_mfma_f32_16x16x32_bf16 v[70:73], v[170:173], v[220:223], v[70:73]
	v_mfma_f32_16x16x32_bf16 v[122:125], v[166:169], v[200:203], v[122:125]
	v_mfma_f32_16x16x32_bf16 v[118:121], v[174:177], v[200:203], v[118:121]
	v_mfma_f32_16x16x32_bf16 v[110:113], v[166:169], v[208:211], v[110:113]
	v_mfma_f32_16x16x32_bf16 v[102:105], v[174:177], v[208:211], v[102:105]
	v_mfma_f32_16x16x32_bf16 v[94:97], v[166:169], v[216:219], v[94:97]
	v_mfma_f32_16x16x32_bf16 v[86:89], v[174:177], v[216:219], v[86:89]
	v_mfma_f32_16x16x32_bf16 v[78:81], v[166:169], v[224:227], v[78:81]
	v_mfma_f32_16x16x32_bf16 v[70:73], v[174:177], v[224:227], v[70:73]
	s_setprio 0
	s_setprio 1
	v_mfma_f32_16x16x32_bf16 v[126:129], v[178:181], v[196:199], v[126:129]
	v_mfma_f32_16x16x32_bf16 v[114:117], v[186:189], v[196:199], v[114:117]
	v_mfma_f32_16x16x32_bf16 v[106:109], v[178:181], v[204:207], v[106:109]
	v_mfma_f32_16x16x32_bf16 v[98:101], v[186:189], v[204:207], v[98:101]
	v_mfma_f32_16x16x32_bf16 v[90:93], v[178:181], v[212:215], v[90:93]
	v_mfma_f32_16x16x32_bf16 v[82:85], v[186:189], v[212:215], v[82:85]
	v_mfma_f32_16x16x32_bf16 v[74:77], v[178:181], v[220:223], v[74:77]
	v_mfma_f32_16x16x32_bf16 v[66:69], v[186:189], v[220:223], v[66:69]
	v_mfma_f32_16x16x32_bf16 v[126:129], v[182:185], v[200:203], v[126:129]
	v_mfma_f32_16x16x32_bf16 v[114:117], v[192:195], v[200:203], v[114:117]
	v_mfma_f32_16x16x32_bf16 v[106:109], v[182:185], v[208:211], v[106:109]
	v_mfma_f32_16x16x32_bf16 v[98:101], v[192:195], v[208:211], v[98:101]
	v_mfma_f32_16x16x32_bf16 v[90:93], v[182:185], v[216:219], v[90:93]
	v_mfma_f32_16x16x32_bf16 v[82:85], v[192:195], v[216:219], v[82:85]
	v_mfma_f32_16x16x32_bf16 v[74:77], v[182:185], v[224:227], v[74:77]
	v_mfma_f32_16x16x32_bf16 v[66:69], v[192:195], v[224:227], v[66:69]
	s_setprio 0
	s_barrier
	s_add_i32 s56, s48, s33
	v_lshl_add_u64 v[228:229], s[30:31], 0, v[132:133]
	s_mov_b32 m0, s56
	ds_read_b128 v[196:199], v160 offset:16384
	ds_read_b128 v[200:203], v160 offset:17408
	ds_read_b128 v[204:207], v160 offset:18432
	ds_read_b128 v[208:211], v160 offset:19456
	ds_read_b128 v[212:215], v160 offset:20480
	ds_read_b128 v[216:219], v160 offset:21504
	ds_read_b128 v[220:223], v160 offset:22528
	ds_read_b128 v[224:227], v160 offset:23552
	global_load_lds_dwordx4 v[228:229], off
	s_add_i32 m0, s56, 0x2000
	s_add_u32 s56, s30, 0x80000
	v_lshl_add_u64 v[230:231], s[30:31], 0, v[136:137]
	s_addc_u32 s57, s31, 0
	s_add_i32 s58, s49, s33
	global_load_lds_dwordx4 v[230:231], off
	v_lshl_add_u64 v[232:233], s[56:57], 0, v[132:133]
	s_mov_b32 m0, s58
	v_lshl_add_u64 v[234:235], s[34:35], 0, v[134:135]
	global_load_lds_dwordx4 v[232:233], off
	v_lshl_add_u64 v[232:233], s[56:57], 0, v[136:137]
	s_add_i32 m0, s58, 0x2000
	s_nop 0
	global_load_lds_dwordx4 v[232:233], off
	v_lshl_add_u64 v[232:233], s[34:35], 0, v[130:131]
	s_mov_b32 m0, s40
	s_nop 0
	global_load_lds_dwordx4 v[232:233], off
	s_mov_b32 m0, s41
	s_nop 0
	global_load_lds_dwordx4 v[234:235], off
	s_waitcnt vmcnt(8)
	s_waitcnt lgkmcnt(0)
	s_barrier
; #define PG8_STAGE(bufoff, gbase, voff) do { _Pragma("unroll") for (int _i = 0; _i < 2; ++_i) \
;         __builtin_amdgcn_global_load_lds((const unsigned*)((const char*)(gbase) + (voff)[_i]), (PG8_LAS unsigned*)(lds + (bufoff) + ldsw + _i * 8192), 16, 0, 0); } while (0)
; #define PG8_LDA(dst, b, h) do { _Pragma("unroll") for (int m = 0; m < 4; ++m) _Pragma("unroll") for (int k = 0; k < 2; ++k) dst[m][k] = *(const PG8_LAS bf16x8*)(lds + PG8_SA(b, h) + aoff + m * 2048 + k * 1024); } while (0)
; #define PG8_LDB(dst, b, h) do { _Pragma("unroll") for (int n = 0; n < 2; ++n) _Pragma("unroll") for (int k = 0; k < 2; ++k) dst[n][k] = *(const PG8_LAS bf16x8*)(lds + PG8_SB(b, h) + boff + n * 2048 + k * 1024); } while (0)
; #define PG8_MMA(ai, bj, At, Bt) do { __builtin_amdgcn_s_setprio(1); _Pragma("unroll") for (int m = 0; m < 4; ++m) _Pragma("unroll") for (int n = 0; n < 2; ++n) _Pragma("unroll") for (int k = 0; k < 2; ++k) \
;         acc[ai][bj][m][n] = __builtin_amdgcn_mfma_f32_16x16x32_bf16(Bt[n][k], At[m][k], acc[ai][bj][m][n], 0, 0, 0); __builtin_amdgcn_s_setprio(0); } while (0)
; #define PG8_WAIT_V(n) asm volatile("s_waitcnt vmcnt(" #n ")" ::: "memory")
; #define PG8_WAIT_L(n) asm volatile("s_waitcnt lgkmcnt(" #n ")" ::: "memory")
; #define PG8_BAR __builtin_amdgcn_s_barrier()
; #define PG8_SCHED __builtin_amdgcn_sched_barrier(0)
; template <class Epi, class Sched, bool ALIGN_EPI = false, bool SP2 = false>
; __device__ __forceinline__ void gemm_phase(PG8_LAS unsigned char* lds, const Gemm g, const Sched& S, const Epi& E) {
;     ...
;             PG8_WAIT_V(8); PG8_WAIT_L(0); PG8_BAR; PG8_MMA(1, 0, At, B0); PG8_MMA(1, 1, At, B1); PG8_BAR; PG8_SCHED;
;             PG8_LDB(B0, 1, 0); PG8_LDB(B1, 1, 1); PG8_SCHED; PG8_LDA(At, 1, 0); PG8_STAGE(PG8_SA(0, 1), a2 + hstep, voffA);
;             PG8_WAIT_V(8); PG8_WAIT_L(0); PG8_BAR; PG8_MMA(0, 0, At, B0); PG8_MMA(0, 1, At, B1); PG8_BAR; PG8_SCHED;
	s_setprio 1
	s_waitcnt lgkmcnt(0)
	v_mfma_f32_16x16x32_bf16 v[62:65], v[162:165], v[196:199], v[62:65]
	v_mfma_f32_16x16x32_bf16 v[54:57], v[170:173], v[196:199], v[54:57]
	v_mfma_f32_16x16x32_bf16 v[46:49], v[162:165], v[204:207], v[46:49]
	v_mfma_f32_16x16x32_bf16 v[38:41], v[170:173], v[204:207], v[38:41]
	v_mfma_f32_16x16x32_bf16 v[30:33], v[162:165], v[212:215], v[30:33]
	v_mfma_f32_16x16x32_bf16 v[22:25], v[170:173], v[212:215], v[22:25]
	v_mfma_f32_16x16x32_bf16 v[14:17], v[162:165], v[220:223], v[14:17]
	v_mfma_f32_16x16x32_bf16 v[6:9], v[170:173], v[220:223], v[6:9]
	v_mfma_f32_16x16x32_bf16 v[62:65], v[166:169], v[200:203], v[62:65]
	v_mfma_f32_16x16x32_bf16 v[54:57], v[174:177], v[200:203], v[54:57]
	v_mfma_f32_16x16x32_bf16 v[46:49], v[166:169], v[208:211], v[46:49]
	v_mfma_f32_16x16x32_bf16 v[38:41], v[174:177], v[208:211], v[38:41]
	v_mfma_f32_16x16x32_bf16 v[30:33], v[166:169], v[216:219], v[30:33]
	v_mfma_f32_16x16x32_bf16 v[22:25], v[174:177], v[216:219], v[22:25]
	v_mfma_f32_16x16x32_bf16 v[14:17], v[166:169], v[224:227], v[14:17]
	v_mfma_f32_16x16x32_bf16 v[6:9], v[174:177], v[224:227], v[6:9]
	s_setprio 0
	s_setprio 1
	v_mfma_f32_16x16x32_bf16 v[58:61], v[178:181], v[196:199], v[58:61]
	v_mfma_f32_16x16x32_bf16 v[50:53], v[186:189], v[196:199], v[50:53]
	v_mfma_f32_16x16x32_bf16 v[42:45], v[178:181], v[204:207], v[42:45]
	v_mfma_f32_16x16x32_bf16 v[34:37], v[186:189], v[204:207], v[34:37]
	v_mfma_f32_16x16x32_bf16 v[26:29], v[178:181], v[212:215], v[26:29]
	v_mfma_f32_16x16x32_bf16 v[18:21], v[186:189], v[212:215], v[18:21]
	v_mfma_f32_16x16x32_bf16 v[10:13], v[178:181], v[220:223], v[10:13]
	v_mfma_f32_16x16x32_bf16 v[2:5], v[186:189], v[220:223], v[2:5]
	v_mfma_f32_16x16x32_bf16 v[58:61], v[182:185], v[200:203], v[58:61]
	v_mfma_f32_16x16x32_bf16 v[50:53], v[192:195], v[200:203], v[50:53]
	v_mfma_f32_16x16x32_bf16 v[42:45], v[182:185], v[208:211], v[42:45]
	v_mfma_f32_16x16x32_bf16 v[34:37], v[192:195], v[208:211], v[34:37]
	v_mfma_f32_16x16x32_bf16 v[26:29], v[182:185], v[216:219], v[26:29]
	v_mfma_f32_16x16x32_bf16 v[18:21], v[192:195], v[216:219], v[18:21]
	v_mfma_f32_16x16x32_bf16 v[10:13], v[182:185], v[224:227], v[10:13]
	v_mfma_f32_16x16x32_bf16 v[2:5], v[192:195], v[224:227], v[2:5]
	s_setprio 0
	s_barrier
	s_add_i32 s56, 0, 0x18000
	v_add_u32_e32 v161, s56, v155
	s_add_i32 s57, 0, 0x1c000
	ds_read_b128 v[162:165], v161
	ds_read_b128 v[166:169], v161 offset:1024
	ds_read_b128 v[170:173], v161 offset:2048
	ds_read_b128 v[174:177], v161 offset:3072
	v_add_u32_e32 v161, s57, v155
	ds_read_b128 v[178:181], v161
	ds_read_b128 v[182:185], v161 offset:1024
	ds_read_b128 v[186:189], v161 offset:2048
	ds_read_b128 v[192:195], v161 offset:3072
	s_add_u32 s34, s34, 0x80000
	s_addc_u32 s35, s35, 0
	s_mov_b32 m0, s42
	v_lshl_add_u64 v[236:237], s[34:35], 0, v[130:131]
	ds_read_b128 v[196:199], v160 offset:32768
	ds_read_b128 v[200:203], v160 offset:33792
	ds_read_b128 v[204:207], v160 offset:34816
	ds_read_b128 v[208:211], v160 offset:35840
	ds_read_b128 v[212:215], v160 offset:36864
	ds_read_b128 v[216:219], v160 offset:37888
	ds_read_b128 v[220:223], v160 offset:38912
	ds_read_b128 v[224:227], v160 offset:39936
	global_load_lds_dwordx4 v[236:237], off
	v_lshl_add_u64 v[236:237], s[34:35], 0, v[134:135]
	s_mov_b32 m0, s43
	s_nop 0
	global_load_lds_dwordx4 v[236:237], off
	s_waitcnt vmcnt(8)
	s_waitcnt lgkmcnt(0)
	s_barrier
	s_setprio 1
	s_waitcnt lgkmcnt(0)
	v_mfma_f32_16x16x32_bf16 v[122:125], v[162:165], v[196:199], v[122:125]
	v_mfma_f32_16x16x32_bf16 v[118:121], v[170:173], v[196:199], v[118:121]
	v_mfma_f32_16x16x32_bf16 v[110:113], v[162:165], v[204:207], v[110:113]
	v_mfma_f32_16x16x32_bf16 v[102:105], v[170:173], v[204:207], v[102:105]
	v_mfma_f32_16x16x32_bf16 v[94:97], v[162:165], v[212:215], v[94:97]
	v_mfma_f32_16x16x32_bf16 v[86:89], v[170:173], v[212:215], v[86:89]
	v_mfma_f32_16x16x32_bf16 v[78:81], v[162:165], v[220:223], v[78:81]
	v_mfma_f32_16x16x32_bf16 v[70:73], v[170:173], v[220:223], v[70:73]
	v_mfma_f32_16x16x32_bf16 v[122:125], v[166:169], v[200:203], v[122:125]
	v_mfma_f32_16x16x32_bf16 v[118:121], v[174:177], v[200:203], v[118:121]
	v_mfma_f32_16x16x32_bf16 v[110:113], v[166:169], v[208:211], v[110:113]
	v_mfma_f32_16x16x32_bf16 v[102:105], v[174:177], v[208:211], v[102:105]
	v_mfma_f32_16x16x32_bf16 v[94:97], v[166:169], v[216:219], v[94:97]
	v_mfma_f32_16x16x32_bf16 v[86:89], v[174:177], v[216:219], v[86:89]
	v_mfma_f32_16x16x32_bf16 v[78:81], v[166:169], v[224:227], v[78:81]
	v_mfma_f32_16x16x32_bf16 v[70:73], v[174:177], v[224:227], v[70:73]
	s_setprio 0
	s_setprio 1
	v_mfma_f32_16x16x32_bf16 v[126:129], v[178:181], v[196:199], v[126:129]
	v_mfma_f32_16x16x32_bf16 v[114:117], v[186:189], v[196:199], v[114:117]
	v_mfma_f32_16x16x32_bf16 v[106:109], v[178:181], v[204:207], v[106:109]
	v_mfma_f32_16x16x32_bf16 v[98:101], v[186:189], v[204:207], v[98:101]
	v_mfma_f32_16x16x32_bf16 v[90:93], v[178:181], v[212:215], v[90:93]
	v_mfma_f32_16x16x32_bf16 v[82:85], v[186:189], v[212:215], v[82:85]
	v_mfma_f32_16x16x32_bf16 v[74:77], v[178:181], v[220:223], v[74:77]
	v_mfma_f32_16x16x32_bf16 v[66:69], v[186:189], v[220:223], v[66:69]
	v_mfma_f32_16x16x32_bf16 v[126:129], v[182:185], v[200:203], v[126:129]
	v_mfma_f32_16x16x32_bf16 v[114:117], v[192:195], v[200:203], v[114:117]
	v_mfma_f32_16x16x32_bf16 v[106:109], v[182:185], v[208:211], v[106:109]
	v_mfma_f32_16x16x32_bf16 v[98:101], v[192:195], v[208:211], v[98:101]
	v_mfma_f32_16x16x32_bf16 v[90:93], v[182:185], v[216:219], v[90:93]
	v_mfma_f32_16x16x32_bf16 v[82:85], v[192:195], v[216:219], v[82:85]
	v_mfma_f32_16x16x32_bf16 v[74:77], v[182:185], v[224:227], v[74:77]
	v_mfma_f32_16x16x32_bf16 v[66:69], v[192:195], v[224:227], v[66:69]
	s_setprio 0
	s_barrier
; #define PG8_STAGE(bufoff, gbase, voff) do { _Pragma("unroll") for (int _i = 0; _i < 2; ++_i) \
;         __builtin_amdgcn_global_load_lds((const unsigned*)((const char*)(gbase) + (voff)[_i]), (PG8_LAS unsigned*)(lds + (bufoff) + ldsw + _i * 8192), 16, 0, 0); } while (0)
; #define PG8_STAGEB(bufoff, gbase, voff) do { _Pragma("unroll") for (int _i = 0; _i < 2; ++_i) \
;         __builtin_amdgcn_global_load_lds((const unsigned*)((const char*)(gbase) + (voff)[_i]), (PG8_LAS unsigned*)(lds + (bufoff) + ldsw + _i * 8192), 16, 0, PG8_BAUX); } while (0)
; #define PG8_LDA(dst, b, h) do { _Pragma("unroll") for (int m = 0; m < 4; ++m) _Pragma("unroll") for (int k = 0; k < 2; ++k) dst[m][k] = *(const PG8_LAS bf16x8*)(lds + PG8_SA(b, h) + aoff + m * 2048 + k * 1024); } while (0)
; #define PG8_MMA(ai, bj, At, Bt) do { __builtin_amdgcn_s_setprio(1); _Pragma("unroll") for (int m = 0; m < 4; ++m) _Pragma("unroll") for (int n = 0; n < 2; ++n) _Pragma("unroll") for (int k = 0; k < 2; ++k) \
;         acc[ai][bj][m][n] = __builtin_amdgcn_mfma_f32_16x16x32_bf16(Bt[n][k], At[m][k], acc[ai][bj][m][n], 0, 0, 0); __builtin_amdgcn_s_setprio(0); } while (0)
; #define PG8_WAIT_V(n) asm volatile("s_waitcnt vmcnt(" #n ")" ::: "memory")
; #define PG8_WAIT_L(n) asm volatile("s_waitcnt lgkmcnt(" #n ")" ::: "memory")
; #define PG8_BAR __builtin_amdgcn_s_barrier()
; #define PG8_SCHED __builtin_amdgcn_sched_barrier(0)
; template <class Epi, class Sched, bool ALIGN_EPI = false, bool SP2 = false>
; __device__ __forceinline__ void gemm_phase(PG8_LAS unsigned char* lds, const Gemm g, const Sched& S, const Epi& E) {
;     ...
;         for (int t = 0; t < nt; t += 2) {
;     ...
;             PG8_LDA(At, 1, 1); PG8_STAGEB(PG8_SB(1, 0), b3, voffB); PG8_STAGEB(PG8_SB(1, 1), b3 + hstep, voffB); PG8_STAGE(PG8_SA(1, 0), a3, voffA);
;             PG8_WAIT_V(8); PG8_WAIT_L(0); PG8_BAR; PG8_MMA(1, 0, At, B0); PG8_MMA(1, 1, At, B1); PG8_BAR; PG8_SCHED;
	s_add_i32 s34, s56, s33
	v_lshl_add_u64 v[228:229], v[228:229], 0, s[14:15]
	s_mov_b32 m0, s34
	ds_read_b128 v[196:199], v160 offset:49152
	ds_read_b128 v[200:203], v160 offset:50176
	ds_read_b128 v[204:207], v160 offset:51200
	ds_read_b128 v[208:211], v160 offset:52224
	ds_read_b128 v[212:215], v160 offset:53248
	ds_read_b128 v[216:219], v160 offset:54272
	ds_read_b128 v[220:223], v160 offset:55296
	ds_read_b128 v[224:227], v160 offset:56320
	global_load_lds_dwordx4 v[228:229], off
	s_add_i32 m0, s34, 0x2000
	s_add_u32 s30, s30, 0x80080
	v_lshl_add_u64 v[228:229], v[230:231], 0, s[14:15]
	s_addc_u32 s31, s31, 0
	s_add_i32 s34, s57, s33
	global_load_lds_dwordx4 v[228:229], off
	v_lshl_add_u64 v[228:229], s[30:31], 0, v[132:133]
	s_mov_b32 m0, s34
	s_nop 0
	global_load_lds_dwordx4 v[228:229], off
	v_lshl_add_u64 v[228:229], s[30:31], 0, v[136:137]
	s_add_i32 m0, s34, 0x2000
	s_nop 0
	global_load_lds_dwordx4 v[228:229], off
	v_lshl_add_u64 v[228:229], v[232:233], 0, s[14:15]
	s_mov_b32 m0, s45
	s_nop 0
	global_load_lds_dwordx4 v[228:229], off
	v_lshl_add_u64 v[228:229], v[234:235], 0, s[14:15]
	s_mov_b32 m0, s46
	s_nop 0
	global_load_lds_dwordx4 v[228:229], off
	s_waitcnt vmcnt(8)
	s_waitcnt lgkmcnt(0)
	s_barrier
	s_setprio 1
	s_waitcnt lgkmcnt(0)
	v_mfma_f32_16x16x32_bf16 v[62:65], v[162:165], v[196:199], v[62:65]
	v_mfma_f32_16x16x32_bf16 v[54:57], v[170:173], v[196:199], v[54:57]
	v_mfma_f32_16x16x32_bf16 v[46:49], v[162:165], v[204:207], v[46:49]
	v_mfma_f32_16x16x32_bf16 v[38:41], v[170:173], v[204:207], v[38:41]
	v_mfma_f32_16x16x32_bf16 v[30:33], v[162:165], v[212:215], v[30:33]
	v_mfma_f32_16x16x32_bf16 v[22:25], v[170:173], v[212:215], v[22:25]
	v_mfma_f32_16x16x32_bf16 v[14:17], v[162:165], v[220:223], v[14:17]
	v_mfma_f32_16x16x32_bf16 v[6:9], v[170:173], v[220:223], v[6:9]
	v_mfma_f32_16x16x32_bf16 v[62:65], v[166:169], v[200:203], v[62:65]
	v_mfma_f32_16x16x32_bf16 v[54:57], v[174:177], v[200:203], v[54:57]
	v_mfma_f32_16x16x32_bf16 v[46:49], v[166:169], v[208:211], v[46:49]
	v_mfma_f32_16x16x32_bf16 v[38:41], v[174:177], v[208:211], v[38:41]
	v_mfma_f32_16x16x32_bf16 v[30:33], v[166:169], v[216:219], v[30:33]
	v_mfma_f32_16x16x32_bf16 v[22:25], v[174:177], v[216:219], v[22:25]
	v_mfma_f32_16x16x32_bf16 v[14:17], v[166:169], v[224:227], v[14:17]
	v_mfma_f32_16x16x32_bf16 v[6:9], v[174:177], v[224:227], v[6:9]
	s_setprio 0
	s_setprio 1
	v_mfma_f32_16x16x32_bf16 v[58:61], v[178:181], v[196:199], v[58:61]
	v_mfma_f32_16x16x32_bf16 v[50:53], v[186:189], v[196:199], v[50:53]
	v_mfma_f32_16x16x32_bf16 v[42:45], v[178:181], v[204:207], v[42:45]
	v_mfma_f32_16x16x32_bf16 v[34:37], v[186:189], v[204:207], v[34:37]
	v_mfma_f32_16x16x32_bf16 v[26:29], v[178:181], v[212:215], v[26:29]
	v_mfma_f32_16x16x32_bf16 v[18:21], v[186:189], v[212:215], v[18:21]
	v_mfma_f32_16x16x32_bf16 v[10:13], v[178:181], v[220:223], v[10:13]
	v_mfma_f32_16x16x32_bf16 v[2:5], v[186:189], v[220:223], v[2:5]
	v_mfma_f32_16x16x32_bf16 v[58:61], v[182:185], v[200:203], v[58:61]
	v_mfma_f32_16x16x32_bf16 v[50:53], v[192:195], v[200:203], v[50:53]
	v_mfma_f32_16x16x32_bf16 v[42:45], v[182:185], v[208:211], v[42:45]
	v_mfma_f32_16x16x32_bf16 v[34:37], v[192:195], v[208:211], v[34:37]
	v_mfma_f32_16x16x32_bf16 v[26:29], v[182:185], v[216:219], v[26:29]
	v_mfma_f32_16x16x32_bf16 v[18:21], v[192:195], v[216:219], v[18:21]
	v_mfma_f32_16x16x32_bf16 v[10:13], v[182:185], v[224:227], v[10:13]
	v_mfma_f32_16x16x32_bf16 v[2:5], v[192:195], v[224:227], v[2:5]
	s_setprio 0
	s_add_i32 s55, s55, 2
	s_add_u32 s28, s28, 0x100
	s_addc_u32 s29, s29, 0
	s_add_u32 s53, s53, 0x100
	s_addc_u32 s54, s54, 0
	s_cmp_gt_u32 s55, 29
	s_barrier
	s_cbranch_scc0 .LBB0_365
	s_and_b64 vcc, exec, s[16:17]
	s_cbranch_vccz .LBB0_368
	s_barrier

; #define PG8_STAGE(bufoff, gbase, voff) do { _Pragma("unroll") for (int _i = 0; _i < 2; ++_i) \
;         __builtin_amdgcn_global_load_lds((const unsigned*)((const char*)(gbase) + (voff)[_i]), (PG8_LAS unsigned*)(lds + (bufoff) + ldsw + _i * 8192), 16, 0, 0); } while (0)
; #define PG8_STAGEB(bufoff, gbase, voff) do { _Pragma("unroll") for (int _i = 0; _i < 2; ++_i) \
;         __builtin_amdgcn_global_load_lds((const unsigned*)((const char*)(gbase) + (voff)[_i]), (PG8_LAS unsigned*)(lds + (bufoff) + ldsw + _i * 8192), 16, 0, PG8_BAUX); } while (0)
; #define PG8_LDA(dst, b, h) do { _Pragma("unroll") for (int m = 0; m < 4; ++m) _Pragma("unroll") for (int k = 0; k < 2; ++k) dst[m][k] = *(const PG8_LAS bf16x8*)(lds + PG8_SA(b, h) + aoff + m * 2048 + k * 1024); } while (0)
; #define PG8_LDB(dst, b, h) do { _Pragma("unroll") for (int n = 0; n < 2; ++n) _Pragma("unroll") for (int k = 0; k < 2; ++k) dst[n][k] = *(const PG8_LAS bf16x8*)(lds + PG8_SB(b, h) + boff + n * 2048 + k * 1024); } while (0)
; #define PG8_MMA(ai, bj, At, Bt) do { __builtin_amdgcn_s_setprio(1); _Pragma("unroll") for (int m = 0; m < 4; ++m) _Pragma("unroll") for (int n = 0; n < 2; ++n) _Pragma("unroll") for (int k = 0; k < 2; ++k) \
;         acc[ai][bj][m][n] = __builtin_amdgcn_mfma_f32_16x16x32_bf16(Bt[n][k], At[m][k], acc[ai][bj][m][n], 0, 0, 0); __builtin_amdgcn_s_setprio(0); } while (0)
; #define PG8_WAIT_V(n) asm volatile("s_waitcnt vmcnt(" #n ")" ::: "memory")
; #define PG8_WAIT_L(n) asm volatile("s_waitcnt lgkmcnt(" #n ")" ::: "memory")
; #define PG8_BAR __builtin_amdgcn_s_barrier()
; #define PG8_SCHED __builtin_amdgcn_sched_barrier(0)
; template <class Epi, class Sched, bool ALIGN_EPI = false, bool SP2 = false>
; __device__ __forceinline__ void gemm_phase(PG8_LAS unsigned char* lds, const Gemm g, const Sched& S, const Epi& E) {
;     ...
;             PG8_LDB(B0, 0, 0); PG8_LDB(B1, 0, 1); PG8_SCHED; PG8_LDA(At, 0, 0); PG8_STAGE(PG8_SA(1, 1), a1 + hstep, voffA);
;             PG8_WAIT_V(8); PG8_WAIT_L(0); PG8_BAR; PG8_MMA(0, 0, At, B0); PG8_MMA(0, 1, At, B1); PG8_BAR; PG8_SCHED;
;             PG8_LDA(At, 0, 1); PG8_STAGEB(PG8_SB(0, 0), b2, voffB); PG8_STAGEB(PG8_SB(0, 1), b2 + hstep, voffB); PG8_STAGE(PG8_SA(0, 0), a2, voffA);
.LBB0_391:
	ds_read_b128 v[144:147], v155
	ds_read_b128 v[148:151], v155 offset:1024
	ds_read_b128 v[160:163], v155 offset:2048
	ds_read_b128 v[164:167], v155 offset:3072
	ds_read_b128 v[168:171], v156
	ds_read_b128 v[172:175], v156 offset:1024
	ds_read_b128 v[176:179], v156 offset:2048
	ds_read_b128 v[180:183], v156 offset:3072
	s_add_u32 s38, s34, 0xfff80080
	s_addc_u32 s39, s35, -1
	s_cmp_eq_u32 s65, 28
	s_cselect_b32 s41, s1, s39
	s_cselect_b32 s40, s25, s38
	s_cselect_b32 s39, s23, s64
	s_cselect_b32 s38, s31, s63
	v_lshl_add_u64 v[188:189], s[34:35], 0, v[140:141]
	s_add_i32 m0, s47, 0xc000
	ds_read_b128 v[184:187], v157
	ds_read_b128 v[192:195], v157 offset:1024
	ds_read_b128 v[196:199], v157 offset:2048
	ds_read_b128 v[200:203], v157 offset:3072
	ds_read_b128 v[204:207], v157 offset:4096
	ds_read_b128 v[208:211], v157 offset:5120
	ds_read_b128 v[212:215], v157 offset:6144
	ds_read_b128 v[216:219], v157 offset:7168
	global_load_lds_dwordx4 v[188:189], off
	v_lshl_add_u64 v[188:189], s[34:35], 0, v[142:143]
	s_add_i32 m0, s47, 0xe000
	s_nop 0
	global_load_lds_dwordx4 v[188:189], off
	s_waitcnt vmcnt(8)
	s_waitcnt lgkmcnt(0)
	s_barrier
	s_setprio 1
	s_waitcnt lgkmcnt(0)
	v_mfma_f32_16x16x32_bf16 v[126:129], v[144:147], v[184:187], v[126:129]
	v_mfma_f32_16x16x32_bf16 v[122:125], v[160:163], v[184:187], v[122:125]
	v_mfma_f32_16x16x32_bf16 v[110:113], v[144:147], v[196:199], v[110:113]
	v_mfma_f32_16x16x32_bf16 v[106:109], v[160:163], v[196:199], v[106:109]
	v_mfma_f32_16x16x32_bf16 v[94:97], v[144:147], v[204:207], v[94:97]
	v_mfma_f32_16x16x32_bf16 v[90:93], v[160:163], v[204:207], v[90:93]
	v_mfma_f32_16x16x32_bf16 v[78:81], v[144:147], v[212:215], v[78:81]
	v_mfma_f32_16x16x32_bf16 v[74:77], v[160:163], v[212:215], v[74:77]
	v_mfma_f32_16x16x32_bf16 v[126:129], v[148:151], v[192:195], v[126:129]
	v_mfma_f32_16x16x32_bf16 v[122:125], v[164:167], v[192:195], v[122:125]
	v_mfma_f32_16x16x32_bf16 v[110:113], v[148:151], v[200:203], v[110:113]
	v_mfma_f32_16x16x32_bf16 v[106:109], v[164:167], v[200:203], v[106:109]
	v_mfma_f32_16x16x32_bf16 v[94:97], v[148:151], v[208:211], v[94:97]
	v_mfma_f32_16x16x32_bf16 v[90:93], v[164:167], v[208:211], v[90:93]
	v_mfma_f32_16x16x32_bf16 v[78:81], v[148:151], v[216:219], v[78:81]
	v_mfma_f32_16x16x32_bf16 v[74:77], v[164:167], v[216:219], v[74:77]
	s_setprio 0
	s_setprio 1
	v_mfma_f32_16x16x32_bf16 v[118:121], v[168:171], v[184:187], v[118:121]
	v_mfma_f32_16x16x32_bf16 v[114:117], v[176:179], v[184:187], v[114:117]
	v_mfma_f32_16x16x32_bf16 v[102:105], v[168:171], v[196:199], v[102:105]
	v_mfma_f32_16x16x32_bf16 v[98:101], v[176:179], v[196:199], v[98:101]
	v_mfma_f32_16x16x32_bf16 v[86:89], v[168:171], v[204:207], v[86:89]
	v_mfma_f32_16x16x32_bf16 v[82:85], v[176:179], v[204:207], v[82:85]
	v_mfma_f32_16x16x32_bf16 v[70:73], v[168:171], v[212:215], v[70:73]
	v_mfma_f32_16x16x32_bf16 v[66:69], v[176:179], v[212:215], v[66:69]
	v_mfma_f32_16x16x32_bf16 v[118:121], v[172:175], v[192:195], v[118:121]
	v_mfma_f32_16x16x32_bf16 v[114:117], v[180:183], v[192:195], v[114:117]
	v_mfma_f32_16x16x32_bf16 v[102:105], v[172:175], v[200:203], v[102:105]
	v_mfma_f32_16x16x32_bf16 v[98:101], v[180:183], v[200:203], v[98:101]
	v_mfma_f32_16x16x32_bf16 v[86:89], v[172:175], v[208:211], v[86:89]
	v_mfma_f32_16x16x32_bf16 v[82:85], v[180:183], v[208:211], v[82:85]
	v_mfma_f32_16x16x32_bf16 v[70:73], v[172:175], v[216:219], v[70:73]
	v_mfma_f32_16x16x32_bf16 v[66:69], v[180:183], v[216:219], v[66:69]
	s_setprio 0
	s_barrier
	s_add_i32 s66, s57, s42
	v_lshl_add_u64 v[188:189], s[38:39], 0, v[132:133]
	s_mov_b32 m0, s66
	ds_read_b128 v[184:187], v157 offset:16384
	ds_read_b128 v[192:195], v157 offset:17408
	ds_read_b128 v[196:199], v157 offset:18432
	ds_read_b128 v[200:203], v157 offset:19456
	ds_read_b128 v[204:207], v157 offset:20480
	ds_read_b128 v[208:211], v157 offset:21504
	ds_read_b128 v[212:215], v157 offset:22528
	ds_read_b128 v[216:219], v157 offset:23552
	global_load_lds_dwordx4 v[188:189], off
	s_add_i32 m0, s66, 0x2000
	s_add_u32 s66, s38, 0x80000
	v_lshl_add_u64 v[220:221], s[38:39], 0, v[136:137]
	s_addc_u32 s67, s39, 0
	s_add_i32 s68, s58, s42
	global_load_lds_dwordx4 v[220:221], off
	v_lshl_add_u64 v[222:223], s[66:67], 0, v[132:133]
	s_mov_b32 m0, s68
	v_lshl_add_u64 v[224:225], s[40:41], 0, v[134:135]
	global_load_lds_dwordx4 v[222:223], off
	v_lshl_add_u64 v[222:223], s[66:67], 0, v[136:137]
	s_add_i32 m0, s68, 0x2000
	s_nop 0
	global_load_lds_dwordx4 v[222:223], off
	v_lshl_add_u64 v[222:223], s[40:41], 0, v[130:131]
	s_mov_b32 m0, s47
	s_nop 0
	global_load_lds_dwordx4 v[222:223], off
	s_mov_b32 m0, s48
	s_nop 0
	global_load_lds_dwordx4 v[224:225], off
	s_waitcnt vmcnt(8)
	s_waitcnt lgkmcnt(0)
	s_barrier
; #define PG8_STAGE(bufoff, gbase, voff) do { _Pragma("unroll") for (int _i = 0; _i < 2; ++_i) \
;         __builtin_amdgcn_global_load_lds((const unsigned*)((const char*)(gbase) + (voff)[_i]), (PG8_LAS unsigned*)(lds + (bufoff) + ldsw + _i * 8192), 16, 0, 0); } while (0)
; #define PG8_LDA(dst, b, h) do { _Pragma("unroll") for (int m = 0; m < 4; ++m) _Pragma("unroll") for (int k = 0; k < 2; ++k) dst[m][k] = *(const PG8_LAS bf16x8*)(lds + PG8_SA(b, h) + aoff + m * 2048 + k * 1024); } while (0)
; #define PG8_LDB(dst, b, h) do { _Pragma("unroll") for (int n = 0; n < 2; ++n) _Pragma("unroll") for (int k = 0; k < 2; ++k) dst[n][k] = *(const PG8_LAS bf16x8*)(lds + PG8_SB(b, h) + boff + n * 2048 + k * 1024); } while (0)
; #define PG8_MMA(ai, bj, At, Bt) do { __builtin_amdgcn_s_setprio(1); _Pragma("unroll") for (int m = 0; m < 4; ++m) _Pragma("unroll") for (int n = 0; n < 2; ++n) _Pragma("unroll") for (int k = 0; k < 2; ++k) \
;         acc[ai][bj][m][n] = __builtin_amdgcn_mfma_f32_16x16x32_bf16(Bt[n][k], At[m][k], acc[ai][bj][m][n], 0, 0, 0); __builtin_amdgcn_s_setprio(0); } while (0)
; #define PG8_WAIT_V(n) asm volatile("s_waitcnt vmcnt(" #n ")" ::: "memory")
; #define PG8_WAIT_L(n) asm volatile("s_waitcnt lgkmcnt(" #n ")" ::: "memory")
; #define PG8_BAR __builtin_amdgcn_s_barrier()
; #define PG8_SCHED __builtin_amdgcn_sched_barrier(0)
; template <class Epi, class Sched, bool ALIGN_EPI = false, bool SP2 = false>
; __device__ __forceinline__ void gemm_phase(PG8_LAS unsigned char* lds, const Gemm g, const Sched& S, const Epi& E) {
;     ...
;             PG8_WAIT_V(8); PG8_WAIT_L(0); PG8_BAR; PG8_MMA(1, 0, At, B0); PG8_MMA(1, 1, At, B1); PG8_BAR; PG8_SCHED;
;             PG8_LDB(B0, 1, 0); PG8_LDB(B1, 1, 1); PG8_SCHED; PG8_LDA(At, 1, 0); PG8_STAGE(PG8_SA(0, 1), a2 + hstep, voffA);
;             PG8_WAIT_V(8); PG8_WAIT_L(0); PG8_BAR; PG8_MMA(0, 0, At, B0); PG8_MMA(0, 1, At, B1); PG8_BAR; PG8_SCHED;
	s_setprio 1
	s_waitcnt lgkmcnt(0)
	v_mfma_f32_16x16x32_bf16 v[62:65], v[144:147], v[184:187], v[62:65]
	v_mfma_f32_16x16x32_bf16 v[58:61], v[160:163], v[184:187], v[58:61]
	v_mfma_f32_16x16x32_bf16 v[46:49], v[144:147], v[196:199], v[46:49]
	v_mfma_f32_16x16x32_bf16 v[42:45], v[160:163], v[196:199], v[42:45]
	v_mfma_f32_16x16x32_bf16 v[30:33], v[144:147], v[204:207], v[30:33]
	v_mfma_f32_16x16x32_bf16 v[26:29], v[160:163], v[204:207], v[26:29]
	v_mfma_f32_16x16x32_bf16 v[14:17], v[144:147], v[212:215], v[14:17]
	v_mfma_f32_16x16x32_bf16 v[10:13], v[160:163], v[212:215], v[10:13]
	v_mfma_f32_16x16x32_bf16 v[62:65], v[148:151], v[192:195], v[62:65]
	v_mfma_f32_16x16x32_bf16 v[58:61], v[164:167], v[192:195], v[58:61]
	v_mfma_f32_16x16x32_bf16 v[46:49], v[148:151], v[200:203], v[46:49]
	v_mfma_f32_16x16x32_bf16 v[42:45], v[164:167], v[200:203], v[42:45]
	v_mfma_f32_16x16x32_bf16 v[30:33], v[148:151], v[208:211], v[30:33]
	v_mfma_f32_16x16x32_bf16 v[26:29], v[164:167], v[208:211], v[26:29]
	v_mfma_f32_16x16x32_bf16 v[14:17], v[148:151], v[216:219], v[14:17]
	v_mfma_f32_16x16x32_bf16 v[10:13], v[164:167], v[216:219], v[10:13]
	s_setprio 0
	s_setprio 1
	v_mfma_f32_16x16x32_bf16 v[54:57], v[168:171], v[184:187], v[54:57]
	v_mfma_f32_16x16x32_bf16 v[50:53], v[176:179], v[184:187], v[50:53]
	v_mfma_f32_16x16x32_bf16 v[38:41], v[168:171], v[196:199], v[38:41]
	v_mfma_f32_16x16x32_bf16 v[34:37], v[176:179], v[196:199], v[34:37]
	v_mfma_f32_16x16x32_bf16 v[22:25], v[168:171], v[204:207], v[22:25]
	v_mfma_f32_16x16x32_bf16 v[18:21], v[176:179], v[204:207], v[18:21]
	v_mfma_f32_16x16x32_bf16 v[6:9], v[168:171], v[212:215], v[6:9]
	v_mfma_f32_16x16x32_bf16 v[2:5], v[176:179], v[212:215], v[2:5]
	v_mfma_f32_16x16x32_bf16 v[54:57], v[172:175], v[192:195], v[54:57]
	v_mfma_f32_16x16x32_bf16 v[50:53], v[180:183], v[192:195], v[50:53]
	v_mfma_f32_16x16x32_bf16 v[38:41], v[172:175], v[200:203], v[38:41]
	v_mfma_f32_16x16x32_bf16 v[34:37], v[180:183], v[200:203], v[34:37]
	v_mfma_f32_16x16x32_bf16 v[22:25], v[172:175], v[208:211], v[22:25]
	v_mfma_f32_16x16x32_bf16 v[18:21], v[180:183], v[208:211], v[18:21]
	v_mfma_f32_16x16x32_bf16 v[6:9], v[172:175], v[216:219], v[6:9]
	v_mfma_f32_16x16x32_bf16 v[2:5], v[180:183], v[216:219], v[2:5]
	s_setprio 0
	s_barrier
	s_add_i32 s66, 0, 0x18000
	v_add_u32_e32 v138, s66, v153
	s_add_i32 s67, 0, 0x1c000
	ds_read_b128 v[144:147], v138
	ds_read_b128 v[148:151], v138 offset:1024
	ds_read_b128 v[160:163], v138 offset:2048
	ds_read_b128 v[164:167], v138 offset:3072
	v_add_u32_e32 v138, s67, v153
	ds_read_b128 v[168:171], v138
	ds_read_b128 v[172:175], v138 offset:1024
	ds_read_b128 v[176:179], v138 offset:2048
	ds_read_b128 v[180:183], v138 offset:3072
	s_add_u32 s40, s40, 0x80000
	s_addc_u32 s41, s41, 0
	s_mov_b32 m0, s49
	v_lshl_add_u64 v[226:227], s[40:41], 0, v[130:131]
	ds_read_b128 v[184:187], v157 offset:32768
	ds_read_b128 v[192:195], v157 offset:33792
	ds_read_b128 v[196:199], v157 offset:34816
	ds_read_b128 v[200:203], v157 offset:35840
	ds_read_b128 v[204:207], v157 offset:36864
	ds_read_b128 v[208:211], v157 offset:37888
	ds_read_b128 v[212:215], v157 offset:38912
	ds_read_b128 v[216:219], v157 offset:39936
	global_load_lds_dwordx4 v[226:227], off
	v_lshl_add_u64 v[226:227], s[40:41], 0, v[134:135]
	s_mov_b32 m0, s50
	s_nop 0
	global_load_lds_dwordx4 v[226:227], off
	s_waitcnt vmcnt(8)
	s_waitcnt lgkmcnt(0)
	s_barrier
	s_setprio 1
	s_waitcnt lgkmcnt(0)
	v_mfma_f32_16x16x32_bf16 v[126:129], v[144:147], v[184:187], v[126:129]
	v_mfma_f32_16x16x32_bf16 v[122:125], v[160:163], v[184:187], v[122:125]
	v_mfma_f32_16x16x32_bf16 v[110:113], v[144:147], v[196:199], v[110:113]
	v_mfma_f32_16x16x32_bf16 v[106:109], v[160:163], v[196:199], v[106:109]
	v_mfma_f32_16x16x32_bf16 v[94:97], v[144:147], v[204:207], v[94:97]
	v_mfma_f32_16x16x32_bf16 v[90:93], v[160:163], v[204:207], v[90:93]
	v_mfma_f32_16x16x32_bf16 v[78:81], v[144:147], v[212:215], v[78:81]
	v_mfma_f32_16x16x32_bf16 v[74:77], v[160:163], v[212:215], v[74:77]
	v_mfma_f32_16x16x32_bf16 v[126:129], v[148:151], v[192:195], v[126:129]
	v_mfma_f32_16x16x32_bf16 v[122:125], v[164:167], v[192:195], v[122:125]
	v_mfma_f32_16x16x32_bf16 v[110:113], v[148:151], v[200:203], v[110:113]
	v_mfma_f32_16x16x32_bf16 v[106:109], v[164:167], v[200:203], v[106:109]
	v_mfma_f32_16x16x32_bf16 v[94:97], v[148:151], v[208:211], v[94:97]
	v_mfma_f32_16x16x32_bf16 v[90:93], v[164:167], v[208:211], v[90:93]
	v_mfma_f32_16x16x32_bf16 v[78:81], v[148:151], v[216:219], v[78:81]
	v_mfma_f32_16x16x32_bf16 v[74:77], v[164:167], v[216:219], v[74:77]
	s_setprio 0
	s_setprio 1
	v_mfma_f32_16x16x32_bf16 v[118:121], v[168:171], v[184:187], v[118:121]
	v_mfma_f32_16x16x32_bf16 v[114:117], v[176:179], v[184:187], v[114:117]
	v_mfma_f32_16x16x32_bf16 v[102:105], v[168:171], v[196:199], v[102:105]
	v_mfma_f32_16x16x32_bf16 v[98:101], v[176:179], v[196:199], v[98:101]
	v_mfma_f32_16x16x32_bf16 v[86:89], v[168:171], v[204:207], v[86:89]
	v_mfma_f32_16x16x32_bf16 v[82:85], v[176:179], v[204:207], v[82:85]
	v_mfma_f32_16x16x32_bf16 v[70:73], v[168:171], v[212:215], v[70:73]
	v_mfma_f32_16x16x32_bf16 v[66:69], v[176:179], v[212:215], v[66:69]
	v_mfma_f32_16x16x32_bf16 v[118:121], v[172:175], v[192:195], v[118:121]
	v_mfma_f32_16x16x32_bf16 v[114:117], v[180:183], v[192:195], v[114:117]
	v_mfma_f32_16x16x32_bf16 v[102:105], v[172:175], v[200:203], v[102:105]
	v_mfma_f32_16x16x32_bf16 v[98:101], v[180:183], v[200:203], v[98:101]
	v_mfma_f32_16x16x32_bf16 v[86:89], v[172:175], v[208:211], v[86:89]
	v_mfma_f32_16x16x32_bf16 v[82:85], v[180:183], v[208:211], v[82:85]
	v_mfma_f32_16x16x32_bf16 v[70:73], v[172:175], v[216:219], v[70:73]
	v_mfma_f32_16x16x32_bf16 v[66:69], v[180:183], v[216:219], v[66:69]
	s_setprio 0
	s_barrier
; #define PG8_STAGE(bufoff, gbase, voff) do { _Pragma("unroll") for (int _i = 0; _i < 2; ++_i) \
;         __builtin_amdgcn_global_load_lds((const unsigned*)((const char*)(gbase) + (voff)[_i]), (PG8_LAS unsigned*)(lds + (bufoff) + ldsw + _i * 8192), 16, 0, 0); } while (0)
; #define PG8_STAGEB(bufoff, gbase, voff) do { _Pragma("unroll") for (int _i = 0; _i < 2; ++_i) \
;         __builtin_amdgcn_global_load_lds((const unsigned*)((const char*)(gbase) + (voff)[_i]), (PG8_LAS unsigned*)(lds + (bufoff) + ldsw + _i * 8192), 16, 0, PG8_BAUX); } while (0)
; #define PG8_LDA(dst, b, h) do { _Pragma("unroll") for (int m = 0; m < 4; ++m) _Pragma("unroll") for (int k = 0; k < 2; ++k) dst[m][k] = *(const PG8_LAS bf16x8*)(lds + PG8_SA(b, h) + aoff + m * 2048 + k * 1024); } while (0)
; #define PG8_MMA(ai, bj, At, Bt) do { __builtin_amdgcn_s_setprio(1); _Pragma("unroll") for (int m = 0; m < 4; ++m) _Pragma("unroll") for (int n = 0; n < 2; ++n) _Pragma("unroll") for (int k = 0; k < 2; ++k) \
;         acc[ai][bj][m][n] = __builtin_amdgcn_mfma_f32_16x16x32_bf16(Bt[n][k], At[m][k], acc[ai][bj][m][n], 0, 0, 0); __builtin_amdgcn_s_setprio(0); } while (0)
; #define PG8_WAIT_V(n) asm volatile("s_waitcnt vmcnt(" #n ")" ::: "memory")
; #define PG8_WAIT_L(n) asm volatile("s_waitcnt lgkmcnt(" #n ")" ::: "memory")
; #define PG8_BAR __builtin_amdgcn_s_barrier()
; #define PG8_SCHED __builtin_amdgcn_sched_barrier(0)
; template <class Epi, class Sched, bool ALIGN_EPI = false, bool SP2 = false>
; __device__ __forceinline__ void gemm_phase(PG8_LAS unsigned char* lds, const Gemm g, const Sched& S, const Epi& E) {
;     ...
;         for (int t = 0; t < nt; t += 2) {
;     ...
;             PG8_LDA(At, 1, 1); PG8_STAGEB(PG8_SB(1, 0), b3, voffB); PG8_STAGEB(PG8_SB(1, 1), b3 + hstep, voffB); PG8_STAGE(PG8_SA(1, 0), a3, voffA);
;             PG8_WAIT_V(8); PG8_WAIT_L(0); PG8_BAR; PG8_MMA(1, 0, At, B0); PG8_MMA(1, 1, At, B1); PG8_BAR; PG8_SCHED;
	s_add_i32 s40, s66, s42
	v_lshl_add_u64 v[188:189], v[188:189], 0, s[16:17]
	s_mov_b32 m0, s40
	ds_read_b128 v[184:187], v157 offset:49152
	ds_read_b128 v[192:195], v157 offset:50176
	ds_read_b128 v[196:199], v157 offset:51200
	ds_read_b128 v[200:203], v157 offset:52224
	ds_read_b128 v[204:207], v157 offset:53248
	ds_read_b128 v[208:211], v157 offset:54272
	ds_read_b128 v[212:215], v157 offset:55296
	ds_read_b128 v[216:219], v157 offset:56320
	global_load_lds_dwordx4 v[188:189], off
	s_add_i32 m0, s40, 0x2000
	s_add_u32 s38, s38, 0x80080
	v_lshl_add_u64 v[188:189], v[220:221], 0, s[16:17]
	s_addc_u32 s39, s39, 0
	s_add_i32 s40, s67, s42
	global_load_lds_dwordx4 v[188:189], off
	v_lshl_add_u64 v[188:189], s[38:39], 0, v[132:133]
	s_mov_b32 m0, s40
	s_nop 0
	global_load_lds_dwordx4 v[188:189], off
	v_lshl_add_u64 v[188:189], s[38:39], 0, v[136:137]
	s_add_i32 m0, s40, 0x2000
	s_nop 0
	global_load_lds_dwordx4 v[188:189], off
	v_lshl_add_u64 v[188:189], v[222:223], 0, s[16:17]
	s_mov_b32 m0, s53
	s_nop 0
	global_load_lds_dwordx4 v[188:189], off
	v_lshl_add_u64 v[188:189], v[224:225], 0, s[16:17]
	s_mov_b32 m0, s54
	s_nop 0
	global_load_lds_dwordx4 v[188:189], off
	s_waitcnt vmcnt(8)
	s_waitcnt lgkmcnt(0)
	s_barrier
	s_setprio 1
	s_waitcnt lgkmcnt(0)
	v_mfma_f32_16x16x32_bf16 v[62:65], v[144:147], v[184:187], v[62:65]
	v_mfma_f32_16x16x32_bf16 v[58:61], v[160:163], v[184:187], v[58:61]
	v_mfma_f32_16x16x32_bf16 v[46:49], v[144:147], v[196:199], v[46:49]
	v_mfma_f32_16x16x32_bf16 v[42:45], v[160:163], v[196:199], v[42:45]
	v_mfma_f32_16x16x32_bf16 v[30:33], v[144:147], v[204:207], v[30:33]
	v_mfma_f32_16x16x32_bf16 v[26:29], v[160:163], v[204:207], v[26:29]
	v_mfma_f32_16x16x32_bf16 v[14:17], v[144:147], v[212:215], v[14:17]
	v_mfma_f32_16x16x32_bf16 v[10:13], v[160:163], v[212:215], v[10:13]
	v_mfma_f32_16x16x32_bf16 v[62:65], v[148:151], v[192:195], v[62:65]
	v_mfma_f32_16x16x32_bf16 v[58:61], v[164:167], v[192:195], v[58:61]
	v_mfma_f32_16x16x32_bf16 v[46:49], v[148:151], v[200:203], v[46:49]
	v_mfma_f32_16x16x32_bf16 v[42:45], v[164:167], v[200:203], v[42:45]
	v_mfma_f32_16x16x32_bf16 v[30:33], v[148:151], v[208:211], v[30:33]
	v_mfma_f32_16x16x32_bf16 v[26:29], v[164:167], v[208:211], v[26:29]
	v_mfma_f32_16x16x32_bf16 v[14:17], v[148:151], v[216:219], v[14:17]
	v_mfma_f32_16x16x32_bf16 v[10:13], v[164:167], v[216:219], v[10:13]
	s_setprio 0
	s_setprio 1
	v_mfma_f32_16x16x32_bf16 v[54:57], v[168:171], v[184:187], v[54:57]
	v_mfma_f32_16x16x32_bf16 v[50:53], v[176:179], v[184:187], v[50:53]
	v_mfma_f32_16x16x32_bf16 v[38:41], v[168:171], v[196:199], v[38:41]
	v_mfma_f32_16x16x32_bf16 v[34:37], v[176:179], v[196:199], v[34:37]
	v_mfma_f32_16x16x32_bf16 v[22:25], v[168:171], v[204:207], v[22:25]
	v_mfma_f32_16x16x32_bf16 v[18:21], v[176:179], v[204:207], v[18:21]
	v_mfma_f32_16x16x32_bf16 v[6:9], v[168:171], v[212:215], v[6:9]
	v_mfma_f32_16x16x32_bf16 v[2:5], v[176:179], v[212:215], v[2:5]
	v_mfma_f32_16x16x32_bf16 v[54:57], v[172:175], v[192:195], v[54:57]
	v_mfma_f32_16x16x32_bf16 v[50:53], v[180:183], v[192:195], v[50:53]
	v_mfma_f32_16x16x32_bf16 v[38:41], v[172:175], v[200:203], v[38:41]
	v_mfma_f32_16x16x32_bf16 v[34:37], v[180:183], v[200:203], v[34:37]
	v_mfma_f32_16x16x32_bf16 v[22:25], v[172:175], v[208:211], v[22:25]
	v_mfma_f32_16x16x32_bf16 v[18:21], v[180:183], v[208:211], v[18:21]
	v_mfma_f32_16x16x32_bf16 v[6:9], v[172:175], v[216:219], v[6:9]
	v_mfma_f32_16x16x32_bf16 v[2:5], v[180:183], v[216:219], v[2:5]
	s_setprio 0
	s_add_i32 s65, s65, 2
	s_add_u32 s34, s34, 0x100
	s_addc_u32 s35, s35, 0
	s_add_u32 s63, s63, 0x100
	s_addc_u32 s64, s64, 0
	s_cmp_gt_u32 s65, 29
	s_barrier
	s_cbranch_scc0 .LBB0_391
	s_and_b64 vcc, exec, s[18:19]
	s_cbranch_vccz .LBB0_394
	s_barrier

; #define PG8_STAGE(bufoff, gbase, voff) do { _Pragma("unroll") for (int _i = 0; _i < 2; ++_i) \
;         __builtin_amdgcn_global_load_lds((const unsigned*)((const char*)(gbase) + (voff)[_i]), (PG8_LAS unsigned*)(lds + (bufoff) + ldsw + _i * 8192), 16, 0, 0); } while (0)
; #define PG8_STAGEB(bufoff, gbase, voff) do { _Pragma("unroll") for (int _i = 0; _i < 2; ++_i) \
;         __builtin_amdgcn_global_load_lds((const unsigned*)((const char*)(gbase) + (voff)[_i]), (PG8_LAS unsigned*)(lds + (bufoff) + ldsw + _i * 8192), 16, 0, PG8_BAUX); } while (0)
; #define PG8_LDA(dst, b, h) do { _Pragma("unroll") for (int m = 0; m < 4; ++m) _Pragma("unroll") for (int k = 0; k < 2; ++k) dst[m][k] = *(const PG8_LAS bf16x8*)(lds + PG8_SA(b, h) + aoff + m * 2048 + k * 1024); } while (0)
; #define PG8_LDB(dst, b, h) do { _Pragma("unroll") for (int n = 0; n < 2; ++n) _Pragma("unroll") for (int k = 0; k < 2; ++k) dst[n][k] = *(const PG8_LAS bf16x8*)(lds + PG8_SB(b, h) + boff + n * 2048 + k * 1024); } while (0)
; #define PG8_MMA(ai, bj, At, Bt) do { __builtin_amdgcn_s_setprio(1); _Pragma("unroll") for (int m = 0; m < 4; ++m) _Pragma("unroll") for (int n = 0; n < 2; ++n) _Pragma("unroll") for (int k = 0; k < 2; ++k) \
;         acc[ai][bj][m][n] = __builtin_amdgcn_mfma_f32_16x16x32_bf16(Bt[n][k], At[m][k], acc[ai][bj][m][n], 0, 0, 0); __builtin_amdgcn_s_setprio(0); } while (0)
; #define PG8_WAIT_V(n) asm volatile("s_waitcnt vmcnt(" #n ")" ::: "memory")
; #define PG8_WAIT_L(n) asm volatile("s_waitcnt lgkmcnt(" #n ")" ::: "memory")
; #define PG8_BAR __builtin_amdgcn_s_barrier()
; #define PG8_SCHED __builtin_amdgcn_sched_barrier(0)
; template <class Epi, class Sched, bool ALIGN_EPI = false, bool SP2 = false>
; __device__ __forceinline__ void gemm_phase(PG8_LAS unsigned char* lds, const Gemm g, const Sched& S, const Epi& E) {
;     ...
;             PG8_LDB(B0, 0, 0); PG8_LDB(B1, 0, 1); PG8_SCHED; PG8_LDA(At, 0, 0); PG8_STAGE(PG8_SA(1, 1), a1 + hstep, voffA);
;             PG8_WAIT_V(8); PG8_WAIT_L(0); PG8_BAR; PG8_MMA(0, 0, At, B0); PG8_MMA(0, 1, At, B1); PG8_BAR; PG8_SCHED;
;             PG8_LDA(At, 0, 1); PG8_STAGEB(PG8_SB(0, 0), b2, voffB); PG8_STAGEB(PG8_SB(0, 1), b2 + hstep, voffB); PG8_STAGE(PG8_SA(0, 0), a2, voffA);
.LBB0_608:
	ds_read_b128 v[146:149], v153
	ds_read_b128 v[158:161], v153 offset:1024
	ds_read_b128 v[162:165], v153 offset:2048
	ds_read_b128 v[166:169], v153 offset:3072
	ds_read_b128 v[170:173], v154
	ds_read_b128 v[174:177], v154 offset:1024
	ds_read_b128 v[178:181], v154 offset:2048
	ds_read_b128 v[182:185], v154 offset:3072
	s_add_u32 s28, s26, 0xffea0080
	s_addc_u32 s29, s27, -1
	s_cmpk_eq_i32 s55, 0x54
	s_cselect_b32 s31, s5, s29
	s_cselect_b32 s30, s4, s28
	s_cselect_b32 s29, s25, s54
	s_cselect_b32 s28, s24, s53
	v_lshl_add_u64 v[220:221], s[26:27], 0, v[138:139]
	s_add_i32 m0, s39, 0xc000
	ds_read_b128 v[186:189], v155
	ds_read_b128 v[192:195], v155 offset:1024
	ds_read_b128 v[196:199], v155 offset:2048
	ds_read_b128 v[200:203], v155 offset:3072
	ds_read_b128 v[204:207], v155 offset:4096
	ds_read_b128 v[208:211], v155 offset:5120
	ds_read_b128 v[212:215], v155 offset:6144
	ds_read_b128 v[216:219], v155 offset:7168
	global_load_lds_dwordx4 v[220:221], off
	v_lshl_add_u64 v[220:221], s[26:27], 0, v[140:141]
	s_add_i32 m0, s39, 0xe000
	s_nop 0
	global_load_lds_dwordx4 v[220:221], off
	s_waitcnt vmcnt(8)
	s_waitcnt lgkmcnt(0)
	s_barrier
	s_setprio 1
	s_waitcnt lgkmcnt(0)
	v_mfma_f32_16x16x32_bf16 v[126:129], v[146:149], v[186:189], v[126:129]
	v_mfma_f32_16x16x32_bf16 v[122:125], v[162:165], v[186:189], v[122:125]
	v_mfma_f32_16x16x32_bf16 v[110:113], v[146:149], v[196:199], v[110:113]
	v_mfma_f32_16x16x32_bf16 v[106:109], v[162:165], v[196:199], v[106:109]
	v_mfma_f32_16x16x32_bf16 v[94:97], v[146:149], v[204:207], v[94:97]
	v_mfma_f32_16x16x32_bf16 v[90:93], v[162:165], v[204:207], v[90:93]
	v_mfma_f32_16x16x32_bf16 v[78:81], v[146:149], v[212:215], v[78:81]
	v_mfma_f32_16x16x32_bf16 v[74:77], v[162:165], v[212:215], v[74:77]
	v_mfma_f32_16x16x32_bf16 v[126:129], v[158:161], v[192:195], v[126:129]
	v_mfma_f32_16x16x32_bf16 v[122:125], v[166:169], v[192:195], v[122:125]
	v_mfma_f32_16x16x32_bf16 v[110:113], v[158:161], v[200:203], v[110:113]
	v_mfma_f32_16x16x32_bf16 v[106:109], v[166:169], v[200:203], v[106:109]
	v_mfma_f32_16x16x32_bf16 v[94:97], v[158:161], v[208:211], v[94:97]
	v_mfma_f32_16x16x32_bf16 v[90:93], v[166:169], v[208:211], v[90:93]
	v_mfma_f32_16x16x32_bf16 v[78:81], v[158:161], v[216:219], v[78:81]
	v_mfma_f32_16x16x32_bf16 v[74:77], v[166:169], v[216:219], v[74:77]
	s_setprio 0
	s_setprio 1
	v_mfma_f32_16x16x32_bf16 v[118:121], v[170:173], v[186:189], v[118:121]
	v_mfma_f32_16x16x32_bf16 v[114:117], v[178:181], v[186:189], v[114:117]
	v_mfma_f32_16x16x32_bf16 v[102:105], v[170:173], v[196:199], v[102:105]
	v_mfma_f32_16x16x32_bf16 v[98:101], v[178:181], v[196:199], v[98:101]
	v_mfma_f32_16x16x32_bf16 v[86:89], v[170:173], v[204:207], v[86:89]
	v_mfma_f32_16x16x32_bf16 v[82:85], v[178:181], v[204:207], v[82:85]
	v_mfma_f32_16x16x32_bf16 v[70:73], v[170:173], v[212:215], v[70:73]
	v_mfma_f32_16x16x32_bf16 v[66:69], v[178:181], v[212:215], v[66:69]
	v_mfma_f32_16x16x32_bf16 v[118:121], v[174:177], v[192:195], v[118:121]
	v_mfma_f32_16x16x32_bf16 v[114:117], v[182:185], v[192:195], v[114:117]
	v_mfma_f32_16x16x32_bf16 v[102:105], v[174:177], v[200:203], v[102:105]
	v_mfma_f32_16x16x32_bf16 v[98:101], v[182:185], v[200:203], v[98:101]
	v_mfma_f32_16x16x32_bf16 v[86:89], v[174:177], v[208:211], v[86:89]
	v_mfma_f32_16x16x32_bf16 v[82:85], v[182:185], v[208:211], v[82:85]
	v_mfma_f32_16x16x32_bf16 v[70:73], v[174:177], v[216:219], v[70:73]
	v_mfma_f32_16x16x32_bf16 v[66:69], v[182:185], v[216:219], v[66:69]
	s_setprio 0
	s_barrier
	s_add_i32 s56, s48, s34
	v_lshl_add_u64 v[220:221], s[28:29], 0, v[132:133]
	s_mov_b32 m0, s56
	ds_read_b128 v[186:189], v155 offset:16384
	ds_read_b128 v[192:195], v155 offset:17408
	ds_read_b128 v[196:199], v155 offset:18432
	ds_read_b128 v[200:203], v155 offset:19456
	ds_read_b128 v[204:207], v155 offset:20480
	ds_read_b128 v[208:211], v155 offset:21504
	ds_read_b128 v[212:215], v155 offset:22528
	ds_read_b128 v[216:219], v155 offset:23552
	global_load_lds_dwordx4 v[220:221], off
	s_add_i32 m0, s56, 0x2000
	s_add_u32 s56, s28, 0x160000
	v_lshl_add_u64 v[222:223], s[28:29], 0, v[136:137]
	s_addc_u32 s57, s29, 0
	s_add_i32 s58, s49, s34
	global_load_lds_dwordx4 v[222:223], off
	v_lshl_add_u64 v[224:225], s[56:57], 0, v[132:133]
	s_mov_b32 m0, s58
	v_lshl_add_u64 v[226:227], s[30:31], 0, v[134:135]
	global_load_lds_dwordx4 v[224:225], off
	v_lshl_add_u64 v[224:225], s[56:57], 0, v[136:137]
	s_add_i32 m0, s58, 0x2000
	s_nop 0
	global_load_lds_dwordx4 v[224:225], off
	v_lshl_add_u64 v[224:225], s[30:31], 0, v[130:131]
	s_mov_b32 m0, s39
	s_nop 0
	global_load_lds_dwordx4 v[224:225], off
	s_mov_b32 m0, s40
	s_nop 0
	global_load_lds_dwordx4 v[226:227], off
	s_waitcnt vmcnt(8)
	s_waitcnt lgkmcnt(0)
	s_barrier
; #define PG8_STAGE(bufoff, gbase, voff) do { _Pragma("unroll") for (int _i = 0; _i < 2; ++_i) \
;         __builtin_amdgcn_global_load_lds((const unsigned*)((const char*)(gbase) + (voff)[_i]), (PG8_LAS unsigned*)(lds + (bufoff) + ldsw + _i * 8192), 16, 0, 0); } while (0)
; #define PG8_LDA(dst, b, h) do { _Pragma("unroll") for (int m = 0; m < 4; ++m) _Pragma("unroll") for (int k = 0; k < 2; ++k) dst[m][k] = *(const PG8_LAS bf16x8*)(lds + PG8_SA(b, h) + aoff + m * 2048 + k * 1024); } while (0)
; #define PG8_LDB(dst, b, h) do { _Pragma("unroll") for (int n = 0; n < 2; ++n) _Pragma("unroll") for (int k = 0; k < 2; ++k) dst[n][k] = *(const PG8_LAS bf16x8*)(lds + PG8_SB(b, h) + boff + n * 2048 + k * 1024); } while (0)
; #define PG8_MMA(ai, bj, At, Bt) do { __builtin_amdgcn_s_setprio(1); _Pragma("unroll") for (int m = 0; m < 4; ++m) _Pragma("unroll") for (int n = 0; n < 2; ++n) _Pragma("unroll") for (int k = 0; k < 2; ++k) \
;         acc[ai][bj][m][n] = __builtin_amdgcn_mfma_f32_16x16x32_bf16(Bt[n][k], At[m][k], acc[ai][bj][m][n], 0, 0, 0); __builtin_amdgcn_s_setprio(0); } while (0)
; #define PG8_WAIT_V(n) asm volatile("s_waitcnt vmcnt(" #n ")" ::: "memory")
; #define PG8_WAIT_L(n) asm volatile("s_waitcnt lgkmcnt(" #n ")" ::: "memory")
; #define PG8_BAR __builtin_amdgcn_s_barrier()
; #define PG8_SCHED __builtin_amdgcn_sched_barrier(0)
; template <class Epi, class Sched, bool ALIGN_EPI = false, bool SP2 = false>
; __device__ __forceinline__ void gemm_phase(PG8_LAS unsigned char* lds, const Gemm g, const Sched& S, const Epi& E) {
;     ...
;             PG8_WAIT_V(8); PG8_WAIT_L(0); PG8_BAR; PG8_MMA(1, 0, At, B0); PG8_MMA(1, 1, At, B1); PG8_BAR; PG8_SCHED;
;             PG8_LDB(B0, 1, 0); PG8_LDB(B1, 1, 1); PG8_SCHED; PG8_LDA(At, 1, 0); PG8_STAGE(PG8_SA(0, 1), a2 + hstep, voffA);
;             PG8_WAIT_V(8); PG8_WAIT_L(0); PG8_BAR; PG8_MMA(0, 0, At, B0); PG8_MMA(0, 1, At, B1); PG8_BAR; PG8_SCHED;
	s_setprio 1
	s_waitcnt lgkmcnt(0)
	v_mfma_f32_16x16x32_bf16 v[62:65], v[146:149], v[186:189], v[62:65]
	v_mfma_f32_16x16x32_bf16 v[58:61], v[162:165], v[186:189], v[58:61]
	v_mfma_f32_16x16x32_bf16 v[46:49], v[146:149], v[196:199], v[46:49]
	v_mfma_f32_16x16x32_bf16 v[42:45], v[162:165], v[196:199], v[42:45]
	v_mfma_f32_16x16x32_bf16 v[30:33], v[146:149], v[204:207], v[30:33]
	v_mfma_f32_16x16x32_bf16 v[26:29], v[162:165], v[204:207], v[26:29]
	v_mfma_f32_16x16x32_bf16 v[14:17], v[146:149], v[212:215], v[14:17]
	v_mfma_f32_16x16x32_bf16 v[10:13], v[162:165], v[212:215], v[10:13]
	v_mfma_f32_16x16x32_bf16 v[62:65], v[158:161], v[192:195], v[62:65]
	v_mfma_f32_16x16x32_bf16 v[58:61], v[166:169], v[192:195], v[58:61]
	v_mfma_f32_16x16x32_bf16 v[46:49], v[158:161], v[200:203], v[46:49]
	v_mfma_f32_16x16x32_bf16 v[42:45], v[166:169], v[200:203], v[42:45]
	v_mfma_f32_16x16x32_bf16 v[30:33], v[158:161], v[208:211], v[30:33]
	v_mfma_f32_16x16x32_bf16 v[26:29], v[166:169], v[208:211], v[26:29]
	v_mfma_f32_16x16x32_bf16 v[14:17], v[158:161], v[216:219], v[14:17]
	v_mfma_f32_16x16x32_bf16 v[10:13], v[166:169], v[216:219], v[10:13]
	s_setprio 0
	s_setprio 1
	v_mfma_f32_16x16x32_bf16 v[54:57], v[170:173], v[186:189], v[54:57]
	v_mfma_f32_16x16x32_bf16 v[50:53], v[178:181], v[186:189], v[50:53]
	v_mfma_f32_16x16x32_bf16 v[38:41], v[170:173], v[196:199], v[38:41]
	v_mfma_f32_16x16x32_bf16 v[34:37], v[178:181], v[196:199], v[34:37]
	v_mfma_f32_16x16x32_bf16 v[22:25], v[170:173], v[204:207], v[22:25]
	v_mfma_f32_16x16x32_bf16 v[18:21], v[178:181], v[204:207], v[18:21]
	v_mfma_f32_16x16x32_bf16 v[6:9], v[170:173], v[212:215], v[6:9]
	v_mfma_f32_16x16x32_bf16 v[2:5], v[178:181], v[212:215], v[2:5]
	v_mfma_f32_16x16x32_bf16 v[54:57], v[174:177], v[192:195], v[54:57]
	v_mfma_f32_16x16x32_bf16 v[50:53], v[182:185], v[192:195], v[50:53]
	v_mfma_f32_16x16x32_bf16 v[38:41], v[174:177], v[200:203], v[38:41]
	v_mfma_f32_16x16x32_bf16 v[34:37], v[182:185], v[200:203], v[34:37]
	v_mfma_f32_16x16x32_bf16 v[22:25], v[174:177], v[208:211], v[22:25]
	v_mfma_f32_16x16x32_bf16 v[18:21], v[182:185], v[208:211], v[18:21]
	v_mfma_f32_16x16x32_bf16 v[6:9], v[174:177], v[216:219], v[6:9]
	v_mfma_f32_16x16x32_bf16 v[2:5], v[182:185], v[216:219], v[2:5]
	s_setprio 0
	s_barrier
	s_add_i32 s56, 0, 0x18000
	v_add_u32_e32 v157, s56, v151
	s_add_i32 s57, 0, 0x1c000
	ds_read_b128 v[146:149], v157
	ds_read_b128 v[158:161], v157 offset:1024
	ds_read_b128 v[162:165], v157 offset:2048
	ds_read_b128 v[166:169], v157 offset:3072
	v_add_u32_e32 v157, s57, v151
	ds_read_b128 v[170:173], v157
	ds_read_b128 v[174:177], v157 offset:1024
	ds_read_b128 v[178:181], v157 offset:2048
	ds_read_b128 v[182:185], v157 offset:3072
	s_add_u32 s30, s30, 0x160000
	s_addc_u32 s31, s31, 0
	s_mov_b32 m0, s41
	v_lshl_add_u64 v[228:229], s[30:31], 0, v[130:131]
	ds_read_b128 v[186:189], v155 offset:32768
	ds_read_b128 v[192:195], v155 offset:33792
	ds_read_b128 v[196:199], v155 offset:34816
	ds_read_b128 v[200:203], v155 offset:35840
	ds_read_b128 v[204:207], v155 offset:36864
	ds_read_b128 v[208:211], v155 offset:37888
	ds_read_b128 v[212:215], v155 offset:38912
	ds_read_b128 v[216:219], v155 offset:39936
	global_load_lds_dwordx4 v[228:229], off
	v_lshl_add_u64 v[228:229], s[30:31], 0, v[134:135]
	s_mov_b32 m0, s42
	s_nop 0
	global_load_lds_dwordx4 v[228:229], off
	s_waitcnt vmcnt(8)
	s_waitcnt lgkmcnt(0)
	s_barrier
	s_setprio 1
	s_waitcnt lgkmcnt(0)
	v_mfma_f32_16x16x32_bf16 v[126:129], v[146:149], v[186:189], v[126:129]
	v_mfma_f32_16x16x32_bf16 v[122:125], v[162:165], v[186:189], v[122:125]
	v_mfma_f32_16x16x32_bf16 v[110:113], v[146:149], v[196:199], v[110:113]
	v_mfma_f32_16x16x32_bf16 v[106:109], v[162:165], v[196:199], v[106:109]
	v_mfma_f32_16x16x32_bf16 v[94:97], v[146:149], v[204:207], v[94:97]
	v_mfma_f32_16x16x32_bf16 v[90:93], v[162:165], v[204:207], v[90:93]
	v_mfma_f32_16x16x32_bf16 v[78:81], v[146:149], v[212:215], v[78:81]
	v_mfma_f32_16x16x32_bf16 v[74:77], v[162:165], v[212:215], v[74:77]
	v_mfma_f32_16x16x32_bf16 v[126:129], v[158:161], v[192:195], v[126:129]
	v_mfma_f32_16x16x32_bf16 v[122:125], v[166:169], v[192:195], v[122:125]
	v_mfma_f32_16x16x32_bf16 v[110:113], v[158:161], v[200:203], v[110:113]
	v_mfma_f32_16x16x32_bf16 v[106:109], v[166:169], v[200:203], v[106:109]
	v_mfma_f32_16x16x32_bf16 v[94:97], v[158:161], v[208:211], v[94:97]
	v_mfma_f32_16x16x32_bf16 v[90:93], v[166:169], v[208:211], v[90:93]
	v_mfma_f32_16x16x32_bf16 v[78:81], v[158:161], v[216:219], v[78:81]
	v_mfma_f32_16x16x32_bf16 v[74:77], v[166:169], v[216:219], v[74:77]
	s_setprio 0
	s_setprio 1
	v_mfma_f32_16x16x32_bf16 v[118:121], v[170:173], v[186:189], v[118:121]
	v_mfma_f32_16x16x32_bf16 v[114:117], v[178:181], v[186:189], v[114:117]
	v_mfma_f32_16x16x32_bf16 v[102:105], v[170:173], v[196:199], v[102:105]
	v_mfma_f32_16x16x32_bf16 v[98:101], v[178:181], v[196:199], v[98:101]
	v_mfma_f32_16x16x32_bf16 v[86:89], v[170:173], v[204:207], v[86:89]
	v_mfma_f32_16x16x32_bf16 v[82:85], v[178:181], v[204:207], v[82:85]
	v_mfma_f32_16x16x32_bf16 v[70:73], v[170:173], v[212:215], v[70:73]
	v_mfma_f32_16x16x32_bf16 v[66:69], v[178:181], v[212:215], v[66:69]
	v_mfma_f32_16x16x32_bf16 v[118:121], v[174:177], v[192:195], v[118:121]
	v_mfma_f32_16x16x32_bf16 v[114:117], v[182:185], v[192:195], v[114:117]
	v_mfma_f32_16x16x32_bf16 v[102:105], v[174:177], v[200:203], v[102:105]
	v_mfma_f32_16x16x32_bf16 v[98:101], v[182:185], v[200:203], v[98:101]
	v_mfma_f32_16x16x32_bf16 v[86:89], v[174:177], v[208:211], v[86:89]
	v_mfma_f32_16x16x32_bf16 v[82:85], v[182:185], v[208:211], v[82:85]
	v_mfma_f32_16x16x32_bf16 v[70:73], v[174:177], v[216:219], v[70:73]
	v_mfma_f32_16x16x32_bf16 v[66:69], v[182:185], v[216:219], v[66:69]
	s_setprio 0
	s_barrier
; #define PG8_STAGE(bufoff, gbase, voff) do { _Pragma("unroll") for (int _i = 0; _i < 2; ++_i) \
;         __builtin_amdgcn_global_load_lds((const unsigned*)((const char*)(gbase) + (voff)[_i]), (PG8_LAS unsigned*)(lds + (bufoff) + ldsw + _i * 8192), 16, 0, 0); } while (0)
; #define PG8_STAGEB(bufoff, gbase, voff) do { _Pragma("unroll") for (int _i = 0; _i < 2; ++_i) \
;         __builtin_amdgcn_global_load_lds((const unsigned*)((const char*)(gbase) + (voff)[_i]), (PG8_LAS unsigned*)(lds + (bufoff) + ldsw + _i * 8192), 16, 0, PG8_BAUX); } while (0)
; #define PG8_LDA(dst, b, h) do { _Pragma("unroll") for (int m = 0; m < 4; ++m) _Pragma("unroll") for (int k = 0; k < 2; ++k) dst[m][k] = *(const PG8_LAS bf16x8*)(lds + PG8_SA(b, h) + aoff + m * 2048 + k * 1024); } while (0)
; #define PG8_MMA(ai, bj, At, Bt) do { __builtin_amdgcn_s_setprio(1); _Pragma("unroll") for (int m = 0; m < 4; ++m) _Pragma("unroll") for (int n = 0; n < 2; ++n) _Pragma("unroll") for (int k = 0; k < 2; ++k) \
;         acc[ai][bj][m][n] = __builtin_amdgcn_mfma_f32_16x16x32_bf16(Bt[n][k], At[m][k], acc[ai][bj][m][n], 0, 0, 0); __builtin_amdgcn_s_setprio(0); } while (0)
; #define PG8_WAIT_V(n) asm volatile("s_waitcnt vmcnt(" #n ")" ::: "memory")
; #define PG8_WAIT_L(n) asm volatile("s_waitcnt lgkmcnt(" #n ")" ::: "memory")
; #define PG8_BAR __builtin_amdgcn_s_barrier()
; #define PG8_SCHED __builtin_amdgcn_sched_barrier(0)
; template <class Epi, class Sched, bool ALIGN_EPI = false, bool SP2 = false>
; __device__ __forceinline__ void gemm_phase(PG8_LAS unsigned char* lds, const Gemm g, const Sched& S, const Epi& E) {
;     ...
;         for (int t = 0; t < nt; t += 2) {
;     ...
;             PG8_LDA(At, 1, 1); PG8_STAGEB(PG8_SB(1, 0), b3, voffB); PG8_STAGEB(PG8_SB(1, 1), b3 + hstep, voffB); PG8_STAGE(PG8_SA(1, 0), a3, voffA);
;             PG8_WAIT_V(8); PG8_WAIT_L(0); PG8_BAR; PG8_MMA(1, 0, At, B0); PG8_MMA(1, 1, At, B1); PG8_BAR; PG8_SCHED;
	s_add_i32 s30, s56, s34
	v_lshl_add_u64 v[220:221], v[220:221], 0, s[20:21]
	s_mov_b32 m0, s30
	ds_read_b128 v[186:189], v155 offset:49152
	ds_read_b128 v[192:195], v155 offset:50176
	ds_read_b128 v[196:199], v155 offset:51200
	ds_read_b128 v[200:203], v155 offset:52224
	ds_read_b128 v[204:207], v155 offset:53248
	ds_read_b128 v[208:211], v155 offset:54272
	ds_read_b128 v[212:215], v155 offset:55296
	ds_read_b128 v[216:219], v155 offset:56320
	global_load_lds_dwordx4 v[220:221], off
	s_add_i32 m0, s30, 0x2000
	s_add_u32 s28, s28, 0x160080
	v_lshl_add_u64 v[220:221], v[222:223], 0, s[20:21]
	s_addc_u32 s29, s29, 0
	s_add_i32 s30, s57, s34
	global_load_lds_dwordx4 v[220:221], off
	v_lshl_add_u64 v[220:221], s[28:29], 0, v[132:133]
	s_mov_b32 m0, s30
	s_nop 0
	global_load_lds_dwordx4 v[220:221], off
	v_lshl_add_u64 v[220:221], s[28:29], 0, v[136:137]
	s_add_i32 m0, s30, 0x2000
	s_nop 0
	global_load_lds_dwordx4 v[220:221], off
	v_lshl_add_u64 v[220:221], v[224:225], 0, s[20:21]
	s_mov_b32 m0, s44
	s_nop 0
	global_load_lds_dwordx4 v[220:221], off
	v_lshl_add_u64 v[220:221], v[226:227], 0, s[20:21]
	s_mov_b32 m0, s45
	s_nop 0
	global_load_lds_dwordx4 v[220:221], off
	s_waitcnt vmcnt(8)
	s_waitcnt lgkmcnt(0)
	s_barrier
	s_setprio 1
	s_waitcnt lgkmcnt(0)
	v_mfma_f32_16x16x32_bf16 v[62:65], v[146:149], v[186:189], v[62:65]
	v_mfma_f32_16x16x32_bf16 v[58:61], v[162:165], v[186:189], v[58:61]
	v_mfma_f32_16x16x32_bf16 v[46:49], v[146:149], v[196:199], v[46:49]
	v_mfma_f32_16x16x32_bf16 v[42:45], v[162:165], v[196:199], v[42:45]
	v_mfma_f32_16x16x32_bf16 v[30:33], v[146:149], v[204:207], v[30:33]
	v_mfma_f32_16x16x32_bf16 v[26:29], v[162:165], v[204:207], v[26:29]
	v_mfma_f32_16x16x32_bf16 v[14:17], v[146:149], v[212:215], v[14:17]
	v_mfma_f32_16x16x32_bf16 v[10:13], v[162:165], v[212:215], v[10:13]
	v_mfma_f32_16x16x32_bf16 v[62:65], v[158:161], v[192:195], v[62:65]
	v_mfma_f32_16x16x32_bf16 v[58:61], v[166:169], v[192:195], v[58:61]
	v_mfma_f32_16x16x32_bf16 v[46:49], v[158:161], v[200:203], v[46:49]
	v_mfma_f32_16x16x32_bf16 v[42:45], v[166:169], v[200:203], v[42:45]
	v_mfma_f32_16x16x32_bf16 v[30:33], v[158:161], v[208:211], v[30:33]
	v_mfma_f32_16x16x32_bf16 v[26:29], v[166:169], v[208:211], v[26:29]
	v_mfma_f32_16x16x32_bf16 v[14:17], v[158:161], v[216:219], v[14:17]
	v_mfma_f32_16x16x32_bf16 v[10:13], v[166:169], v[216:219], v[10:13]
	s_setprio 0
	s_setprio 1
	v_mfma_f32_16x16x32_bf16 v[54:57], v[170:173], v[186:189], v[54:57]
	v_mfma_f32_16x16x32_bf16 v[50:53], v[178:181], v[186:189], v[50:53]
	v_mfma_f32_16x16x32_bf16 v[38:41], v[170:173], v[196:199], v[38:41]
	v_mfma_f32_16x16x32_bf16 v[34:37], v[178:181], v[196:199], v[34:37]
	v_mfma_f32_16x16x32_bf16 v[22:25], v[170:173], v[204:207], v[22:25]
	v_mfma_f32_16x16x32_bf16 v[18:21], v[178:181], v[204:207], v[18:21]
	v_mfma_f32_16x16x32_bf16 v[6:9], v[170:173], v[212:215], v[6:9]
	v_mfma_f32_16x16x32_bf16 v[2:5], v[178:181], v[212:215], v[2:5]
	v_mfma_f32_16x16x32_bf16 v[54:57], v[174:177], v[192:195], v[54:57]
	v_mfma_f32_16x16x32_bf16 v[50:53], v[182:185], v[192:195], v[50:53]
	v_mfma_f32_16x16x32_bf16 v[38:41], v[174:177], v[200:203], v[38:41]
	v_mfma_f32_16x16x32_bf16 v[34:37], v[182:185], v[200:203], v[34:37]
	v_mfma_f32_16x16x32_bf16 v[22:25], v[174:177], v[208:211], v[22:25]
	v_mfma_f32_16x16x32_bf16 v[18:21], v[182:185], v[208:211], v[18:21]
	v_mfma_f32_16x16x32_bf16 v[6:9], v[174:177], v[216:219], v[6:9]
	v_mfma_f32_16x16x32_bf16 v[2:5], v[182:185], v[216:219], v[2:5]
	s_setprio 0
	s_add_i32 s55, s55, 2
	s_add_u32 s26, s26, 0x100
	s_addc_u32 s27, s27, 0
	s_add_u32 s53, s53, 0x100
	s_addc_u32 s54, s54, 0
	s_cmpk_gt_u32 s55, 0x55
	s_barrier
	s_cbranch_scc0 .LBB0_608
	s_and_b64 vcc, exec, s[22:23]
	s_cbranch_vccz .LBB0_611
	s_barrier

; #define PG8_STAGE(bufoff, gbase, voff) do { _Pragma("unroll") for (int _i = 0; _i < 2; ++_i) \
;         __builtin_amdgcn_global_load_lds((const unsigned*)((const char*)(gbase) + (voff)[_i]), (PG8_LAS unsigned*)(lds + (bufoff) + ldsw + _i * 8192), 16, 0, 0); } while (0)
; #define PG8_STAGEB(bufoff, gbase, voff) do { _Pragma("unroll") for (int _i = 0; _i < 2; ++_i) \
;         __builtin_amdgcn_global_load_lds((const unsigned*)((const char*)(gbase) + (voff)[_i]), (PG8_LAS unsigned*)(lds + (bufoff) + ldsw + _i * 8192), 16, 0, PG8_BAUX); } while (0)
; #define PG8_LDA(dst, b, h) do { _Pragma("unroll") for (int m = 0; m < 4; ++m) _Pragma("unroll") for (int k = 0; k < 2; ++k) dst[m][k] = *(const PG8_LAS bf16x8*)(lds + PG8_SA(b, h) + aoff + m * 2048 + k * 1024); } while (0)
; #define PG8_LDB(dst, b, h) do { _Pragma("unroll") for (int n = 0; n < 2; ++n) _Pragma("unroll") for (int k = 0; k < 2; ++k) dst[n][k] = *(const PG8_LAS bf16x8*)(lds + PG8_SB(b, h) + boff + n * 2048 + k * 1024); } while (0)
; #define PG8_MMA(ai, bj, At, Bt) do { __builtin_amdgcn_s_setprio(1); _Pragma("unroll") for (int m = 0; m < 4; ++m) _Pragma("unroll") for (int n = 0; n < 2; ++n) _Pragma("unroll") for (int k = 0; k < 2; ++k) \
;         acc[ai][bj][m][n] = __builtin_amdgcn_mfma_f32_16x16x32_bf16(Bt[n][k], At[m][k], acc[ai][bj][m][n], 0, 0, 0); __builtin_amdgcn_s_setprio(0); } while (0)
; template <class Epi, class Sched, bool ALIGN_EPI = false, bool SP2 = false>
; __device__ __forceinline__ void gemm_phase(PG8_LAS unsigned char* lds, const Gemm g, const Sched& S, const Epi& E) {
;     ...
;             const bool last = (t == nt - 2);
;             const char* a1 = cA + (size_t)(t + 1) * kstep;
;             const char* a2 = last ? nA : cA + (size_t)(t + 2) * kstep; const char* b2 = last ? nB : cB + (size_t)(t + 2) * kstep;
;             const char* a3 = a2 + kstep; const char* b3 = b2 + kstep;
;             if (last && has_next) S.a_ready(nxt);
;             if constexpr (SP2) {
;             PG8_LDB(B0, 0, 0); PG8_LDB(B1, 0, 1); PG8_SCHED; PG8_LDA(At, 0, 0); PG8_STAGE(PG8_SA(1, 1), a1 + hstep, voffA);
;             PG8_WAIT_V(8); PG8_WAIT_L(0); PG8_BAR; PG8_MMA(0, 0, At, B0); PG8_MMA(0, 1, At, B1); PG8_BAR; PG8_SCHED;
;             PG8_LDA(At, 0, 1); PG8_STAGEB(PG8_SB(0, 0), b2, voffB); PG8_STAGEB(PG8_SB(0, 1), b2 + hstep, voffB); PG8_STAGE(PG8_SA(0, 0), a2, voffA);
.LBB0_709:
	ds_read_b128 v[160:163], v141
	ds_read_b128 v[164:167], v141 offset:1024
	ds_read_b128 v[168:171], v141 offset:2048
	ds_read_b128 v[172:175], v141 offset:3072
	ds_read_b128 v[176:179], v196
	ds_read_b128 v[202:205], v196 offset:1024
	ds_read_b128 v[206:209], v196 offset:2048
	ds_read_b128 v[210:213], v196 offset:3072
	s_add_u32 s6, s4, 0xfff80080
	s_addc_u32 s7, s5, -1
	s_cmp_eq_u32 s50, 28
	s_cselect_b32 s9, s3, s7
	s_cselect_b32 s8, s15, s6
	s_cselect_b32 s7, s18, s45
	s_cselect_b32 s6, s33, s43
	v_lshl_add_u64 v[180:181], s[4:5], 0, v[156:157]
	s_add_i32 m0, s63, 0xc000
	ds_read_b128 v[214:217], v197
	ds_read_b128 v[218:221], v197 offset:1024
	ds_read_b128 v[222:225], v197 offset:2048
	ds_read_b128 v[226:229], v197 offset:3072
	ds_read_b128 v[230:233], v197 offset:4096
	ds_read_b128 v[234:237], v197 offset:5120
	ds_read_b128 v[238:241], v197 offset:6144
	ds_read_b128 v[242:245], v197 offset:7168
	global_load_lds_dwordx4 v[180:181], off
	v_lshl_add_u64 v[180:181], s[4:5], 0, v[158:159]
	s_add_i32 m0, s63, 0xe000
	s_nop 0
	global_load_lds_dwordx4 v[180:181], off
	s_waitcnt vmcnt(8)
	s_waitcnt lgkmcnt(0)
	s_barrier
	s_setprio 1
	s_waitcnt lgkmcnt(0)
	v_mfma_f32_16x16x32_bf16 v[126:129], v[160:163], v[214:217], v[126:129]
	v_mfma_f32_16x16x32_bf16 v[122:125], v[168:171], v[214:217], v[122:125]
	v_mfma_f32_16x16x32_bf16 v[110:113], v[160:163], v[222:225], v[110:113]
	v_mfma_f32_16x16x32_bf16 v[106:109], v[168:171], v[222:225], v[106:109]
	v_mfma_f32_16x16x32_bf16 v[94:97], v[160:163], v[230:233], v[94:97]
	v_mfma_f32_16x16x32_bf16 v[90:93], v[168:171], v[230:233], v[90:93]
	v_mfma_f32_16x16x32_bf16 v[78:81], v[160:163], v[238:241], v[78:81]
	v_mfma_f32_16x16x32_bf16 v[74:77], v[168:171], v[238:241], v[74:77]
	v_mfma_f32_16x16x32_bf16 v[126:129], v[164:167], v[218:221], v[126:129]
	v_mfma_f32_16x16x32_bf16 v[122:125], v[172:175], v[218:221], v[122:125]
	v_mfma_f32_16x16x32_bf16 v[110:113], v[164:167], v[226:229], v[110:113]
	v_mfma_f32_16x16x32_bf16 v[106:109], v[172:175], v[226:229], v[106:109]
	v_mfma_f32_16x16x32_bf16 v[94:97], v[164:167], v[234:237], v[94:97]
	v_mfma_f32_16x16x32_bf16 v[90:93], v[172:175], v[234:237], v[90:93]
	v_mfma_f32_16x16x32_bf16 v[78:81], v[164:167], v[242:245], v[78:81]
	v_mfma_f32_16x16x32_bf16 v[74:77], v[172:175], v[242:245], v[74:77]
	s_setprio 0
	s_setprio 1
	v_mfma_f32_16x16x32_bf16 v[118:121], v[176:179], v[214:217], v[118:121]
	v_mfma_f32_16x16x32_bf16 v[114:117], v[206:209], v[214:217], v[114:117]
	v_mfma_f32_16x16x32_bf16 v[102:105], v[176:179], v[222:225], v[102:105]
	v_mfma_f32_16x16x32_bf16 v[98:101], v[206:209], v[222:225], v[98:101]
	v_mfma_f32_16x16x32_bf16 v[86:89], v[176:179], v[230:233], v[86:89]
	v_mfma_f32_16x16x32_bf16 v[82:85], v[206:209], v[230:233], v[82:85]
	v_mfma_f32_16x16x32_bf16 v[70:73], v[176:179], v[238:241], v[70:73]
	v_mfma_f32_16x16x32_bf16 v[66:69], v[206:209], v[238:241], v[66:69]
	v_mfma_f32_16x16x32_bf16 v[118:121], v[202:205], v[218:221], v[118:121]
	v_mfma_f32_16x16x32_bf16 v[114:117], v[210:213], v[218:221], v[114:117]
	v_mfma_f32_16x16x32_bf16 v[102:105], v[202:205], v[226:229], v[102:105]
	v_mfma_f32_16x16x32_bf16 v[98:101], v[210:213], v[226:229], v[98:101]
	v_mfma_f32_16x16x32_bf16 v[86:89], v[202:205], v[234:237], v[86:89]
	v_mfma_f32_16x16x32_bf16 v[82:85], v[210:213], v[234:237], v[82:85]
	v_mfma_f32_16x16x32_bf16 v[70:73], v[202:205], v[242:245], v[70:73]
	v_mfma_f32_16x16x32_bf16 v[66:69], v[210:213], v[242:245], v[66:69]
	s_setprio 0
	s_barrier
	s_add_i32 s51, s77, s60
	v_lshl_add_u64 v[180:181], s[6:7], 0, v[132:133]
	s_mov_b32 m0, s51
	ds_read_b128 v[214:217], v197 offset:16384
	ds_read_b128 v[218:221], v197 offset:17408
	ds_read_b128 v[222:225], v197 offset:18432
	ds_read_b128 v[226:229], v197 offset:19456
	ds_read_b128 v[230:233], v197 offset:20480
	ds_read_b128 v[234:237], v197 offset:21504
	ds_read_b128 v[238:241], v197 offset:22528
	ds_read_b128 v[242:245], v197 offset:23552
	global_load_lds_dwordx4 v[180:181], off
	s_add_i32 m0, s51, 0x2000
	s_add_u32 s52, s6, 0x80000
	v_lshl_add_u64 v[246:247], s[6:7], 0, v[136:137]
	s_addc_u32 s53, s7, 0
	s_add_i32 s51, s78, s60
	global_load_lds_dwordx4 v[246:247], off
	v_lshl_add_u64 v[248:249], s[52:53], 0, v[132:133]
	s_mov_b32 m0, s51
	v_lshl_add_u64 v[250:251], s[8:9], 0, v[134:135]
	global_load_lds_dwordx4 v[248:249], off
	v_lshl_add_u64 v[248:249], s[52:53], 0, v[136:137]
	s_add_i32 m0, s51, 0x2000
	s_nop 0
	global_load_lds_dwordx4 v[248:249], off
	v_lshl_add_u64 v[248:249], s[8:9], 0, v[130:131]
	s_mov_b32 m0, s63
	s_nop 0
	global_load_lds_dwordx4 v[248:249], off
	s_mov_b32 m0, s64
	s_nop 0
	global_load_lds_dwordx4 v[250:251], off
	s_waitcnt vmcnt(8)
	s_waitcnt lgkmcnt(0)
	s_barrier
; #define PG8_STAGE(bufoff, gbase, voff) do { _Pragma("unroll") for (int _i = 0; _i < 2; ++_i) \
;         __builtin_amdgcn_global_load_lds((const unsigned*)((const char*)(gbase) + (voff)[_i]), (PG8_LAS unsigned*)(lds + (bufoff) + ldsw + _i * 8192), 16, 0, 0); } while (0)
; #define PG8_LDA(dst, b, h) do { _Pragma("unroll") for (int m = 0; m < 4; ++m) _Pragma("unroll") for (int k = 0; k < 2; ++k) dst[m][k] = *(const PG8_LAS bf16x8*)(lds + PG8_SA(b, h) + aoff + m * 2048 + k * 1024); } while (0)
; #define PG8_LDB(dst, b, h) do { _Pragma("unroll") for (int n = 0; n < 2; ++n) _Pragma("unroll") for (int k = 0; k < 2; ++k) dst[n][k] = *(const PG8_LAS bf16x8*)(lds + PG8_SB(b, h) + boff + n * 2048 + k * 1024); } while (0)
; #define PG8_MMA(ai, bj, At, Bt) do { __builtin_amdgcn_s_setprio(1); _Pragma("unroll") for (int m = 0; m < 4; ++m) _Pragma("unroll") for (int n = 0; n < 2; ++n) _Pragma("unroll") for (int k = 0; k < 2; ++k) \
;         acc[ai][bj][m][n] = __builtin_amdgcn_mfma_f32_16x16x32_bf16(Bt[n][k], At[m][k], acc[ai][bj][m][n], 0, 0, 0); __builtin_amdgcn_s_setprio(0); } while (0)
; #define PG8_WAIT_V(n) asm volatile("s_waitcnt vmcnt(" #n ")" ::: "memory")
; #define PG8_WAIT_L(n) asm volatile("s_waitcnt lgkmcnt(" #n ")" ::: "memory")
; #define PG8_BAR __builtin_amdgcn_s_barrier()
; #define PG8_SCHED __builtin_amdgcn_sched_barrier(0)
; template <class Epi, class Sched, bool ALIGN_EPI = false, bool SP2 = false>
; __device__ __forceinline__ void gemm_phase(PG8_LAS unsigned char* lds, const Gemm g, const Sched& S, const Epi& E) {
;     ...
;             PG8_WAIT_V(8); PG8_WAIT_L(0); PG8_BAR; PG8_MMA(1, 0, At, B0); PG8_MMA(1, 1, At, B1); PG8_BAR; PG8_SCHED;
;             PG8_LDB(B0, 1, 0); PG8_LDB(B1, 1, 1); PG8_SCHED; PG8_LDA(At, 1, 0); PG8_STAGE(PG8_SA(0, 1), a2 + hstep, voffA);
;             PG8_WAIT_V(8); PG8_WAIT_L(0); PG8_BAR; PG8_MMA(0, 0, At, B0); PG8_MMA(0, 1, At, B1); PG8_BAR; PG8_SCHED;
	s_setprio 1
	s_waitcnt lgkmcnt(0)
	v_mfma_f32_16x16x32_bf16 v[62:65], v[160:163], v[214:217], v[62:65]
	v_mfma_f32_16x16x32_bf16 v[58:61], v[168:171], v[214:217], v[58:61]
	v_mfma_f32_16x16x32_bf16 v[46:49], v[160:163], v[222:225], v[46:49]
	v_mfma_f32_16x16x32_bf16 v[42:45], v[168:171], v[222:225], v[42:45]
	v_mfma_f32_16x16x32_bf16 v[30:33], v[160:163], v[230:233], v[30:33]
	v_mfma_f32_16x16x32_bf16 v[26:29], v[168:171], v[230:233], v[26:29]
	v_mfma_f32_16x16x32_bf16 v[14:17], v[160:163], v[238:241], v[14:17]
	v_mfma_f32_16x16x32_bf16 v[10:13], v[168:171], v[238:241], v[10:13]
	v_mfma_f32_16x16x32_bf16 v[62:65], v[164:167], v[218:221], v[62:65]
	v_mfma_f32_16x16x32_bf16 v[58:61], v[172:175], v[218:221], v[58:61]
	v_mfma_f32_16x16x32_bf16 v[46:49], v[164:167], v[226:229], v[46:49]
	v_mfma_f32_16x16x32_bf16 v[42:45], v[172:175], v[226:229], v[42:45]
	v_mfma_f32_16x16x32_bf16 v[30:33], v[164:167], v[234:237], v[30:33]
	v_mfma_f32_16x16x32_bf16 v[26:29], v[172:175], v[234:237], v[26:29]
	v_mfma_f32_16x16x32_bf16 v[14:17], v[164:167], v[242:245], v[14:17]
	v_mfma_f32_16x16x32_bf16 v[10:13], v[172:175], v[242:245], v[10:13]
	s_setprio 0
	s_setprio 1
	v_mfma_f32_16x16x32_bf16 v[54:57], v[176:179], v[214:217], v[54:57]
	v_mfma_f32_16x16x32_bf16 v[50:53], v[206:209], v[214:217], v[50:53]
	v_mfma_f32_16x16x32_bf16 v[38:41], v[176:179], v[222:225], v[38:41]
	v_mfma_f32_16x16x32_bf16 v[34:37], v[206:209], v[222:225], v[34:37]
	v_mfma_f32_16x16x32_bf16 v[22:25], v[176:179], v[230:233], v[22:25]
	v_mfma_f32_16x16x32_bf16 v[18:21], v[206:209], v[230:233], v[18:21]
	v_mfma_f32_16x16x32_bf16 v[6:9], v[176:179], v[238:241], v[6:9]
	v_mfma_f32_16x16x32_bf16 v[2:5], v[206:209], v[238:241], v[2:5]
	v_mfma_f32_16x16x32_bf16 v[54:57], v[202:205], v[218:221], v[54:57]
	v_mfma_f32_16x16x32_bf16 v[50:53], v[210:213], v[218:221], v[50:53]
	v_mfma_f32_16x16x32_bf16 v[38:41], v[202:205], v[226:229], v[38:41]
	v_mfma_f32_16x16x32_bf16 v[34:37], v[210:213], v[226:229], v[34:37]
	v_mfma_f32_16x16x32_bf16 v[22:25], v[202:205], v[234:237], v[22:25]
	v_mfma_f32_16x16x32_bf16 v[18:21], v[210:213], v[234:237], v[18:21]
	v_mfma_f32_16x16x32_bf16 v[6:9], v[202:205], v[242:245], v[6:9]
	v_mfma_f32_16x16x32_bf16 v[2:5], v[210:213], v[242:245], v[2:5]
	s_setprio 0
	s_barrier
	s_add_i32 s51, 0, 0x18000
	v_add_u32_e32 v142, s51, v193
	s_add_i32 s52, 0, 0x1c000
	ds_read_b128 v[160:163], v142
	ds_read_b128 v[164:167], v142 offset:1024
	ds_read_b128 v[168:171], v142 offset:2048
	ds_read_b128 v[172:175], v142 offset:3072
	v_add_u32_e32 v142, s52, v193
	ds_read_b128 v[176:179], v142
	ds_read_b128 v[202:205], v142 offset:1024
	ds_read_b128 v[206:209], v142 offset:2048
	ds_read_b128 v[210:213], v142 offset:3072
	s_add_u32 s8, s8, 0x80000
	s_addc_u32 s9, s9, 0
	s_mov_b32 m0, s65
	v_lshl_add_u64 v[252:253], s[8:9], 0, v[130:131]
	ds_read_b128 v[214:217], v197 offset:32768
	ds_read_b128 v[218:221], v197 offset:33792
	ds_read_b128 v[222:225], v197 offset:34816
	ds_read_b128 v[226:229], v197 offset:35840
	ds_read_b128 v[230:233], v197 offset:36864
	ds_read_b128 v[234:237], v197 offset:37888
	ds_read_b128 v[238:241], v197 offset:38912
	ds_read_b128 v[242:245], v197 offset:39936
	global_load_lds_dwordx4 v[252:253], off
	v_lshl_add_u64 v[252:253], s[8:9], 0, v[134:135]
	s_mov_b32 m0, s66
	s_nop 0
	global_load_lds_dwordx4 v[252:253], off
	s_waitcnt vmcnt(8)
	s_waitcnt lgkmcnt(0)
	s_barrier
	s_setprio 1
	s_waitcnt lgkmcnt(0)
	v_mfma_f32_16x16x32_bf16 v[126:129], v[160:163], v[214:217], v[126:129]
	v_mfma_f32_16x16x32_bf16 v[122:125], v[168:171], v[214:217], v[122:125]
	v_mfma_f32_16x16x32_bf16 v[110:113], v[160:163], v[222:225], v[110:113]
	v_mfma_f32_16x16x32_bf16 v[106:109], v[168:171], v[222:225], v[106:109]
	v_mfma_f32_16x16x32_bf16 v[94:97], v[160:163], v[230:233], v[94:97]
	v_mfma_f32_16x16x32_bf16 v[90:93], v[168:171], v[230:233], v[90:93]
	v_mfma_f32_16x16x32_bf16 v[78:81], v[160:163], v[238:241], v[78:81]
	v_mfma_f32_16x16x32_bf16 v[74:77], v[168:171], v[238:241], v[74:77]
	v_mfma_f32_16x16x32_bf16 v[126:129], v[164:167], v[218:221], v[126:129]
	v_mfma_f32_16x16x32_bf16 v[122:125], v[172:175], v[218:221], v[122:125]
	v_mfma_f32_16x16x32_bf16 v[110:113], v[164:167], v[226:229], v[110:113]
	v_mfma_f32_16x16x32_bf16 v[106:109], v[172:175], v[226:229], v[106:109]
	v_mfma_f32_16x16x32_bf16 v[94:97], v[164:167], v[234:237], v[94:97]
	v_mfma_f32_16x16x32_bf16 v[90:93], v[172:175], v[234:237], v[90:93]
	v_mfma_f32_16x16x32_bf16 v[78:81], v[164:167], v[242:245], v[78:81]
	v_mfma_f32_16x16x32_bf16 v[74:77], v[172:175], v[242:245], v[74:77]
	s_setprio 0
	s_setprio 1
	v_mfma_f32_16x16x32_bf16 v[118:121], v[176:179], v[214:217], v[118:121]
	v_mfma_f32_16x16x32_bf16 v[114:117], v[206:209], v[214:217], v[114:117]
	v_mfma_f32_16x16x32_bf16 v[102:105], v[176:179], v[222:225], v[102:105]
	v_mfma_f32_16x16x32_bf16 v[98:101], v[206:209], v[222:225], v[98:101]
	v_mfma_f32_16x16x32_bf16 v[86:89], v[176:179], v[230:233], v[86:89]
	v_mfma_f32_16x16x32_bf16 v[82:85], v[206:209], v[230:233], v[82:85]
	v_mfma_f32_16x16x32_bf16 v[70:73], v[176:179], v[238:241], v[70:73]
	v_mfma_f32_16x16x32_bf16 v[66:69], v[206:209], v[238:241], v[66:69]
	v_mfma_f32_16x16x32_bf16 v[118:121], v[202:205], v[218:221], v[118:121]
	v_mfma_f32_16x16x32_bf16 v[114:117], v[210:213], v[218:221], v[114:117]
	v_mfma_f32_16x16x32_bf16 v[102:105], v[202:205], v[226:229], v[102:105]
	v_mfma_f32_16x16x32_bf16 v[98:101], v[210:213], v[226:229], v[98:101]
	v_mfma_f32_16x16x32_bf16 v[86:89], v[202:205], v[234:237], v[86:89]
	v_mfma_f32_16x16x32_bf16 v[82:85], v[210:213], v[234:237], v[82:85]
	v_mfma_f32_16x16x32_bf16 v[70:73], v[202:205], v[242:245], v[70:73]
	v_mfma_f32_16x16x32_bf16 v[66:69], v[210:213], v[242:245], v[66:69]
	s_setprio 0
	s_barrier
; #define PG8_STAGE(bufoff, gbase, voff) do { _Pragma("unroll") for (int _i = 0; _i < 2; ++_i) \
;         __builtin_amdgcn_global_load_lds((const unsigned*)((const char*)(gbase) + (voff)[_i]), (PG8_LAS unsigned*)(lds + (bufoff) + ldsw + _i * 8192), 16, 0, 0); } while (0)
; #define PG8_STAGEB(bufoff, gbase, voff) do { _Pragma("unroll") for (int _i = 0; _i < 2; ++_i) \
;         __builtin_amdgcn_global_load_lds((const unsigned*)((const char*)(gbase) + (voff)[_i]), (PG8_LAS unsigned*)(lds + (bufoff) + ldsw + _i * 8192), 16, 0, PG8_BAUX); } while (0)
; #define PG8_LDA(dst, b, h) do { _Pragma("unroll") for (int m = 0; m < 4; ++m) _Pragma("unroll") for (int k = 0; k < 2; ++k) dst[m][k] = *(const PG8_LAS bf16x8*)(lds + PG8_SA(b, h) + aoff + m * 2048 + k * 1024); } while (0)
; #define PG8_MMA(ai, bj, At, Bt) do { __builtin_amdgcn_s_setprio(1); _Pragma("unroll") for (int m = 0; m < 4; ++m) _Pragma("unroll") for (int n = 0; n < 2; ++n) _Pragma("unroll") for (int k = 0; k < 2; ++k) \
;         acc[ai][bj][m][n] = __builtin_amdgcn_mfma_f32_16x16x32_bf16(Bt[n][k], At[m][k], acc[ai][bj][m][n], 0, 0, 0); __builtin_amdgcn_s_setprio(0); } while (0)
; #define PG8_WAIT_V(n) asm volatile("s_waitcnt vmcnt(" #n ")" ::: "memory")
; #define PG8_WAIT_L(n) asm volatile("s_waitcnt lgkmcnt(" #n ")" ::: "memory")
; #define PG8_BAR __builtin_amdgcn_s_barrier()
; #define PG8_SCHED __builtin_amdgcn_sched_barrier(0)
; template <class Epi, class Sched, bool ALIGN_EPI = false, bool SP2 = false>
; __device__ __forceinline__ void gemm_phase(PG8_LAS unsigned char* lds, const Gemm g, const Sched& S, const Epi& E) {
;     ...
;         for (int t = 0; t < nt; t += 2) {
;     ...
;             PG8_LDA(At, 1, 1); PG8_STAGEB(PG8_SB(1, 0), b3, voffB); PG8_STAGEB(PG8_SB(1, 1), b3 + hstep, voffB); PG8_STAGE(PG8_SA(1, 0), a3, voffA);
;             PG8_WAIT_V(8); PG8_WAIT_L(0); PG8_BAR; PG8_MMA(1, 0, At, B0); PG8_MMA(1, 1, At, B1); PG8_BAR; PG8_SCHED;
	s_add_i32 s8, s51, s60
	v_lshl_add_u64 v[180:181], v[180:181], 0, s[22:23]
	s_mov_b32 m0, s8
	ds_read_b128 v[214:217], v197 offset:49152
	ds_read_b128 v[218:221], v197 offset:50176
	ds_read_b128 v[222:225], v197 offset:51200
	ds_read_b128 v[226:229], v197 offset:52224
	ds_read_b128 v[230:233], v197 offset:53248
	ds_read_b128 v[234:237], v197 offset:54272
	ds_read_b128 v[238:241], v197 offset:55296
	ds_read_b128 v[242:245], v197 offset:56320
	global_load_lds_dwordx4 v[180:181], off
	s_add_i32 m0, s8, 0x2000
	s_add_u32 s6, s6, 0x80080
	v_lshl_add_u64 v[180:181], v[246:247], 0, s[22:23]
	s_addc_u32 s7, s7, 0
	s_add_i32 s8, s52, s60
	global_load_lds_dwordx4 v[180:181], off
	v_lshl_add_u64 v[180:181], s[6:7], 0, v[132:133]
	s_mov_b32 m0, s8
	s_nop 0
	global_load_lds_dwordx4 v[180:181], off
	v_lshl_add_u64 v[180:181], s[6:7], 0, v[136:137]
	s_add_i32 m0, s8, 0x2000
	s_nop 0
	global_load_lds_dwordx4 v[180:181], off
	v_lshl_add_u64 v[180:181], v[248:249], 0, s[22:23]
	s_mov_b32 m0, s70
	s_nop 0
	global_load_lds_dwordx4 v[180:181], off
	v_lshl_add_u64 v[180:181], v[250:251], 0, s[22:23]
	s_mov_b32 m0, s71
	s_nop 0
	global_load_lds_dwordx4 v[180:181], off
	s_waitcnt vmcnt(8)
	s_waitcnt lgkmcnt(0)
	s_barrier
	s_setprio 1
	s_waitcnt lgkmcnt(0)
	v_mfma_f32_16x16x32_bf16 v[62:65], v[160:163], v[214:217], v[62:65]
	v_mfma_f32_16x16x32_bf16 v[58:61], v[168:171], v[214:217], v[58:61]
	v_mfma_f32_16x16x32_bf16 v[46:49], v[160:163], v[222:225], v[46:49]
	v_mfma_f32_16x16x32_bf16 v[42:45], v[168:171], v[222:225], v[42:45]
	v_mfma_f32_16x16x32_bf16 v[30:33], v[160:163], v[230:233], v[30:33]
	v_mfma_f32_16x16x32_bf16 v[26:29], v[168:171], v[230:233], v[26:29]
	v_mfma_f32_16x16x32_bf16 v[14:17], v[160:163], v[238:241], v[14:17]
	v_mfma_f32_16x16x32_bf16 v[10:13], v[168:171], v[238:241], v[10:13]
	v_mfma_f32_16x16x32_bf16 v[62:65], v[164:167], v[218:221], v[62:65]
	v_mfma_f32_16x16x32_bf16 v[58:61], v[172:175], v[218:221], v[58:61]
	v_mfma_f32_16x16x32_bf16 v[46:49], v[164:167], v[226:229], v[46:49]
	v_mfma_f32_16x16x32_bf16 v[42:45], v[172:175], v[226:229], v[42:45]
	v_mfma_f32_16x16x32_bf16 v[30:33], v[164:167], v[234:237], v[30:33]
	v_mfma_f32_16x16x32_bf16 v[26:29], v[172:175], v[234:237], v[26:29]
	v_mfma_f32_16x16x32_bf16 v[14:17], v[164:167], v[242:245], v[14:17]
	v_mfma_f32_16x16x32_bf16 v[10:13], v[172:175], v[242:245], v[10:13]
	s_setprio 0
	s_setprio 1
	v_mfma_f32_16x16x32_bf16 v[54:57], v[176:179], v[214:217], v[54:57]
	v_mfma_f32_16x16x32_bf16 v[50:53], v[206:209], v[214:217], v[50:53]
	v_mfma_f32_16x16x32_bf16 v[38:41], v[176:179], v[222:225], v[38:41]
	v_mfma_f32_16x16x32_bf16 v[34:37], v[206:209], v[222:225], v[34:37]
	v_mfma_f32_16x16x32_bf16 v[22:25], v[176:179], v[230:233], v[22:25]
	v_mfma_f32_16x16x32_bf16 v[18:21], v[206:209], v[230:233], v[18:21]
	v_mfma_f32_16x16x32_bf16 v[6:9], v[176:179], v[238:241], v[6:9]
	v_mfma_f32_16x16x32_bf16 v[2:5], v[206:209], v[238:241], v[2:5]
	v_mfma_f32_16x16x32_bf16 v[54:57], v[202:205], v[218:221], v[54:57]
	v_mfma_f32_16x16x32_bf16 v[50:53], v[210:213], v[218:221], v[50:53]
	v_mfma_f32_16x16x32_bf16 v[38:41], v[202:205], v[226:229], v[38:41]
	v_mfma_f32_16x16x32_bf16 v[34:37], v[210:213], v[226:229], v[34:37]
	v_mfma_f32_16x16x32_bf16 v[22:25], v[202:205], v[234:237], v[22:25]
	v_mfma_f32_16x16x32_bf16 v[18:21], v[210:213], v[234:237], v[18:21]
	v_mfma_f32_16x16x32_bf16 v[6:9], v[202:205], v[242:245], v[6:9]
	v_mfma_f32_16x16x32_bf16 v[2:5], v[210:213], v[242:245], v[2:5]
	s_setprio 0
	s_add_i32 s50, s50, 2
	s_add_u32 s4, s4, 0x100
	s_addc_u32 s5, s5, 0
	s_add_u32 s43, s43, 0x100
	s_addc_u32 s45, s45, 0
	s_cmp_gt_u32 s50, 29
	s_barrier
	s_cbranch_scc0 .LBB0_709
	s_and_b64 vcc, exec, s[24:25]
	s_cbranch_vccz .LBB0_712
	s_barrier

; #define PG8_STAGE(bufoff, gbase, voff) do { _Pragma("unroll") for (int _i = 0; _i < 2; ++_i) \
;         __builtin_amdgcn_global_load_lds((const unsigned*)((const char*)(gbase) + (voff)[_i]), (PG8_LAS unsigned*)(lds + (bufoff) + ldsw + _i * 8192), 16, 0, 0); } while (0)
; #define PG8_STAGEB(bufoff, gbase, voff) do { _Pragma("unroll") for (int _i = 0; _i < 2; ++_i) \
;         __builtin_amdgcn_global_load_lds((const unsigned*)((const char*)(gbase) + (voff)[_i]), (PG8_LAS unsigned*)(lds + (bufoff) + ldsw + _i * 8192), 16, 0, PG8_BAUX); } while (0)
; #define PG8_LDA(dst, b, h) do { _Pragma("unroll") for (int m = 0; m < 4; ++m) _Pragma("unroll") for (int k = 0; k < 2; ++k) dst[m][k] = *(const PG8_LAS bf16x8*)(lds + PG8_SA(b, h) + aoff + m * 2048 + k * 1024); } while (0)
; #define PG8_LDB(dst, b, h) do { _Pragma("unroll") for (int n = 0; n < 2; ++n) _Pragma("unroll") for (int k = 0; k < 2; ++k) dst[n][k] = *(const PG8_LAS bf16x8*)(lds + PG8_SB(b, h) + boff + n * 2048 + k * 1024); } while (0)
; #define PG8_MMA(ai, bj, At, Bt) do { __builtin_amdgcn_s_setprio(1); _Pragma("unroll") for (int m = 0; m < 4; ++m) _Pragma("unroll") for (int n = 0; n < 2; ++n) _Pragma("unroll") for (int k = 0; k < 2; ++k) \
;         acc[ai][bj][m][n] = __builtin_amdgcn_mfma_f32_16x16x32_bf16(Bt[n][k], At[m][k], acc[ai][bj][m][n], 0, 0, 0); __builtin_amdgcn_s_setprio(0); } while (0)
; template <class Epi, class Sched, bool ALIGN_EPI = false, bool SP2 = false>
; __device__ __forceinline__ void gemm_phase(PG8_LAS unsigned char* lds, const Gemm g, const Sched& S, const Epi& E) {
;     ...
;             const bool last = (t == nt - 2);
;             const char* a1 = cA + (size_t)(t + 1) * kstep;
;             const char* a2 = last ? nA : cA + (size_t)(t + 2) * kstep; const char* b2 = last ? nB : cB + (size_t)(t + 2) * kstep;
;             const char* a3 = a2 + kstep; const char* b3 = b2 + kstep;
;             if (last && has_next) S.a_ready(nxt);
;             if constexpr (SP2) {
;             PG8_LDB(B0, 0, 0); PG8_LDB(B1, 0, 1); PG8_SCHED; PG8_LDA(At, 0, 0); PG8_STAGE(PG8_SA(1, 1), a1 + hstep, voffA);
;             PG8_WAIT_V(8); PG8_WAIT_L(0); PG8_BAR; PG8_MMA(0, 0, At, B0); PG8_MMA(0, 1, At, B1); PG8_BAR; PG8_SCHED;
;             PG8_LDA(At, 0, 1); PG8_STAGEB(PG8_SB(0, 0), b2, voffB); PG8_STAGEB(PG8_SB(0, 1), b2 + hstep, voffB); PG8_STAGE(PG8_SA(0, 0), a2, voffA);
.LBB0_952:
	ds_read_b128 v[150:153], v139
	ds_read_b128 v[154:157], v139 offset:1024
	ds_read_b128 v[158:161], v139 offset:2048
	ds_read_b128 v[162:165], v139 offset:3072
	ds_read_b128 v[166:169], v145
	ds_read_b128 v[170:173], v145 offset:1024
	ds_read_b128 v[174:177], v145 offset:2048
	ds_read_b128 v[178:181], v145 offset:3072
	s_add_u32 s10, s6, s8
	s_addc_u32 s11, s7, s9
	s_add_u32 s10, s10, 0x8700100
	s_addc_u32 s11, s11, 0
	s_add_u32 s45, s29, s8
	s_addc_u32 s46, s30, s9
	s_cmpk_eq_i32 s8, 0x300
	s_cselect_b32 s15, s3, s11
	s_cselect_b32 s14, s2, s10
	s_cselect_b32 s11, s1, s46
	s_cselect_b32 s10, s0, s45
	s_mov_b32 m0, s33
	v_lshl_add_u64 v[216:217], v[140:141], 0, s[8:9]
	ds_read_b128 v[182:185], v146
	ds_read_b128 v[186:189], v146 offset:1024
	ds_read_b128 v[192:195], v146 offset:2048
	ds_read_b128 v[196:199], v146 offset:3072
	ds_read_b128 v[200:203], v146 offset:4096
	ds_read_b128 v[204:207], v146 offset:5120
	ds_read_b128 v[208:211], v146 offset:6144
	ds_read_b128 v[212:215], v146 offset:7168
	global_load_lds_dwordx4 v[216:217], off
	v_lshl_add_u64 v[216:217], v[142:143], 0, s[8:9]
	s_mov_b32 m0, s34
	s_nop 0
	global_load_lds_dwordx4 v[216:217], off
	s_waitcnt vmcnt(8)
	s_waitcnt lgkmcnt(0)
	s_barrier
	s_setprio 1
	s_waitcnt lgkmcnt(0)
	v_mfma_f32_16x16x32_bf16 v[126:129], v[150:153], v[182:185], v[126:129]
	v_mfma_f32_16x16x32_bf16 v[122:125], v[158:161], v[182:185], v[122:125]
	v_mfma_f32_16x16x32_bf16 v[118:121], v[150:153], v[192:195], v[118:121]
	v_mfma_f32_16x16x32_bf16 v[114:117], v[158:161], v[192:195], v[114:117]
	v_mfma_f32_16x16x32_bf16 v[102:105], v[150:153], v[200:203], v[102:105]
	v_mfma_f32_16x16x32_bf16 v[98:101], v[158:161], v[200:203], v[98:101]
	v_mfma_f32_16x16x32_bf16 v[86:89], v[150:153], v[208:211], v[86:89]
	v_mfma_f32_16x16x32_bf16 v[82:85], v[158:161], v[208:211], v[82:85]
	v_mfma_f32_16x16x32_bf16 v[126:129], v[154:157], v[186:189], v[126:129]
	v_mfma_f32_16x16x32_bf16 v[122:125], v[162:165], v[186:189], v[122:125]
	v_mfma_f32_16x16x32_bf16 v[118:121], v[154:157], v[196:199], v[118:121]
	v_mfma_f32_16x16x32_bf16 v[114:117], v[162:165], v[196:199], v[114:117]
	v_mfma_f32_16x16x32_bf16 v[102:105], v[154:157], v[204:207], v[102:105]
	v_mfma_f32_16x16x32_bf16 v[98:101], v[162:165], v[204:207], v[98:101]
	v_mfma_f32_16x16x32_bf16 v[86:89], v[154:157], v[212:215], v[86:89]
	v_mfma_f32_16x16x32_bf16 v[82:85], v[162:165], v[212:215], v[82:85]
	s_setprio 0
	s_setprio 1
	v_mfma_f32_16x16x32_bf16 v[110:113], v[166:169], v[182:185], v[110:113]
	v_mfma_f32_16x16x32_bf16 v[106:109], v[174:177], v[182:185], v[106:109]
	v_mfma_f32_16x16x32_bf16 v[94:97], v[166:169], v[192:195], v[94:97]
	v_mfma_f32_16x16x32_bf16 v[90:93], v[174:177], v[192:195], v[90:93]
	v_mfma_f32_16x16x32_bf16 v[78:81], v[166:169], v[200:203], v[78:81]
	v_mfma_f32_16x16x32_bf16 v[74:77], v[174:177], v[200:203], v[74:77]
	v_mfma_f32_16x16x32_bf16 v[70:73], v[166:169], v[208:211], v[70:73]
	v_mfma_f32_16x16x32_bf16 v[66:69], v[174:177], v[208:211], v[66:69]
	v_mfma_f32_16x16x32_bf16 v[110:113], v[170:173], v[186:189], v[110:113]
	v_mfma_f32_16x16x32_bf16 v[106:109], v[178:181], v[186:189], v[106:109]
	v_mfma_f32_16x16x32_bf16 v[94:97], v[170:173], v[196:199], v[94:97]
	v_mfma_f32_16x16x32_bf16 v[90:93], v[178:181], v[196:199], v[90:93]
	v_mfma_f32_16x16x32_bf16 v[78:81], v[170:173], v[204:207], v[78:81]
	v_mfma_f32_16x16x32_bf16 v[74:77], v[178:181], v[204:207], v[74:77]
	v_mfma_f32_16x16x32_bf16 v[70:73], v[170:173], v[212:215], v[70:73]
	v_mfma_f32_16x16x32_bf16 v[66:69], v[178:181], v[212:215], v[66:69]
	s_setprio 0
	s_barrier
	s_mov_b32 m0, s35
	v_lshl_add_u64 v[216:217], s[10:11], 0, v[134:135]
	s_add_u32 s46, s10, 0x20000
	ds_read_b128 v[182:185], v146 offset:16384
	ds_read_b128 v[186:189], v146 offset:17408
	ds_read_b128 v[192:195], v146 offset:18432
	ds_read_b128 v[196:199], v146 offset:19456
	ds_read_b128 v[200:203], v146 offset:20480
	ds_read_b128 v[204:207], v146 offset:21504
	ds_read_b128 v[208:211], v146 offset:22528
	ds_read_b128 v[212:215], v146 offset:23552
	global_load_lds_dwordx4 v[216:217], off
	v_lshl_add_u64 v[218:219], s[10:11], 0, v[130:131]
	s_mov_b32 m0, s38
	s_addc_u32 s47, s11, 0
	global_load_lds_dwordx4 v[218:219], off
	v_lshl_add_u64 v[220:221], s[46:47], 0, v[134:135]
	s_mov_b32 m0, s39
	v_lshl_add_u64 v[222:223], s[14:15], 0, v[132:133]
	global_load_lds_dwordx4 v[220:221], off
	v_lshl_add_u64 v[220:221], s[46:47], 0, v[130:131]
	s_mov_b32 m0, s40
	s_nop 0
	global_load_lds_dwordx4 v[220:221], off
	v_lshl_add_u64 v[220:221], s[14:15], 0, v[136:137]
	s_mov_b32 m0, s22
	s_nop 0
	global_load_lds_dwordx4 v[220:221], off
	s_mov_b32 m0, s23
	s_nop 0
	global_load_lds_dwordx4 v[222:223], off
	s_waitcnt vmcnt(8)
	s_waitcnt lgkmcnt(0)
	s_barrier
; #define PG8_STAGE(bufoff, gbase, voff) do { _Pragma("unroll") for (int _i = 0; _i < 2; ++_i) \
;         __builtin_amdgcn_global_load_lds((const unsigned*)((const char*)(gbase) + (voff)[_i]), (PG8_LAS unsigned*)(lds + (bufoff) + ldsw + _i * 8192), 16, 0, 0); } while (0)
; #define PG8_LDA(dst, b, h) do { _Pragma("unroll") for (int m = 0; m < 4; ++m) _Pragma("unroll") for (int k = 0; k < 2; ++k) dst[m][k] = *(const PG8_LAS bf16x8*)(lds + PG8_SA(b, h) + aoff + m * 2048 + k * 1024); } while (0)
; #define PG8_LDB(dst, b, h) do { _Pragma("unroll") for (int n = 0; n < 2; ++n) _Pragma("unroll") for (int k = 0; k < 2; ++k) dst[n][k] = *(const PG8_LAS bf16x8*)(lds + PG8_SB(b, h) + boff + n * 2048 + k * 1024); } while (0)
; #define PG8_MMA(ai, bj, At, Bt) do { __builtin_amdgcn_s_setprio(1); _Pragma("unroll") for (int m = 0; m < 4; ++m) _Pragma("unroll") for (int n = 0; n < 2; ++n) _Pragma("unroll") for (int k = 0; k < 2; ++k) \
;         acc[ai][bj][m][n] = __builtin_amdgcn_mfma_f32_16x16x32_bf16(Bt[n][k], At[m][k], acc[ai][bj][m][n], 0, 0, 0); __builtin_amdgcn_s_setprio(0); } while (0)
; #define PG8_WAIT_V(n) asm volatile("s_waitcnt vmcnt(" #n ")" ::: "memory")
; #define PG8_WAIT_L(n) asm volatile("s_waitcnt lgkmcnt(" #n ")" ::: "memory")
; #define PG8_BAR __builtin_amdgcn_s_barrier()
; #define PG8_SCHED __builtin_amdgcn_sched_barrier(0)
; template <class Epi, class Sched, bool ALIGN_EPI = false, bool SP2 = false>
; __device__ __forceinline__ void gemm_phase(PG8_LAS unsigned char* lds, const Gemm g, const Sched& S, const Epi& E) {
;     ...
;             PG8_WAIT_V(8); PG8_WAIT_L(0); PG8_BAR; PG8_MMA(1, 0, At, B0); PG8_MMA(1, 1, At, B1); PG8_BAR; PG8_SCHED;
;             PG8_LDB(B0, 1, 0); PG8_LDB(B1, 1, 1); PG8_SCHED; PG8_LDA(At, 1, 0); PG8_STAGE(PG8_SA(0, 1), a2 + hstep, voffA);
;             PG8_WAIT_V(8); PG8_WAIT_L(0); PG8_BAR; PG8_MMA(0, 0, At, B0); PG8_MMA(0, 1, At, B1); PG8_BAR; PG8_SCHED;
	s_setprio 1
	s_waitcnt lgkmcnt(0)
	v_mfma_f32_16x16x32_bf16 v[62:65], v[150:153], v[182:185], v[62:65]
	v_mfma_f32_16x16x32_bf16 v[58:61], v[158:161], v[182:185], v[58:61]
	v_mfma_f32_16x16x32_bf16 v[54:57], v[150:153], v[192:195], v[54:57]
	v_mfma_f32_16x16x32_bf16 v[50:53], v[158:161], v[192:195], v[50:53]
	v_mfma_f32_16x16x32_bf16 v[38:41], v[150:153], v[200:203], v[38:41]
	v_mfma_f32_16x16x32_bf16 v[34:37], v[158:161], v[200:203], v[34:37]
	v_mfma_f32_16x16x32_bf16 v[22:25], v[150:153], v[208:211], v[22:25]
	v_mfma_f32_16x16x32_bf16 v[18:21], v[158:161], v[208:211], v[18:21]
	v_mfma_f32_16x16x32_bf16 v[62:65], v[154:157], v[186:189], v[62:65]
	v_mfma_f32_16x16x32_bf16 v[58:61], v[162:165], v[186:189], v[58:61]
	v_mfma_f32_16x16x32_bf16 v[54:57], v[154:157], v[196:199], v[54:57]
	v_mfma_f32_16x16x32_bf16 v[50:53], v[162:165], v[196:199], v[50:53]
	v_mfma_f32_16x16x32_bf16 v[38:41], v[154:157], v[204:207], v[38:41]
	v_mfma_f32_16x16x32_bf16 v[34:37], v[162:165], v[204:207], v[34:37]
	v_mfma_f32_16x16x32_bf16 v[22:25], v[154:157], v[212:215], v[22:25]
	v_mfma_f32_16x16x32_bf16 v[18:21], v[162:165], v[212:215], v[18:21]
	s_setprio 0
	s_setprio 1
	v_mfma_f32_16x16x32_bf16 v[46:49], v[166:169], v[182:185], v[46:49]
	v_mfma_f32_16x16x32_bf16 v[42:45], v[174:177], v[182:185], v[42:45]
	v_mfma_f32_16x16x32_bf16 v[30:33], v[166:169], v[192:195], v[30:33]
	v_mfma_f32_16x16x32_bf16 v[26:29], v[174:177], v[192:195], v[26:29]
	v_mfma_f32_16x16x32_bf16 v[14:17], v[166:169], v[200:203], v[14:17]
	v_mfma_f32_16x16x32_bf16 v[10:13], v[174:177], v[200:203], v[10:13]
	v_mfma_f32_16x16x32_bf16 v[6:9], v[166:169], v[208:211], v[6:9]
	v_mfma_f32_16x16x32_bf16 v[2:5], v[174:177], v[208:211], v[2:5]
	v_mfma_f32_16x16x32_bf16 v[46:49], v[170:173], v[186:189], v[46:49]
	v_mfma_f32_16x16x32_bf16 v[42:45], v[178:181], v[186:189], v[42:45]
	v_mfma_f32_16x16x32_bf16 v[30:33], v[170:173], v[196:199], v[30:33]
	v_mfma_f32_16x16x32_bf16 v[26:29], v[178:181], v[196:199], v[26:29]
	v_mfma_f32_16x16x32_bf16 v[14:17], v[170:173], v[204:207], v[14:17]
	v_mfma_f32_16x16x32_bf16 v[10:13], v[178:181], v[204:207], v[10:13]
	v_mfma_f32_16x16x32_bf16 v[6:9], v[170:173], v[212:215], v[6:9]
	v_mfma_f32_16x16x32_bf16 v[2:5], v[178:181], v[212:215], v[2:5]
	s_setprio 0
	s_barrier
	ds_read_b128 v[150:153], v147
	ds_read_b128 v[154:157], v147 offset:1024
	ds_read_b128 v[158:161], v147 offset:2048
	ds_read_b128 v[162:165], v147 offset:3072
	ds_read_b128 v[166:169], v148
	ds_read_b128 v[170:173], v148 offset:1024
	ds_read_b128 v[174:177], v148 offset:2048
	ds_read_b128 v[178:181], v148 offset:3072
	s_add_u32 s14, s14, 0x20000
	s_addc_u32 s15, s15, 0
	s_mov_b32 m0, s24
	v_lshl_add_u64 v[224:225], s[14:15], 0, v[136:137]
	ds_read_b128 v[182:185], v146 offset:32768
	ds_read_b128 v[186:189], v146 offset:33792
	ds_read_b128 v[192:195], v146 offset:34816
	ds_read_b128 v[196:199], v146 offset:35840
	ds_read_b128 v[200:203], v146 offset:36864
	ds_read_b128 v[204:207], v146 offset:37888
	ds_read_b128 v[208:211], v146 offset:38912
	ds_read_b128 v[212:215], v146 offset:39936
	global_load_lds_dwordx4 v[224:225], off
	v_lshl_add_u64 v[224:225], s[14:15], 0, v[132:133]
	s_mov_b32 m0, s25
	s_nop 0
	global_load_lds_dwordx4 v[224:225], off
	s_waitcnt vmcnt(8)
	s_waitcnt lgkmcnt(0)
	s_barrier
	s_setprio 1
	s_waitcnt lgkmcnt(0)
	v_mfma_f32_16x16x32_bf16 v[126:129], v[150:153], v[182:185], v[126:129]
	v_mfma_f32_16x16x32_bf16 v[122:125], v[158:161], v[182:185], v[122:125]
	v_mfma_f32_16x16x32_bf16 v[118:121], v[150:153], v[192:195], v[118:121]
	v_mfma_f32_16x16x32_bf16 v[114:117], v[158:161], v[192:195], v[114:117]
	v_mfma_f32_16x16x32_bf16 v[102:105], v[150:153], v[200:203], v[102:105]
	v_mfma_f32_16x16x32_bf16 v[98:101], v[158:161], v[200:203], v[98:101]
	v_mfma_f32_16x16x32_bf16 v[86:89], v[150:153], v[208:211], v[86:89]
	v_mfma_f32_16x16x32_bf16 v[82:85], v[158:161], v[208:211], v[82:85]
	v_mfma_f32_16x16x32_bf16 v[126:129], v[154:157], v[186:189], v[126:129]
	v_mfma_f32_16x16x32_bf16 v[122:125], v[162:165], v[186:189], v[122:125]
	v_mfma_f32_16x16x32_bf16 v[118:121], v[154:157], v[196:199], v[118:121]
	v_mfma_f32_16x16x32_bf16 v[114:117], v[162:165], v[196:199], v[114:117]
	v_mfma_f32_16x16x32_bf16 v[102:105], v[154:157], v[204:207], v[102:105]
	v_mfma_f32_16x16x32_bf16 v[98:101], v[162:165], v[204:207], v[98:101]
	v_mfma_f32_16x16x32_bf16 v[86:89], v[154:157], v[212:215], v[86:89]
	v_mfma_f32_16x16x32_bf16 v[82:85], v[162:165], v[212:215], v[82:85]
	s_setprio 0
	s_setprio 1
	v_mfma_f32_16x16x32_bf16 v[110:113], v[166:169], v[182:185], v[110:113]
	v_mfma_f32_16x16x32_bf16 v[106:109], v[174:177], v[182:185], v[106:109]
	v_mfma_f32_16x16x32_bf16 v[94:97], v[166:169], v[192:195], v[94:97]
	v_mfma_f32_16x16x32_bf16 v[90:93], v[174:177], v[192:195], v[90:93]
	v_mfma_f32_16x16x32_bf16 v[78:81], v[166:169], v[200:203], v[78:81]
	v_mfma_f32_16x16x32_bf16 v[74:77], v[174:177], v[200:203], v[74:77]
	v_mfma_f32_16x16x32_bf16 v[70:73], v[166:169], v[208:211], v[70:73]
	v_mfma_f32_16x16x32_bf16 v[66:69], v[174:177], v[208:211], v[66:69]
	v_mfma_f32_16x16x32_bf16 v[110:113], v[170:173], v[186:189], v[110:113]
	v_mfma_f32_16x16x32_bf16 v[106:109], v[178:181], v[186:189], v[106:109]
	v_mfma_f32_16x16x32_bf16 v[94:97], v[170:173], v[196:199], v[94:97]
	v_mfma_f32_16x16x32_bf16 v[90:93], v[178:181], v[196:199], v[90:93]
	v_mfma_f32_16x16x32_bf16 v[78:81], v[170:173], v[204:207], v[78:81]
	v_mfma_f32_16x16x32_bf16 v[74:77], v[178:181], v[204:207], v[74:77]
	v_mfma_f32_16x16x32_bf16 v[70:73], v[170:173], v[212:215], v[70:73]
	v_mfma_f32_16x16x32_bf16 v[66:69], v[178:181], v[212:215], v[66:69]
	s_setprio 0
	s_barrier
; #define PG8_STAGE(bufoff, gbase, voff) do { _Pragma("unroll") for (int _i = 0; _i < 2; ++_i) \
;         __builtin_amdgcn_global_load_lds((const unsigned*)((const char*)(gbase) + (voff)[_i]), (PG8_LAS unsigned*)(lds + (bufoff) + ldsw + _i * 8192), 16, 0, 0); } while (0)
; #define PG8_STAGEB(bufoff, gbase, voff) do { _Pragma("unroll") for (int _i = 0; _i < 2; ++_i) \
;         __builtin_amdgcn_global_load_lds((const unsigned*)((const char*)(gbase) + (voff)[_i]), (PG8_LAS unsigned*)(lds + (bufoff) + ldsw + _i * 8192), 16, 0, PG8_BAUX); } while (0)
; #define PG8_LDA(dst, b, h) do { _Pragma("unroll") for (int m = 0; m < 4; ++m) _Pragma("unroll") for (int k = 0; k < 2; ++k) dst[m][k] = *(const PG8_LAS bf16x8*)(lds + PG8_SA(b, h) + aoff + m * 2048 + k * 1024); } while (0)
; #define PG8_MMA(ai, bj, At, Bt) do { __builtin_amdgcn_s_setprio(1); _Pragma("unroll") for (int m = 0; m < 4; ++m) _Pragma("unroll") for (int n = 0; n < 2; ++n) _Pragma("unroll") for (int k = 0; k < 2; ++k) \
;         acc[ai][bj][m][n] = __builtin_amdgcn_mfma_f32_16x16x32_bf16(Bt[n][k], At[m][k], acc[ai][bj][m][n], 0, 0, 0); __builtin_amdgcn_s_setprio(0); } while (0)
; #define PG8_WAIT_V(n) asm volatile("s_waitcnt vmcnt(" #n ")" ::: "memory")
; #define PG8_WAIT_L(n) asm volatile("s_waitcnt lgkmcnt(" #n ")" ::: "memory")
; #define PG8_BAR __builtin_amdgcn_s_barrier()
; #define PG8_SCHED __builtin_amdgcn_sched_barrier(0)
; template <class Epi, class Sched, bool ALIGN_EPI = false, bool SP2 = false>
; __device__ __forceinline__ void gemm_phase(PG8_LAS unsigned char* lds, const Gemm g, const Sched& S, const Epi& E) {
;     ...
;         for (int t = 0; t < nt; t += 2) {
;     ...
;             PG8_LDA(At, 1, 1); PG8_STAGEB(PG8_SB(1, 0), b3, voffB); PG8_STAGEB(PG8_SB(1, 1), b3 + hstep, voffB); PG8_STAGE(PG8_SA(1, 0), a3, voffA);
;             PG8_WAIT_V(8); PG8_WAIT_L(0); PG8_BAR; PG8_MMA(1, 0, At, B0); PG8_MMA(1, 1, At, B1); PG8_BAR; PG8_SCHED;
	s_mov_b32 m0, s41
	v_lshl_add_u64 v[216:217], v[216:217], 0, s[4:5]
	s_add_u32 s10, s10, 0x20080
	ds_read_b128 v[182:185], v146 offset:49152
	ds_read_b128 v[186:189], v146 offset:50176
	ds_read_b128 v[192:195], v146 offset:51200
	ds_read_b128 v[196:199], v146 offset:52224
	ds_read_b128 v[200:203], v146 offset:53248
	ds_read_b128 v[204:207], v146 offset:54272
	ds_read_b128 v[208:211], v146 offset:55296
	ds_read_b128 v[212:215], v146 offset:56320
	global_load_lds_dwordx4 v[216:217], off
	v_lshl_add_u64 v[216:217], v[218:219], 0, s[4:5]
	s_mov_b32 m0, s42
	s_addc_u32 s11, s11, 0
	global_load_lds_dwordx4 v[216:217], off
	v_lshl_add_u64 v[216:217], s[10:11], 0, v[134:135]
	s_mov_b32 m0, s43
	s_nop 0
	global_load_lds_dwordx4 v[216:217], off
	v_lshl_add_u64 v[216:217], s[10:11], 0, v[130:131]
	s_mov_b32 m0, s44
	s_nop 0
	global_load_lds_dwordx4 v[216:217], off
	v_lshl_add_u64 v[216:217], v[220:221], 0, s[4:5]
	s_mov_b32 m0, s27
	s_nop 0
	global_load_lds_dwordx4 v[216:217], off
	v_lshl_add_u64 v[216:217], v[222:223], 0, s[4:5]
	s_mov_b32 m0, s28
	s_nop 0
	global_load_lds_dwordx4 v[216:217], off
	s_waitcnt vmcnt(8)
	s_waitcnt lgkmcnt(0)
	s_barrier
	s_setprio 1
	s_waitcnt lgkmcnt(0)
	v_mfma_f32_16x16x32_bf16 v[62:65], v[150:153], v[182:185], v[62:65]
	v_mfma_f32_16x16x32_bf16 v[58:61], v[158:161], v[182:185], v[58:61]
	v_mfma_f32_16x16x32_bf16 v[54:57], v[150:153], v[192:195], v[54:57]
	v_mfma_f32_16x16x32_bf16 v[50:53], v[158:161], v[192:195], v[50:53]
	v_mfma_f32_16x16x32_bf16 v[38:41], v[150:153], v[200:203], v[38:41]
	v_mfma_f32_16x16x32_bf16 v[34:37], v[158:161], v[200:203], v[34:37]
	v_mfma_f32_16x16x32_bf16 v[22:25], v[150:153], v[208:211], v[22:25]
	v_mfma_f32_16x16x32_bf16 v[18:21], v[158:161], v[208:211], v[18:21]
	v_mfma_f32_16x16x32_bf16 v[62:65], v[154:157], v[186:189], v[62:65]
	v_mfma_f32_16x16x32_bf16 v[58:61], v[162:165], v[186:189], v[58:61]
	v_mfma_f32_16x16x32_bf16 v[54:57], v[154:157], v[196:199], v[54:57]
	v_mfma_f32_16x16x32_bf16 v[50:53], v[162:165], v[196:199], v[50:53]
	v_mfma_f32_16x16x32_bf16 v[38:41], v[154:157], v[204:207], v[38:41]
	v_mfma_f32_16x16x32_bf16 v[34:37], v[162:165], v[204:207], v[34:37]
	v_mfma_f32_16x16x32_bf16 v[22:25], v[154:157], v[212:215], v[22:25]
	v_mfma_f32_16x16x32_bf16 v[18:21], v[162:165], v[212:215], v[18:21]
	s_setprio 0
	s_setprio 1
	v_mfma_f32_16x16x32_bf16 v[46:49], v[166:169], v[182:185], v[46:49]
	v_mfma_f32_16x16x32_bf16 v[42:45], v[174:177], v[182:185], v[42:45]
	v_mfma_f32_16x16x32_bf16 v[30:33], v[166:169], v[192:195], v[30:33]
	v_mfma_f32_16x16x32_bf16 v[26:29], v[174:177], v[192:195], v[26:29]
	v_mfma_f32_16x16x32_bf16 v[14:17], v[166:169], v[200:203], v[14:17]
	v_mfma_f32_16x16x32_bf16 v[10:13], v[174:177], v[200:203], v[10:13]
	v_mfma_f32_16x16x32_bf16 v[6:9], v[166:169], v[208:211], v[6:9]
	v_mfma_f32_16x16x32_bf16 v[2:5], v[174:177], v[208:211], v[2:5]
	v_mfma_f32_16x16x32_bf16 v[46:49], v[170:173], v[186:189], v[46:49]
	v_mfma_f32_16x16x32_bf16 v[42:45], v[178:181], v[186:189], v[42:45]
	v_mfma_f32_16x16x32_bf16 v[30:33], v[170:173], v[196:199], v[30:33]
	v_mfma_f32_16x16x32_bf16 v[26:29], v[178:181], v[196:199], v[26:29]
	v_mfma_f32_16x16x32_bf16 v[14:17], v[170:173], v[204:207], v[14:17]
	v_mfma_f32_16x16x32_bf16 v[10:13], v[178:181], v[204:207], v[10:13]
	v_mfma_f32_16x16x32_bf16 v[6:9], v[170:173], v[212:215], v[6:9]
	v_mfma_f32_16x16x32_bf16 v[2:5], v[178:181], v[212:215], v[2:5]
	s_setprio 0
	s_add_i32 s31, s31, 2
	s_add_u32 s8, s8, 0x100
	s_addc_u32 s9, s9, 0
	s_cmp_gt_u32 s31, 5
	s_barrier
	s_cbranch_scc0 .LBB0_952
	s_cmpk_lt_u32 s20, 0x100
	s_cbranch_scc0 .LBB0_955
	s_barrier

; #define PG8_STAGE(bufoff, gbase, voff) do { _Pragma("unroll") for (int _i = 0; _i < 2; ++_i) \
;         __builtin_amdgcn_global_load_lds((const unsigned*)((const char*)(gbase) + (voff)[_i]), (PG8_LAS unsigned*)(lds + (bufoff) + ldsw + _i * 8192), 16, 0, 0); } while (0)
; #define PG8_STAGEB(bufoff, gbase, voff) do { _Pragma("unroll") for (int _i = 0; _i < 2; ++_i) \
;         __builtin_amdgcn_global_load_lds((const unsigned*)((const char*)(gbase) + (voff)[_i]), (PG8_LAS unsigned*)(lds + (bufoff) + ldsw + _i * 8192), 16, 0, PG8_BAUX); } while (0)
; #define PG8_LDA(dst, b, h) do { _Pragma("unroll") for (int m = 0; m < 4; ++m) _Pragma("unroll") for (int k = 0; k < 2; ++k) dst[m][k] = *(const PG8_LAS bf16x8*)(lds + PG8_SA(b, h) + aoff + m * 2048 + k * 1024); } while (0)
; #define PG8_LDB(dst, b, h) do { _Pragma("unroll") for (int n = 0; n < 2; ++n) _Pragma("unroll") for (int k = 0; k < 2; ++k) dst[n][k] = *(const PG8_LAS bf16x8*)(lds + PG8_SB(b, h) + boff + n * 2048 + k * 1024); } while (0)
; #define PG8_MMA(ai, bj, At, Bt) do { __builtin_amdgcn_s_setprio(1); _Pragma("unroll") for (int m = 0; m < 4; ++m) _Pragma("unroll") for (int n = 0; n < 2; ++n) _Pragma("unroll") for (int k = 0; k < 2; ++k) \
;         acc[ai][bj][m][n] = __builtin_amdgcn_mfma_f32_16x16x32_bf16(Bt[n][k], At[m][k], acc[ai][bj][m][n], 0, 0, 0); __builtin_amdgcn_s_setprio(0); } while (0)
; template <class Epi, class Sched, bool ALIGN_EPI = false, bool SP2 = false>
; __device__ __forceinline__ void gemm_phase(PG8_LAS unsigned char* lds, const Gemm g, const Sched& S, const Epi& E) {
;     ...
;             const bool last = (t == nt - 2);
;             const char* a1 = cA + (size_t)(t + 1) * kstep;
;             const char* a2 = last ? nA : cA + (size_t)(t + 2) * kstep; const char* b2 = last ? nB : cB + (size_t)(t + 2) * kstep;
;             const char* a3 = a2 + kstep; const char* b3 = b2 + kstep;
;             if (last && has_next) S.a_ready(nxt);
;             if constexpr (SP2) {
;             PG8_LDB(B0, 0, 0); PG8_LDB(B1, 0, 1); PG8_SCHED; PG8_LDA(At, 0, 0); PG8_STAGE(PG8_SA(1, 1), a1 + hstep, voffA);
;             PG8_WAIT_V(8); PG8_WAIT_L(0); PG8_BAR; PG8_MMA(0, 0, At, B0); PG8_MMA(0, 1, At, B1); PG8_BAR; PG8_SCHED;
;             PG8_LDA(At, 0, 1); PG8_STAGEB(PG8_SB(0, 0), b2, voffB); PG8_STAGEB(PG8_SB(0, 1), b2 + hstep, voffB); PG8_STAGE(PG8_SA(0, 0), a2, voffA);
.LBB0_1330:
	ds_read_b128 v[160:163], v155
	ds_read_b128 v[164:167], v155 offset:1024
	ds_read_b128 v[168:171], v155 offset:2048
	ds_read_b128 v[172:175], v155 offset:3072
	ds_read_b128 v[180:183], v156
	ds_read_b128 v[184:187], v156 offset:1024
	ds_read_b128 v[192:195], v156 offset:2048
	ds_read_b128 v[196:199], v156 offset:3072
	s_add_u32 s30, s28, 0xfff80080
	s_addc_u32 s31, s29, -1
	s_cmp_eq_u32 s55, 28
	s_cselect_b32 s35, s19, s31
	s_cselect_b32 s34, s25, s30
	s_cselect_b32 s31, s17, s54
	s_cselect_b32 s30, s52, s53
	v_lshl_add_u64 v[148:149], s[28:29], 0, v[140:141]
	s_add_i32 m0, s27, 0xc000
	ds_read_b128 v[200:203], v157
	ds_read_b128 v[204:207], v157 offset:1024
	ds_read_b128 v[208:211], v157 offset:2048
	ds_read_b128 v[212:215], v157 offset:3072
	ds_read_b128 v[216:219], v157 offset:4096
	ds_read_b128 v[220:223], v157 offset:5120
	ds_read_b128 v[224:227], v157 offset:6144
	ds_read_b128 v[228:231], v157 offset:7168
	global_load_lds_dwordx4 v[148:149], off
	v_lshl_add_u64 v[148:149], s[28:29], 0, v[142:143]
	s_add_i32 m0, s27, 0xe000
	s_nop 0
	global_load_lds_dwordx4 v[148:149], off
	s_waitcnt vmcnt(8)
	s_waitcnt lgkmcnt(0)
	s_barrier
	s_setprio 1
	s_waitcnt lgkmcnt(0)
	v_mfma_f32_16x16x32_bf16 v[126:129], v[160:163], v[200:203], v[126:129]
	v_mfma_f32_16x16x32_bf16 v[122:125], v[168:171], v[200:203], v[122:125]
	v_mfma_f32_16x16x32_bf16 v[110:113], v[160:163], v[208:211], v[110:113]
	v_mfma_f32_16x16x32_bf16 v[106:109], v[168:171], v[208:211], v[106:109]
	v_mfma_f32_16x16x32_bf16 v[94:97], v[160:163], v[216:219], v[94:97]
	v_mfma_f32_16x16x32_bf16 v[90:93], v[168:171], v[216:219], v[90:93]
	v_mfma_f32_16x16x32_bf16 v[78:81], v[160:163], v[224:227], v[78:81]
	v_mfma_f32_16x16x32_bf16 v[74:77], v[168:171], v[224:227], v[74:77]
	v_mfma_f32_16x16x32_bf16 v[126:129], v[164:167], v[204:207], v[126:129]
	v_mfma_f32_16x16x32_bf16 v[122:125], v[172:175], v[204:207], v[122:125]
	v_mfma_f32_16x16x32_bf16 v[110:113], v[164:167], v[212:215], v[110:113]
	v_mfma_f32_16x16x32_bf16 v[106:109], v[172:175], v[212:215], v[106:109]
	v_mfma_f32_16x16x32_bf16 v[94:97], v[164:167], v[220:223], v[94:97]
	v_mfma_f32_16x16x32_bf16 v[90:93], v[172:175], v[220:223], v[90:93]
	v_mfma_f32_16x16x32_bf16 v[78:81], v[164:167], v[228:231], v[78:81]
	v_mfma_f32_16x16x32_bf16 v[74:77], v[172:175], v[228:231], v[74:77]
	s_setprio 0
	s_setprio 1
	v_mfma_f32_16x16x32_bf16 v[118:121], v[180:183], v[200:203], v[118:121]
	v_mfma_f32_16x16x32_bf16 v[114:117], v[192:195], v[200:203], v[114:117]
	v_mfma_f32_16x16x32_bf16 v[102:105], v[180:183], v[208:211], v[102:105]
	v_mfma_f32_16x16x32_bf16 v[98:101], v[192:195], v[208:211], v[98:101]
	v_mfma_f32_16x16x32_bf16 v[86:89], v[180:183], v[216:219], v[86:89]
	v_mfma_f32_16x16x32_bf16 v[82:85], v[192:195], v[216:219], v[82:85]
	v_mfma_f32_16x16x32_bf16 v[70:73], v[180:183], v[224:227], v[70:73]
	v_mfma_f32_16x16x32_bf16 v[66:69], v[192:195], v[224:227], v[66:69]
	v_mfma_f32_16x16x32_bf16 v[118:121], v[184:187], v[204:207], v[118:121]
	v_mfma_f32_16x16x32_bf16 v[114:117], v[196:199], v[204:207], v[114:117]
	v_mfma_f32_16x16x32_bf16 v[102:105], v[184:187], v[212:215], v[102:105]
	v_mfma_f32_16x16x32_bf16 v[98:101], v[196:199], v[212:215], v[98:101]
	v_mfma_f32_16x16x32_bf16 v[86:89], v[184:187], v[220:223], v[86:89]
	v_mfma_f32_16x16x32_bf16 v[82:85], v[196:199], v[220:223], v[82:85]
	v_mfma_f32_16x16x32_bf16 v[70:73], v[184:187], v[228:231], v[70:73]
	v_mfma_f32_16x16x32_bf16 v[66:69], v[196:199], v[228:231], v[66:69]
	s_setprio 0
	s_barrier
	s_add_i32 s56, s50, s33
	v_lshl_add_u64 v[148:149], s[30:31], 0, v[132:133]
	s_mov_b32 m0, s56
	ds_read_b128 v[200:203], v157 offset:16384
	ds_read_b128 v[204:207], v157 offset:17408
	ds_read_b128 v[208:211], v157 offset:18432
	ds_read_b128 v[212:215], v157 offset:19456
	ds_read_b128 v[216:219], v157 offset:20480
	ds_read_b128 v[220:223], v157 offset:21504
	ds_read_b128 v[224:227], v157 offset:22528
	ds_read_b128 v[228:231], v157 offset:23552
	global_load_lds_dwordx4 v[148:149], off
	s_add_i32 m0, s56, 0x2000
	s_add_u32 s56, s30, 0x80000
	v_lshl_add_u64 v[176:177], s[30:31], 0, v[136:137]
	s_addc_u32 s57, s31, 0
	s_add_i32 s58, s51, s33
	global_load_lds_dwordx4 v[176:177], off
	v_lshl_add_u64 v[188:189], s[56:57], 0, v[132:133]
	s_mov_b32 m0, s58
	v_lshl_add_u64 v[232:233], s[34:35], 0, v[134:135]
	global_load_lds_dwordx4 v[188:189], off
	v_lshl_add_u64 v[188:189], s[56:57], 0, v[136:137]
	s_add_i32 m0, s58, 0x2000
	s_nop 0
	global_load_lds_dwordx4 v[188:189], off
	v_lshl_add_u64 v[188:189], s[34:35], 0, v[130:131]
	s_mov_b32 m0, s27
	s_nop 0
	global_load_lds_dwordx4 v[188:189], off
	s_mov_b32 m0, s42
	s_nop 0
	global_load_lds_dwordx4 v[232:233], off
	s_waitcnt vmcnt(8)
	s_waitcnt lgkmcnt(0)
	s_barrier
; #define PG8_STAGE(bufoff, gbase, voff) do { _Pragma("unroll") for (int _i = 0; _i < 2; ++_i) \
;         __builtin_amdgcn_global_load_lds((const unsigned*)((const char*)(gbase) + (voff)[_i]), (PG8_LAS unsigned*)(lds + (bufoff) + ldsw + _i * 8192), 16, 0, 0); } while (0)
; #define PG8_LDA(dst, b, h) do { _Pragma("unroll") for (int m = 0; m < 4; ++m) _Pragma("unroll") for (int k = 0; k < 2; ++k) dst[m][k] = *(const PG8_LAS bf16x8*)(lds + PG8_SA(b, h) + aoff + m * 2048 + k * 1024); } while (0)
; #define PG8_LDB(dst, b, h) do { _Pragma("unroll") for (int n = 0; n < 2; ++n) _Pragma("unroll") for (int k = 0; k < 2; ++k) dst[n][k] = *(const PG8_LAS bf16x8*)(lds + PG8_SB(b, h) + boff + n * 2048 + k * 1024); } while (0)
; #define PG8_MMA(ai, bj, At, Bt) do { __builtin_amdgcn_s_setprio(1); _Pragma("unroll") for (int m = 0; m < 4; ++m) _Pragma("unroll") for (int n = 0; n < 2; ++n) _Pragma("unroll") for (int k = 0; k < 2; ++k) \
;         acc[ai][bj][m][n] = __builtin_amdgcn_mfma_f32_16x16x32_bf16(Bt[n][k], At[m][k], acc[ai][bj][m][n], 0, 0, 0); __builtin_amdgcn_s_setprio(0); } while (0)
; #define PG8_WAIT_V(n) asm volatile("s_waitcnt vmcnt(" #n ")" ::: "memory")
; #define PG8_WAIT_L(n) asm volatile("s_waitcnt lgkmcnt(" #n ")" ::: "memory")
; #define PG8_BAR __builtin_amdgcn_s_barrier()
; #define PG8_SCHED __builtin_amdgcn_sched_barrier(0)
; template <class Epi, class Sched, bool ALIGN_EPI = false, bool SP2 = false>
; __device__ __forceinline__ void gemm_phase(PG8_LAS unsigned char* lds, const Gemm g, const Sched& S, const Epi& E) {
;     ...
;             PG8_WAIT_V(8); PG8_WAIT_L(0); PG8_BAR; PG8_MMA(1, 0, At, B0); PG8_MMA(1, 1, At, B1); PG8_BAR; PG8_SCHED;
;             PG8_LDB(B0, 1, 0); PG8_LDB(B1, 1, 1); PG8_SCHED; PG8_LDA(At, 1, 0); PG8_STAGE(PG8_SA(0, 1), a2 + hstep, voffA);
;             PG8_WAIT_V(8); PG8_WAIT_L(0); PG8_BAR; PG8_MMA(0, 0, At, B0); PG8_MMA(0, 1, At, B1); PG8_BAR; PG8_SCHED;
	s_setprio 1
	s_waitcnt lgkmcnt(0)
	v_mfma_f32_16x16x32_bf16 v[62:65], v[160:163], v[200:203], v[62:65]
	v_mfma_f32_16x16x32_bf16 v[58:61], v[168:171], v[200:203], v[58:61]
	v_mfma_f32_16x16x32_bf16 v[46:49], v[160:163], v[208:211], v[46:49]
	v_mfma_f32_16x16x32_bf16 v[42:45], v[168:171], v[208:211], v[42:45]
	v_mfma_f32_16x16x32_bf16 v[30:33], v[160:163], v[216:219], v[30:33]
	v_mfma_f32_16x16x32_bf16 v[26:29], v[168:171], v[216:219], v[26:29]
	v_mfma_f32_16x16x32_bf16 v[14:17], v[160:163], v[224:227], v[14:17]
	v_mfma_f32_16x16x32_bf16 v[10:13], v[168:171], v[224:227], v[10:13]
	v_mfma_f32_16x16x32_bf16 v[62:65], v[164:167], v[204:207], v[62:65]
	v_mfma_f32_16x16x32_bf16 v[58:61], v[172:175], v[204:207], v[58:61]
	v_mfma_f32_16x16x32_bf16 v[46:49], v[164:167], v[212:215], v[46:49]
	v_mfma_f32_16x16x32_bf16 v[42:45], v[172:175], v[212:215], v[42:45]
	v_mfma_f32_16x16x32_bf16 v[30:33], v[164:167], v[220:223], v[30:33]
	v_mfma_f32_16x16x32_bf16 v[26:29], v[172:175], v[220:223], v[26:29]
	v_mfma_f32_16x16x32_bf16 v[14:17], v[164:167], v[228:231], v[14:17]
	v_mfma_f32_16x16x32_bf16 v[10:13], v[172:175], v[228:231], v[10:13]
	s_setprio 0
	s_setprio 1
	v_mfma_f32_16x16x32_bf16 v[54:57], v[180:183], v[200:203], v[54:57]
	v_mfma_f32_16x16x32_bf16 v[50:53], v[192:195], v[200:203], v[50:53]
	v_mfma_f32_16x16x32_bf16 v[38:41], v[180:183], v[208:211], v[38:41]
	v_mfma_f32_16x16x32_bf16 v[34:37], v[192:195], v[208:211], v[34:37]
	v_mfma_f32_16x16x32_bf16 v[22:25], v[180:183], v[216:219], v[22:25]
	v_mfma_f32_16x16x32_bf16 v[18:21], v[192:195], v[216:219], v[18:21]
	v_mfma_f32_16x16x32_bf16 v[6:9], v[180:183], v[224:227], v[6:9]
	v_mfma_f32_16x16x32_bf16 v[2:5], v[192:195], v[224:227], v[2:5]
	v_mfma_f32_16x16x32_bf16 v[54:57], v[184:187], v[204:207], v[54:57]
	v_mfma_f32_16x16x32_bf16 v[50:53], v[196:199], v[204:207], v[50:53]
	v_mfma_f32_16x16x32_bf16 v[38:41], v[184:187], v[212:215], v[38:41]
	v_mfma_f32_16x16x32_bf16 v[34:37], v[196:199], v[212:215], v[34:37]
	v_mfma_f32_16x16x32_bf16 v[22:25], v[184:187], v[220:223], v[22:25]
	v_mfma_f32_16x16x32_bf16 v[18:21], v[196:199], v[220:223], v[18:21]
	v_mfma_f32_16x16x32_bf16 v[6:9], v[184:187], v[228:231], v[6:9]
	v_mfma_f32_16x16x32_bf16 v[2:5], v[196:199], v[228:231], v[2:5]
	s_setprio 0
	s_barrier
	s_add_i32 s56, 0, 0x18000
	v_add_u32_e32 v138, s56, v153
	s_add_i32 s57, 0, 0x1c000
	ds_read_b128 v[160:163], v138
	ds_read_b128 v[164:167], v138 offset:1024
	ds_read_b128 v[168:171], v138 offset:2048
	ds_read_b128 v[172:175], v138 offset:3072
	v_add_u32_e32 v138, s57, v153
	ds_read_b128 v[180:183], v138
	ds_read_b128 v[184:187], v138 offset:1024
	ds_read_b128 v[192:195], v138 offset:2048
	ds_read_b128 v[196:199], v138 offset:3072
	s_add_u32 s34, s34, 0x80000
	s_addc_u32 s35, s35, 0
	s_mov_b32 m0, s43
	v_lshl_add_u64 v[234:235], s[34:35], 0, v[130:131]
	ds_read_b128 v[200:203], v157 offset:32768
	ds_read_b128 v[204:207], v157 offset:33792
	ds_read_b128 v[208:211], v157 offset:34816
	ds_read_b128 v[212:215], v157 offset:35840
	ds_read_b128 v[216:219], v157 offset:36864
	ds_read_b128 v[220:223], v157 offset:37888
	ds_read_b128 v[224:227], v157 offset:38912
	ds_read_b128 v[228:231], v157 offset:39936
	global_load_lds_dwordx4 v[234:235], off
	v_lshl_add_u64 v[234:235], s[34:35], 0, v[134:135]
	s_mov_b32 m0, s44
	s_nop 0
	global_load_lds_dwordx4 v[234:235], off
	s_waitcnt vmcnt(8)
	s_waitcnt lgkmcnt(0)
	s_barrier
	s_setprio 1
	s_waitcnt lgkmcnt(0)
	v_mfma_f32_16x16x32_bf16 v[126:129], v[160:163], v[200:203], v[126:129]
	v_mfma_f32_16x16x32_bf16 v[122:125], v[168:171], v[200:203], v[122:125]
	v_mfma_f32_16x16x32_bf16 v[110:113], v[160:163], v[208:211], v[110:113]
	v_mfma_f32_16x16x32_bf16 v[106:109], v[168:171], v[208:211], v[106:109]
	v_mfma_f32_16x16x32_bf16 v[94:97], v[160:163], v[216:219], v[94:97]
	v_mfma_f32_16x16x32_bf16 v[90:93], v[168:171], v[216:219], v[90:93]
	v_mfma_f32_16x16x32_bf16 v[78:81], v[160:163], v[224:227], v[78:81]
	v_mfma_f32_16x16x32_bf16 v[74:77], v[168:171], v[224:227], v[74:77]
	v_mfma_f32_16x16x32_bf16 v[126:129], v[164:167], v[204:207], v[126:129]
	v_mfma_f32_16x16x32_bf16 v[122:125], v[172:175], v[204:207], v[122:125]
	v_mfma_f32_16x16x32_bf16 v[110:113], v[164:167], v[212:215], v[110:113]
	v_mfma_f32_16x16x32_bf16 v[106:109], v[172:175], v[212:215], v[106:109]
	v_mfma_f32_16x16x32_bf16 v[94:97], v[164:167], v[220:223], v[94:97]
	v_mfma_f32_16x16x32_bf16 v[90:93], v[172:175], v[220:223], v[90:93]
	v_mfma_f32_16x16x32_bf16 v[78:81], v[164:167], v[228:231], v[78:81]
	v_mfma_f32_16x16x32_bf16 v[74:77], v[172:175], v[228:231], v[74:77]
	s_setprio 0
	s_setprio 1
	v_mfma_f32_16x16x32_bf16 v[118:121], v[180:183], v[200:203], v[118:121]
	v_mfma_f32_16x16x32_bf16 v[114:117], v[192:195], v[200:203], v[114:117]
	v_mfma_f32_16x16x32_bf16 v[102:105], v[180:183], v[208:211], v[102:105]
	v_mfma_f32_16x16x32_bf16 v[98:101], v[192:195], v[208:211], v[98:101]
	v_mfma_f32_16x16x32_bf16 v[86:89], v[180:183], v[216:219], v[86:89]
	v_mfma_f32_16x16x32_bf16 v[82:85], v[192:195], v[216:219], v[82:85]
	v_mfma_f32_16x16x32_bf16 v[70:73], v[180:183], v[224:227], v[70:73]
	v_mfma_f32_16x16x32_bf16 v[66:69], v[192:195], v[224:227], v[66:69]
	v_mfma_f32_16x16x32_bf16 v[118:121], v[184:187], v[204:207], v[118:121]
	v_mfma_f32_16x16x32_bf16 v[114:117], v[196:199], v[204:207], v[114:117]
	v_mfma_f32_16x16x32_bf16 v[102:105], v[184:187], v[212:215], v[102:105]
	v_mfma_f32_16x16x32_bf16 v[98:101], v[196:199], v[212:215], v[98:101]
	v_mfma_f32_16x16x32_bf16 v[86:89], v[184:187], v[220:223], v[86:89]
	v_mfma_f32_16x16x32_bf16 v[82:85], v[196:199], v[220:223], v[82:85]
	v_mfma_f32_16x16x32_bf16 v[70:73], v[184:187], v[228:231], v[70:73]
	v_mfma_f32_16x16x32_bf16 v[66:69], v[196:199], v[228:231], v[66:69]
	s_setprio 0
	s_barrier
; #define PG8_STAGE(bufoff, gbase, voff) do { _Pragma("unroll") for (int _i = 0; _i < 2; ++_i) \
;         __builtin_amdgcn_global_load_lds((const unsigned*)((const char*)(gbase) + (voff)[_i]), (PG8_LAS unsigned*)(lds + (bufoff) + ldsw + _i * 8192), 16, 0, 0); } while (0)
; #define PG8_STAGEB(bufoff, gbase, voff) do { _Pragma("unroll") for (int _i = 0; _i < 2; ++_i) \
;         __builtin_amdgcn_global_load_lds((const unsigned*)((const char*)(gbase) + (voff)[_i]), (PG8_LAS unsigned*)(lds + (bufoff) + ldsw + _i * 8192), 16, 0, PG8_BAUX); } while (0)
; #define PG8_LDA(dst, b, h) do { _Pragma("unroll") for (int m = 0; m < 4; ++m) _Pragma("unroll") for (int k = 0; k < 2; ++k) dst[m][k] = *(const PG8_LAS bf16x8*)(lds + PG8_SA(b, h) + aoff + m * 2048 + k * 1024); } while (0)
; #define PG8_MMA(ai, bj, At, Bt) do { __builtin_amdgcn_s_setprio(1); _Pragma("unroll") for (int m = 0; m < 4; ++m) _Pragma("unroll") for (int n = 0; n < 2; ++n) _Pragma("unroll") for (int k = 0; k < 2; ++k) \
;         acc[ai][bj][m][n] = __builtin_amdgcn_mfma_f32_16x16x32_bf16(Bt[n][k], At[m][k], acc[ai][bj][m][n], 0, 0, 0); __builtin_amdgcn_s_setprio(0); } while (0)
; #define PG8_WAIT_V(n) asm volatile("s_waitcnt vmcnt(" #n ")" ::: "memory")
; #define PG8_WAIT_L(n) asm volatile("s_waitcnt lgkmcnt(" #n ")" ::: "memory")
; #define PG8_BAR __builtin_amdgcn_s_barrier()
; #define PG8_SCHED __builtin_amdgcn_sched_barrier(0)
; template <class Epi, class Sched, bool ALIGN_EPI = false, bool SP2 = false>
; __device__ __forceinline__ void gemm_phase(PG8_LAS unsigned char* lds, const Gemm g, const Sched& S, const Epi& E) {
;     ...
;         for (int t = 0; t < nt; t += 2) {
;     ...
;             PG8_LDA(At, 1, 1); PG8_STAGEB(PG8_SB(1, 0), b3, voffB); PG8_STAGEB(PG8_SB(1, 1), b3 + hstep, voffB); PG8_STAGE(PG8_SA(1, 0), a3, voffA);
;             PG8_WAIT_V(8); PG8_WAIT_L(0); PG8_BAR; PG8_MMA(1, 0, At, B0); PG8_MMA(1, 1, At, B1); PG8_BAR; PG8_SCHED;
	s_add_i32 s34, s56, s33
	v_lshl_add_u64 v[148:149], v[148:149], 0, s[12:13]
	s_mov_b32 m0, s34
	ds_read_b128 v[200:203], v157 offset:49152
	ds_read_b128 v[204:207], v157 offset:50176
	ds_read_b128 v[208:211], v157 offset:51200
	ds_read_b128 v[212:215], v157 offset:52224
	ds_read_b128 v[216:219], v157 offset:53248
	ds_read_b128 v[220:223], v157 offset:54272
	ds_read_b128 v[224:227], v157 offset:55296
	ds_read_b128 v[228:231], v157 offset:56320
	global_load_lds_dwordx4 v[148:149], off
	s_add_i32 m0, s34, 0x2000
	s_add_u32 s30, s30, 0x80080
	v_lshl_add_u64 v[148:149], v[176:177], 0, s[12:13]
	s_addc_u32 s31, s31, 0
	s_add_i32 s34, s57, s33
	global_load_lds_dwordx4 v[148:149], off
	v_lshl_add_u64 v[148:149], s[30:31], 0, v[132:133]
	s_mov_b32 m0, s34
	s_nop 0
	global_load_lds_dwordx4 v[148:149], off
	v_lshl_add_u64 v[148:149], s[30:31], 0, v[136:137]
	s_add_i32 m0, s34, 0x2000
	s_nop 0
	global_load_lds_dwordx4 v[148:149], off
	v_lshl_add_u64 v[148:149], v[188:189], 0, s[12:13]
	s_mov_b32 m0, s46
	s_nop 0
	global_load_lds_dwordx4 v[148:149], off
	v_lshl_add_u64 v[148:149], v[232:233], 0, s[12:13]
	s_mov_b32 m0, s47
	s_nop 0
	global_load_lds_dwordx4 v[148:149], off
	s_waitcnt vmcnt(8)
	s_waitcnt lgkmcnt(0)
	s_barrier
	s_setprio 1
	s_waitcnt lgkmcnt(0)
	v_mfma_f32_16x16x32_bf16 v[62:65], v[160:163], v[200:203], v[62:65]
	v_mfma_f32_16x16x32_bf16 v[58:61], v[168:171], v[200:203], v[58:61]
	v_mfma_f32_16x16x32_bf16 v[46:49], v[160:163], v[208:211], v[46:49]
	v_mfma_f32_16x16x32_bf16 v[42:45], v[168:171], v[208:211], v[42:45]
	v_mfma_f32_16x16x32_bf16 v[30:33], v[160:163], v[216:219], v[30:33]
	v_mfma_f32_16x16x32_bf16 v[26:29], v[168:171], v[216:219], v[26:29]
	v_mfma_f32_16x16x32_bf16 v[14:17], v[160:163], v[224:227], v[14:17]
	v_mfma_f32_16x16x32_bf16 v[10:13], v[168:171], v[224:227], v[10:13]
	v_mfma_f32_16x16x32_bf16 v[62:65], v[164:167], v[204:207], v[62:65]
	v_mfma_f32_16x16x32_bf16 v[58:61], v[172:175], v[204:207], v[58:61]
	v_mfma_f32_16x16x32_bf16 v[46:49], v[164:167], v[212:215], v[46:49]
	v_mfma_f32_16x16x32_bf16 v[42:45], v[172:175], v[212:215], v[42:45]
	v_mfma_f32_16x16x32_bf16 v[30:33], v[164:167], v[220:223], v[30:33]
	v_mfma_f32_16x16x32_bf16 v[26:29], v[172:175], v[220:223], v[26:29]
	v_mfma_f32_16x16x32_bf16 v[14:17], v[164:167], v[228:231], v[14:17]
	v_mfma_f32_16x16x32_bf16 v[10:13], v[172:175], v[228:231], v[10:13]
	s_setprio 0
	s_setprio 1
	v_mfma_f32_16x16x32_bf16 v[54:57], v[180:183], v[200:203], v[54:57]
	v_mfma_f32_16x16x32_bf16 v[50:53], v[192:195], v[200:203], v[50:53]
	v_mfma_f32_16x16x32_bf16 v[38:41], v[180:183], v[208:211], v[38:41]
	v_mfma_f32_16x16x32_bf16 v[34:37], v[192:195], v[208:211], v[34:37]
	v_mfma_f32_16x16x32_bf16 v[22:25], v[180:183], v[216:219], v[22:25]
	v_mfma_f32_16x16x32_bf16 v[18:21], v[192:195], v[216:219], v[18:21]
	v_mfma_f32_16x16x32_bf16 v[6:9], v[180:183], v[224:227], v[6:9]
	v_mfma_f32_16x16x32_bf16 v[2:5], v[192:195], v[224:227], v[2:5]
	v_mfma_f32_16x16x32_bf16 v[54:57], v[184:187], v[204:207], v[54:57]
	v_mfma_f32_16x16x32_bf16 v[50:53], v[196:199], v[204:207], v[50:53]
	v_mfma_f32_16x16x32_bf16 v[38:41], v[184:187], v[212:215], v[38:41]
	v_mfma_f32_16x16x32_bf16 v[34:37], v[196:199], v[212:215], v[34:37]
	v_mfma_f32_16x16x32_bf16 v[22:25], v[184:187], v[220:223], v[22:25]
	v_mfma_f32_16x16x32_bf16 v[18:21], v[196:199], v[220:223], v[18:21]
	v_mfma_f32_16x16x32_bf16 v[6:9], v[184:187], v[228:231], v[6:9]
	v_mfma_f32_16x16x32_bf16 v[2:5], v[196:199], v[228:231], v[2:5]
	s_setprio 0
	s_add_i32 s55, s55, 2
	s_add_u32 s28, s28, 0x100
	s_addc_u32 s29, s29, 0
	s_add_u32 s53, s53, 0x100
	s_addc_u32 s54, s54, 0
	s_cmp_gt_u32 s55, 29
	s_barrier
	s_cbranch_scc0 .LBB0_1330
	s_and_b64 vcc, exec, s[14:15]
	s_cbranch_vccz .LBB0_1333
	s_barrier

; #define PG8_STAGE(bufoff, gbase, voff) do { _Pragma("unroll") for (int _i = 0; _i < 2; ++_i) \
;         __builtin_amdgcn_global_load_lds((const unsigned*)((const char*)(gbase) + (voff)[_i]), (PG8_LAS unsigned*)(lds + (bufoff) + ldsw + _i * 8192), 16, 0, 0); } while (0)
; #define PG8_STAGEB(bufoff, gbase, voff) do { _Pragma("unroll") for (int _i = 0; _i < 2; ++_i) \
;         __builtin_amdgcn_global_load_lds((const unsigned*)((const char*)(gbase) + (voff)[_i]), (PG8_LAS unsigned*)(lds + (bufoff) + ldsw + _i * 8192), 16, 0, PG8_BAUX); } while (0)
; #define PG8_LDA(dst, b, h) do { _Pragma("unroll") for (int m = 0; m < 4; ++m) _Pragma("unroll") for (int k = 0; k < 2; ++k) dst[m][k] = *(const PG8_LAS bf16x8*)(lds + PG8_SA(b, h) + aoff + m * 2048 + k * 1024); } while (0)
; #define PG8_LDB(dst, b, h) do { _Pragma("unroll") for (int n = 0; n < 2; ++n) _Pragma("unroll") for (int k = 0; k < 2; ++k) dst[n][k] = *(const PG8_LAS bf16x8*)(lds + PG8_SB(b, h) + boff + n * 2048 + k * 1024); } while (0)
; #define PG8_MMA(ai, bj, At, Bt) do { __builtin_amdgcn_s_setprio(1); _Pragma("unroll") for (int m = 0; m < 4; ++m) _Pragma("unroll") for (int n = 0; n < 2; ++n) _Pragma("unroll") for (int k = 0; k < 2; ++k) \
;         acc[ai][bj][m][n] = __builtin_amdgcn_mfma_f32_16x16x32_bf16(Bt[n][k], At[m][k], acc[ai][bj][m][n], 0, 0, 0); __builtin_amdgcn_s_setprio(0); } while (0)
; template <class Epi, class Sched, bool ALIGN_EPI = false, bool SP2 = false>
; __device__ __forceinline__ void gemm_phase(PG8_LAS unsigned char* lds, const Gemm g, const Sched& S, const Epi& E) {
;     ...
;             const bool last = (t == nt - 2);
;             const char* a1 = cA + (size_t)(t + 1) * kstep;
;             const char* a2 = last ? nA : cA + (size_t)(t + 2) * kstep; const char* b2 = last ? nB : cB + (size_t)(t + 2) * kstep;
;             const char* a3 = a2 + kstep; const char* b3 = b2 + kstep;
;             if (last && has_next) S.a_ready(nxt);
;             if constexpr (SP2) {
;             PG8_LDB(B0, 0, 0); PG8_LDB(B1, 0, 1); PG8_SCHED; PG8_LDA(At, 0, 0); PG8_STAGE(PG8_SA(1, 1), a1 + hstep, voffA);
;             PG8_WAIT_V(8); PG8_WAIT_L(0); PG8_BAR; PG8_MMA(0, 0, At, B0); PG8_MMA(0, 1, At, B1); PG8_BAR; PG8_SCHED;
;             PG8_LDA(At, 0, 1); PG8_STAGEB(PG8_SB(0, 0), b2, voffB); PG8_STAGEB(PG8_SB(0, 1), b2 + hstep, voffB); PG8_STAGE(PG8_SA(0, 0), a2, voffA);
.LBB0_1437:
	ds_read_b128 v[156:159], v152
	ds_read_b128 v[160:163], v152 offset:1024
	ds_read_b128 v[164:167], v152 offset:2048
	ds_read_b128 v[168:171], v152 offset:3072
	ds_read_b128 v[172:175], v153
	ds_read_b128 v[180:183], v153 offset:1024
	ds_read_b128 v[184:187], v153 offset:2048
	ds_read_b128 v[192:195], v153 offset:3072
	s_add_u32 s24, s22, 0xfff80080
	s_addc_u32 s25, s23, -1
	s_cmp_eq_u32 s49, 28
	s_cselect_b32 s27, s15, s25
	s_cselect_b32 s26, s45, s24
	s_cselect_b32 s25, s13, s48
	s_cselect_b32 s24, s46, s47
	v_lshl_add_u64 v[176:177], s[22:23], 0, v[138:139]
	s_add_i32 m0, s17, 0xc000
	ds_read_b128 v[196:199], v154
	ds_read_b128 v[200:203], v154 offset:1024
	ds_read_b128 v[204:207], v154 offset:2048
	ds_read_b128 v[208:211], v154 offset:3072
	ds_read_b128 v[212:215], v154 offset:4096
	ds_read_b128 v[216:219], v154 offset:5120
	ds_read_b128 v[220:223], v154 offset:6144
	ds_read_b128 v[224:227], v154 offset:7168
	global_load_lds_dwordx4 v[176:177], off
	v_lshl_add_u64 v[176:177], s[22:23], 0, v[140:141]
	s_add_i32 m0, s17, 0xe000
	s_nop 0
	global_load_lds_dwordx4 v[176:177], off
	s_waitcnt vmcnt(8)
	s_waitcnt lgkmcnt(0)
	s_barrier
	s_setprio 1
	s_waitcnt lgkmcnt(0)
	v_mfma_f32_16x16x32_bf16 v[126:129], v[156:159], v[196:199], v[126:129]
	v_mfma_f32_16x16x32_bf16 v[122:125], v[164:167], v[196:199], v[122:125]
	v_mfma_f32_16x16x32_bf16 v[118:121], v[156:159], v[204:207], v[118:121]
	v_mfma_f32_16x16x32_bf16 v[110:113], v[164:167], v[204:207], v[110:113]
	v_mfma_f32_16x16x32_bf16 v[98:101], v[156:159], v[212:215], v[98:101]
	v_mfma_f32_16x16x32_bf16 v[90:93], v[164:167], v[212:215], v[90:93]
	v_mfma_f32_16x16x32_bf16 v[86:89], v[156:159], v[220:223], v[86:89]
	v_mfma_f32_16x16x32_bf16 v[78:81], v[164:167], v[220:223], v[78:81]
	v_mfma_f32_16x16x32_bf16 v[126:129], v[160:163], v[200:203], v[126:129]
	v_mfma_f32_16x16x32_bf16 v[122:125], v[168:171], v[200:203], v[122:125]
	v_mfma_f32_16x16x32_bf16 v[118:121], v[160:163], v[208:211], v[118:121]
	v_mfma_f32_16x16x32_bf16 v[110:113], v[168:171], v[208:211], v[110:113]
	v_mfma_f32_16x16x32_bf16 v[98:101], v[160:163], v[216:219], v[98:101]
	v_mfma_f32_16x16x32_bf16 v[90:93], v[168:171], v[216:219], v[90:93]
	v_mfma_f32_16x16x32_bf16 v[86:89], v[160:163], v[224:227], v[86:89]
	v_mfma_f32_16x16x32_bf16 v[78:81], v[168:171], v[224:227], v[78:81]
	s_setprio 0
	s_setprio 1
	v_mfma_f32_16x16x32_bf16 v[114:117], v[172:175], v[196:199], v[114:117]
	v_mfma_f32_16x16x32_bf16 v[106:109], v[184:187], v[196:199], v[106:109]
	v_mfma_f32_16x16x32_bf16 v[102:105], v[172:175], v[204:207], v[102:105]
	v_mfma_f32_16x16x32_bf16 v[94:97], v[184:187], v[204:207], v[94:97]
	v_mfma_f32_16x16x32_bf16 v[82:85], v[172:175], v[212:215], v[82:85]
	v_mfma_f32_16x16x32_bf16 v[74:77], v[184:187], v[212:215], v[74:77]
	v_mfma_f32_16x16x32_bf16 v[70:73], v[172:175], v[220:223], v[70:73]
	v_mfma_f32_16x16x32_bf16 v[66:69], v[184:187], v[220:223], v[66:69]
	v_mfma_f32_16x16x32_bf16 v[114:117], v[180:183], v[200:203], v[114:117]
	v_mfma_f32_16x16x32_bf16 v[106:109], v[192:195], v[200:203], v[106:109]
	v_mfma_f32_16x16x32_bf16 v[102:105], v[180:183], v[208:211], v[102:105]
	v_mfma_f32_16x16x32_bf16 v[94:97], v[192:195], v[208:211], v[94:97]
	v_mfma_f32_16x16x32_bf16 v[82:85], v[180:183], v[216:219], v[82:85]
	v_mfma_f32_16x16x32_bf16 v[74:77], v[192:195], v[216:219], v[74:77]
	v_mfma_f32_16x16x32_bf16 v[70:73], v[180:183], v[224:227], v[70:73]
	v_mfma_f32_16x16x32_bf16 v[66:69], v[192:195], v[224:227], v[66:69]
	s_setprio 0
	s_barrier
	s_add_i32 s50, s42, s29
	v_lshl_add_u64 v[176:177], s[24:25], 0, v[132:133]
	s_mov_b32 m0, s50
	ds_read_b128 v[196:199], v154 offset:16384
	ds_read_b128 v[200:203], v154 offset:17408
	ds_read_b128 v[204:207], v154 offset:18432
	ds_read_b128 v[208:211], v154 offset:19456
	ds_read_b128 v[212:215], v154 offset:20480
	ds_read_b128 v[216:219], v154 offset:21504
	ds_read_b128 v[220:223], v154 offset:22528
	ds_read_b128 v[224:227], v154 offset:23552
	global_load_lds_dwordx4 v[176:177], off
	s_add_i32 m0, s50, 0x2000
	s_add_u32 s50, s24, 0x80000
	v_lshl_add_u64 v[188:189], s[24:25], 0, v[136:137]
	s_addc_u32 s51, s25, 0
	s_add_i32 s52, s43, s29
	global_load_lds_dwordx4 v[188:189], off
	v_lshl_add_u64 v[228:229], s[50:51], 0, v[132:133]
	s_mov_b32 m0, s52
	v_lshl_add_u64 v[230:231], s[26:27], 0, v[134:135]
	global_load_lds_dwordx4 v[228:229], off
	v_lshl_add_u64 v[228:229], s[50:51], 0, v[136:137]
	s_add_i32 m0, s52, 0x2000
	s_nop 0
	global_load_lds_dwordx4 v[228:229], off
	v_lshl_add_u64 v[228:229], s[26:27], 0, v[130:131]
	s_mov_b32 m0, s17
	s_nop 0
	global_load_lds_dwordx4 v[228:229], off
	s_mov_b32 m0, s33
	s_nop 0
	global_load_lds_dwordx4 v[230:231], off
	s_waitcnt vmcnt(8)
	s_waitcnt lgkmcnt(0)
	s_barrier
; #define PG8_STAGE(bufoff, gbase, voff) do { _Pragma("unroll") for (int _i = 0; _i < 2; ++_i) \
;         __builtin_amdgcn_global_load_lds((const unsigned*)((const char*)(gbase) + (voff)[_i]), (PG8_LAS unsigned*)(lds + (bufoff) + ldsw + _i * 8192), 16, 0, 0); } while (0)
; #define PG8_LDA(dst, b, h) do { _Pragma("unroll") for (int m = 0; m < 4; ++m) _Pragma("unroll") for (int k = 0; k < 2; ++k) dst[m][k] = *(const PG8_LAS bf16x8*)(lds + PG8_SA(b, h) + aoff + m * 2048 + k * 1024); } while (0)
; #define PG8_LDB(dst, b, h) do { _Pragma("unroll") for (int n = 0; n < 2; ++n) _Pragma("unroll") for (int k = 0; k < 2; ++k) dst[n][k] = *(const PG8_LAS bf16x8*)(lds + PG8_SB(b, h) + boff + n * 2048 + k * 1024); } while (0)
; #define PG8_MMA(ai, bj, At, Bt) do { __builtin_amdgcn_s_setprio(1); _Pragma("unroll") for (int m = 0; m < 4; ++m) _Pragma("unroll") for (int n = 0; n < 2; ++n) _Pragma("unroll") for (int k = 0; k < 2; ++k) \
;         acc[ai][bj][m][n] = __builtin_amdgcn_mfma_f32_16x16x32_bf16(Bt[n][k], At[m][k], acc[ai][bj][m][n], 0, 0, 0); __builtin_amdgcn_s_setprio(0); } while (0)
; #define PG8_WAIT_V(n) asm volatile("s_waitcnt vmcnt(" #n ")" ::: "memory")
; #define PG8_WAIT_L(n) asm volatile("s_waitcnt lgkmcnt(" #n ")" ::: "memory")
; #define PG8_BAR __builtin_amdgcn_s_barrier()
; #define PG8_SCHED __builtin_amdgcn_sched_barrier(0)
; template <class Epi, class Sched, bool ALIGN_EPI = false, bool SP2 = false>
; __device__ __forceinline__ void gemm_phase(PG8_LAS unsigned char* lds, const Gemm g, const Sched& S, const Epi& E) {
;     ...
;             PG8_WAIT_V(8); PG8_WAIT_L(0); PG8_BAR; PG8_MMA(1, 0, At, B0); PG8_MMA(1, 1, At, B1); PG8_BAR; PG8_SCHED;
;             PG8_LDB(B0, 1, 0); PG8_LDB(B1, 1, 1); PG8_SCHED; PG8_LDA(At, 1, 0); PG8_STAGE(PG8_SA(0, 1), a2 + hstep, voffA);
;             PG8_WAIT_V(8); PG8_WAIT_L(0); PG8_BAR; PG8_MMA(0, 0, At, B0); PG8_MMA(0, 1, At, B1); PG8_BAR; PG8_SCHED;
	s_setprio 1
	s_waitcnt lgkmcnt(0)
	v_mfma_f32_16x16x32_bf16 v[62:65], v[156:159], v[196:199], v[62:65]
	v_mfma_f32_16x16x32_bf16 v[58:61], v[164:167], v[196:199], v[58:61]
	v_mfma_f32_16x16x32_bf16 v[54:57], v[156:159], v[204:207], v[54:57]
	v_mfma_f32_16x16x32_bf16 v[46:49], v[164:167], v[204:207], v[46:49]
	v_mfma_f32_16x16x32_bf16 v[38:41], v[156:159], v[212:215], v[38:41]
	v_mfma_f32_16x16x32_bf16 v[30:33], v[164:167], v[212:215], v[30:33]
	v_mfma_f32_16x16x32_bf16 v[22:25], v[156:159], v[220:223], v[22:25]
	v_mfma_f32_16x16x32_bf16 v[14:17], v[164:167], v[220:223], v[14:17]
	v_mfma_f32_16x16x32_bf16 v[62:65], v[160:163], v[200:203], v[62:65]
	v_mfma_f32_16x16x32_bf16 v[58:61], v[168:171], v[200:203], v[58:61]
	v_mfma_f32_16x16x32_bf16 v[54:57], v[160:163], v[208:211], v[54:57]
	v_mfma_f32_16x16x32_bf16 v[46:49], v[168:171], v[208:211], v[46:49]
	v_mfma_f32_16x16x32_bf16 v[38:41], v[160:163], v[216:219], v[38:41]
	v_mfma_f32_16x16x32_bf16 v[30:33], v[168:171], v[216:219], v[30:33]
	v_mfma_f32_16x16x32_bf16 v[22:25], v[160:163], v[224:227], v[22:25]
	v_mfma_f32_16x16x32_bf16 v[14:17], v[168:171], v[224:227], v[14:17]
	s_setprio 0
	s_setprio 1
	v_mfma_f32_16x16x32_bf16 v[50:53], v[172:175], v[196:199], v[50:53]
	v_mfma_f32_16x16x32_bf16 v[42:45], v[184:187], v[196:199], v[42:45]
	v_mfma_f32_16x16x32_bf16 v[34:37], v[172:175], v[204:207], v[34:37]
	v_mfma_f32_16x16x32_bf16 v[26:29], v[184:187], v[204:207], v[26:29]
	v_mfma_f32_16x16x32_bf16 v[18:21], v[172:175], v[212:215], v[18:21]
	v_mfma_f32_16x16x32_bf16 v[10:13], v[184:187], v[212:215], v[10:13]
	v_mfma_f32_16x16x32_bf16 v[6:9], v[172:175], v[220:223], v[6:9]
	v_mfma_f32_16x16x32_bf16 v[2:5], v[184:187], v[220:223], v[2:5]
	v_mfma_f32_16x16x32_bf16 v[50:53], v[180:183], v[200:203], v[50:53]
	v_mfma_f32_16x16x32_bf16 v[42:45], v[192:195], v[200:203], v[42:45]
	v_mfma_f32_16x16x32_bf16 v[34:37], v[180:183], v[208:211], v[34:37]
	v_mfma_f32_16x16x32_bf16 v[26:29], v[192:195], v[208:211], v[26:29]
	v_mfma_f32_16x16x32_bf16 v[18:21], v[180:183], v[216:219], v[18:21]
	v_mfma_f32_16x16x32_bf16 v[10:13], v[192:195], v[216:219], v[10:13]
	v_mfma_f32_16x16x32_bf16 v[6:9], v[180:183], v[224:227], v[6:9]
	v_mfma_f32_16x16x32_bf16 v[2:5], v[192:195], v[224:227], v[2:5]
	s_setprio 0
	s_barrier
	s_add_i32 s50, 0, 0x18000
	v_add_u32_e32 v155, s50, v147
	s_add_i32 s51, 0, 0x1c000
	ds_read_b128 v[156:159], v155
	ds_read_b128 v[160:163], v155 offset:1024
	ds_read_b128 v[164:167], v155 offset:2048
	ds_read_b128 v[168:171], v155 offset:3072
	v_add_u32_e32 v155, s51, v147
	ds_read_b128 v[172:175], v155
	ds_read_b128 v[180:183], v155 offset:1024
	ds_read_b128 v[184:187], v155 offset:2048
	ds_read_b128 v[192:195], v155 offset:3072
	s_add_u32 s26, s26, 0x80000
	s_addc_u32 s27, s27, 0
	s_mov_b32 m0, s34
	v_lshl_add_u64 v[232:233], s[26:27], 0, v[130:131]
	ds_read_b128 v[196:199], v154 offset:32768
	ds_read_b128 v[200:203], v154 offset:33792
	ds_read_b128 v[204:207], v154 offset:34816
	ds_read_b128 v[208:211], v154 offset:35840
	ds_read_b128 v[212:215], v154 offset:36864
	ds_read_b128 v[216:219], v154 offset:37888
	ds_read_b128 v[220:223], v154 offset:38912
	ds_read_b128 v[224:227], v154 offset:39936
	global_load_lds_dwordx4 v[232:233], off
	v_lshl_add_u64 v[232:233], s[26:27], 0, v[134:135]
	s_mov_b32 m0, s35
	s_nop 0
	global_load_lds_dwordx4 v[232:233], off
	s_waitcnt vmcnt(8)
	s_waitcnt lgkmcnt(0)
	s_barrier
	s_setprio 1
	s_waitcnt lgkmcnt(0)
	v_mfma_f32_16x16x32_bf16 v[126:129], v[156:159], v[196:199], v[126:129]
	v_mfma_f32_16x16x32_bf16 v[122:125], v[164:167], v[196:199], v[122:125]
	v_mfma_f32_16x16x32_bf16 v[118:121], v[156:159], v[204:207], v[118:121]
	v_mfma_f32_16x16x32_bf16 v[110:113], v[164:167], v[204:207], v[110:113]
	v_mfma_f32_16x16x32_bf16 v[98:101], v[156:159], v[212:215], v[98:101]
	v_mfma_f32_16x16x32_bf16 v[90:93], v[164:167], v[212:215], v[90:93]
	v_mfma_f32_16x16x32_bf16 v[86:89], v[156:159], v[220:223], v[86:89]
	v_mfma_f32_16x16x32_bf16 v[78:81], v[164:167], v[220:223], v[78:81]
	v_mfma_f32_16x16x32_bf16 v[126:129], v[160:163], v[200:203], v[126:129]
	v_mfma_f32_16x16x32_bf16 v[122:125], v[168:171], v[200:203], v[122:125]
	v_mfma_f32_16x16x32_bf16 v[118:121], v[160:163], v[208:211], v[118:121]
	v_mfma_f32_16x16x32_bf16 v[110:113], v[168:171], v[208:211], v[110:113]
	v_mfma_f32_16x16x32_bf16 v[98:101], v[160:163], v[216:219], v[98:101]
	v_mfma_f32_16x16x32_bf16 v[90:93], v[168:171], v[216:219], v[90:93]
	v_mfma_f32_16x16x32_bf16 v[86:89], v[160:163], v[224:227], v[86:89]
	v_mfma_f32_16x16x32_bf16 v[78:81], v[168:171], v[224:227], v[78:81]
	s_setprio 0
	s_setprio 1
	v_mfma_f32_16x16x32_bf16 v[114:117], v[172:175], v[196:199], v[114:117]
	v_mfma_f32_16x16x32_bf16 v[106:109], v[184:187], v[196:199], v[106:109]
	v_mfma_f32_16x16x32_bf16 v[102:105], v[172:175], v[204:207], v[102:105]
	v_mfma_f32_16x16x32_bf16 v[94:97], v[184:187], v[204:207], v[94:97]
	v_mfma_f32_16x16x32_bf16 v[82:85], v[172:175], v[212:215], v[82:85]
	v_mfma_f32_16x16x32_bf16 v[74:77], v[184:187], v[212:215], v[74:77]
	v_mfma_f32_16x16x32_bf16 v[70:73], v[172:175], v[220:223], v[70:73]
	v_mfma_f32_16x16x32_bf16 v[66:69], v[184:187], v[220:223], v[66:69]
	v_mfma_f32_16x16x32_bf16 v[114:117], v[180:183], v[200:203], v[114:117]
	v_mfma_f32_16x16x32_bf16 v[106:109], v[192:195], v[200:203], v[106:109]
	v_mfma_f32_16x16x32_bf16 v[102:105], v[180:183], v[208:211], v[102:105]
	v_mfma_f32_16x16x32_bf16 v[94:97], v[192:195], v[208:211], v[94:97]
	v_mfma_f32_16x16x32_bf16 v[82:85], v[180:183], v[216:219], v[82:85]
	v_mfma_f32_16x16x32_bf16 v[74:77], v[192:195], v[216:219], v[74:77]
	v_mfma_f32_16x16x32_bf16 v[70:73], v[180:183], v[224:227], v[70:73]
	v_mfma_f32_16x16x32_bf16 v[66:69], v[192:195], v[224:227], v[66:69]
	s_setprio 0
	s_barrier
; #define PG8_STAGE(bufoff, gbase, voff) do { _Pragma("unroll") for (int _i = 0; _i < 2; ++_i) \
;         __builtin_amdgcn_global_load_lds((const unsigned*)((const char*)(gbase) + (voff)[_i]), (PG8_LAS unsigned*)(lds + (bufoff) + ldsw + _i * 8192), 16, 0, 0); } while (0)
; #define PG8_STAGEB(bufoff, gbase, voff) do { _Pragma("unroll") for (int _i = 0; _i < 2; ++_i) \
;         __builtin_amdgcn_global_load_lds((const unsigned*)((const char*)(gbase) + (voff)[_i]), (PG8_LAS unsigned*)(lds + (bufoff) + ldsw + _i * 8192), 16, 0, PG8_BAUX); } while (0)
; #define PG8_LDA(dst, b, h) do { _Pragma("unroll") for (int m = 0; m < 4; ++m) _Pragma("unroll") for (int k = 0; k < 2; ++k) dst[m][k] = *(const PG8_LAS bf16x8*)(lds + PG8_SA(b, h) + aoff + m * 2048 + k * 1024); } while (0)
; #define PG8_MMA(ai, bj, At, Bt) do { __builtin_amdgcn_s_setprio(1); _Pragma("unroll") for (int m = 0; m < 4; ++m) _Pragma("unroll") for (int n = 0; n < 2; ++n) _Pragma("unroll") for (int k = 0; k < 2; ++k) \
;         acc[ai][bj][m][n] = __builtin_amdgcn_mfma_f32_16x16x32_bf16(Bt[n][k], At[m][k], acc[ai][bj][m][n], 0, 0, 0); __builtin_amdgcn_s_setprio(0); } while (0)
; #define PG8_WAIT_V(n) asm volatile("s_waitcnt vmcnt(" #n ")" ::: "memory")
; #define PG8_WAIT_L(n) asm volatile("s_waitcnt lgkmcnt(" #n ")" ::: "memory")
; #define PG8_BAR __builtin_amdgcn_s_barrier()
; #define PG8_SCHED __builtin_amdgcn_sched_barrier(0)
; template <class Epi, class Sched, bool ALIGN_EPI = false, bool SP2 = false>
; __device__ __forceinline__ void gemm_phase(PG8_LAS unsigned char* lds, const Gemm g, const Sched& S, const Epi& E) {
;     ...
;         for (int t = 0; t < nt; t += 2) {
;     ...
;             PG8_LDA(At, 1, 1); PG8_STAGEB(PG8_SB(1, 0), b3, voffB); PG8_STAGEB(PG8_SB(1, 1), b3 + hstep, voffB); PG8_STAGE(PG8_SA(1, 0), a3, voffA);
;             PG8_WAIT_V(8); PG8_WAIT_L(0); PG8_BAR; PG8_MMA(1, 0, At, B0); PG8_MMA(1, 1, At, B1); PG8_BAR; PG8_SCHED;
	s_add_i32 s26, s50, s29
	v_lshl_add_u64 v[176:177], v[176:177], 0, s[8:9]
	s_mov_b32 m0, s26
	ds_read_b128 v[196:199], v154 offset:49152
	ds_read_b128 v[200:203], v154 offset:50176
	ds_read_b128 v[204:207], v154 offset:51200
	ds_read_b128 v[208:211], v154 offset:52224
	ds_read_b128 v[212:215], v154 offset:53248
	ds_read_b128 v[216:219], v154 offset:54272
	ds_read_b128 v[220:223], v154 offset:55296
	ds_read_b128 v[224:227], v154 offset:56320
	global_load_lds_dwordx4 v[176:177], off
	s_add_i32 m0, s26, 0x2000
	s_add_u32 s24, s24, 0x80080
	v_lshl_add_u64 v[176:177], v[188:189], 0, s[8:9]
	s_addc_u32 s25, s25, 0
	s_add_i32 s26, s51, s29
	global_load_lds_dwordx4 v[176:177], off
	v_lshl_add_u64 v[176:177], s[24:25], 0, v[132:133]
	s_mov_b32 m0, s26
	s_nop 0
	global_load_lds_dwordx4 v[176:177], off
	v_lshl_add_u64 v[176:177], s[24:25], 0, v[136:137]
	s_add_i32 m0, s26, 0x2000
	s_nop 0
	global_load_lds_dwordx4 v[176:177], off
	v_lshl_add_u64 v[176:177], v[228:229], 0, s[8:9]
	s_mov_b32 m0, s39
	s_nop 0
	global_load_lds_dwordx4 v[176:177], off
	v_lshl_add_u64 v[176:177], v[230:231], 0, s[8:9]
	s_mov_b32 m0, s40
	s_nop 0
	global_load_lds_dwordx4 v[176:177], off
	s_waitcnt vmcnt(8)
	s_waitcnt lgkmcnt(0)
	s_barrier
	s_setprio 1
	s_waitcnt lgkmcnt(0)
	v_mfma_f32_16x16x32_bf16 v[62:65], v[156:159], v[196:199], v[62:65]
	v_mfma_f32_16x16x32_bf16 v[58:61], v[164:167], v[196:199], v[58:61]
	v_mfma_f32_16x16x32_bf16 v[54:57], v[156:159], v[204:207], v[54:57]
	v_mfma_f32_16x16x32_bf16 v[46:49], v[164:167], v[204:207], v[46:49]
	v_mfma_f32_16x16x32_bf16 v[38:41], v[156:159], v[212:215], v[38:41]
	v_mfma_f32_16x16x32_bf16 v[30:33], v[164:167], v[212:215], v[30:33]
	v_mfma_f32_16x16x32_bf16 v[22:25], v[156:159], v[220:223], v[22:25]
	v_mfma_f32_16x16x32_bf16 v[14:17], v[164:167], v[220:223], v[14:17]
	v_mfma_f32_16x16x32_bf16 v[62:65], v[160:163], v[200:203], v[62:65]
	v_mfma_f32_16x16x32_bf16 v[58:61], v[168:171], v[200:203], v[58:61]
	v_mfma_f32_16x16x32_bf16 v[54:57], v[160:163], v[208:211], v[54:57]
	v_mfma_f32_16x16x32_bf16 v[46:49], v[168:171], v[208:211], v[46:49]
	v_mfma_f32_16x16x32_bf16 v[38:41], v[160:163], v[216:219], v[38:41]
	v_mfma_f32_16x16x32_bf16 v[30:33], v[168:171], v[216:219], v[30:33]
	v_mfma_f32_16x16x32_bf16 v[22:25], v[160:163], v[224:227], v[22:25]
	v_mfma_f32_16x16x32_bf16 v[14:17], v[168:171], v[224:227], v[14:17]
	s_setprio 0
	s_setprio 1
	v_mfma_f32_16x16x32_bf16 v[50:53], v[172:175], v[196:199], v[50:53]
	v_mfma_f32_16x16x32_bf16 v[42:45], v[184:187], v[196:199], v[42:45]
	v_mfma_f32_16x16x32_bf16 v[34:37], v[172:175], v[204:207], v[34:37]
	v_mfma_f32_16x16x32_bf16 v[26:29], v[184:187], v[204:207], v[26:29]
	v_mfma_f32_16x16x32_bf16 v[18:21], v[172:175], v[212:215], v[18:21]
	v_mfma_f32_16x16x32_bf16 v[10:13], v[184:187], v[212:215], v[10:13]
	v_mfma_f32_16x16x32_bf16 v[6:9], v[172:175], v[220:223], v[6:9]
	v_mfma_f32_16x16x32_bf16 v[2:5], v[184:187], v[220:223], v[2:5]
	v_mfma_f32_16x16x32_bf16 v[50:53], v[180:183], v[200:203], v[50:53]
	v_mfma_f32_16x16x32_bf16 v[42:45], v[192:195], v[200:203], v[42:45]
	v_mfma_f32_16x16x32_bf16 v[34:37], v[180:183], v[208:211], v[34:37]
	v_mfma_f32_16x16x32_bf16 v[26:29], v[192:195], v[208:211], v[26:29]
	v_mfma_f32_16x16x32_bf16 v[18:21], v[180:183], v[216:219], v[18:21]
	v_mfma_f32_16x16x32_bf16 v[10:13], v[192:195], v[216:219], v[10:13]
	v_mfma_f32_16x16x32_bf16 v[6:9], v[180:183], v[224:227], v[6:9]
	v_mfma_f32_16x16x32_bf16 v[2:5], v[192:195], v[224:227], v[2:5]
	s_setprio 0
	s_add_i32 s49, s49, 2
	s_add_u32 s22, s22, 0x100
	s_addc_u32 s23, s23, 0
	s_add_u32 s47, s47, 0x100
	s_addc_u32 s48, s48, 0
	s_cmp_gt_u32 s49, 29
	s_barrier
	s_cbranch_scc0 .LBB0_1437
	s_and_b64 vcc, exec, s[10:11]
	s_cbranch_vccz .LBB0_1440
	s_barrier

; #define PG8_STAGE(bufoff, gbase, voff) do { _Pragma("unroll") for (int _i = 0; _i < 2; ++_i) \
;         __builtin_amdgcn_global_load_lds((const unsigned*)((const char*)(gbase) + (voff)[_i]), (PG8_LAS unsigned*)(lds + (bufoff) + ldsw + _i * 8192), 16, 0, 0); } while (0)
; #define PG8_STAGEB(bufoff, gbase, voff) do { _Pragma("unroll") for (int _i = 0; _i < 2; ++_i) \
;         __builtin_amdgcn_global_load_lds((const unsigned*)((const char*)(gbase) + (voff)[_i]), (PG8_LAS unsigned*)(lds + (bufoff) + ldsw + _i * 8192), 16, 0, PG8_BAUX); } while (0)
; #define PG8_LDA(dst, b, h) do { _Pragma("unroll") for (int m = 0; m < 4; ++m) _Pragma("unroll") for (int k = 0; k < 2; ++k) dst[m][k] = *(const PG8_LAS bf16x8*)(lds + PG8_SA(b, h) + aoff + m * 2048 + k * 1024); } while (0)
; #define PG8_LDB(dst, b, h) do { _Pragma("unroll") for (int n = 0; n < 2; ++n) _Pragma("unroll") for (int k = 0; k < 2; ++k) dst[n][k] = *(const PG8_LAS bf16x8*)(lds + PG8_SB(b, h) + boff + n * 2048 + k * 1024); } while (0)
; #define PG8_MMA(ai, bj, At, Bt) do { __builtin_amdgcn_s_setprio(1); _Pragma("unroll") for (int m = 0; m < 4; ++m) _Pragma("unroll") for (int n = 0; n < 2; ++n) _Pragma("unroll") for (int k = 0; k < 2; ++k) \
;         acc[ai][bj][m][n] = __builtin_amdgcn_mfma_f32_16x16x32_bf16(Bt[n][k], At[m][k], acc[ai][bj][m][n], 0, 0, 0); __builtin_amdgcn_s_setprio(0); } while (0)
; template <class Epi, class Sched, bool ALIGN_EPI = false, bool SP2 = false>
; __device__ __forceinline__ void gemm_phase(PG8_LAS unsigned char* lds, const Gemm g, const Sched& S, const Epi& E) {
;     ...
;             const bool last = (t == nt - 2);
;             const char* a1 = cA + (size_t)(t + 1) * kstep;
;             const char* a2 = last ? nA : cA + (size_t)(t + 2) * kstep; const char* b2 = last ? nB : cB + (size_t)(t + 2) * kstep;
;             const char* a3 = a2 + kstep; const char* b3 = b2 + kstep;
;             if (last && has_next) S.a_ready(nxt);
;             if constexpr (SP2) {
;             PG8_LDB(B0, 0, 0); PG8_LDB(B1, 0, 1); PG8_SCHED; PG8_LDA(At, 0, 0); PG8_STAGE(PG8_SA(1, 1), a1 + hstep, voffA);
;             PG8_WAIT_V(8); PG8_WAIT_L(0); PG8_BAR; PG8_MMA(0, 0, At, B0); PG8_MMA(0, 1, At, B1); PG8_BAR; PG8_SCHED;
;             PG8_LDA(At, 0, 1); PG8_STAGEB(PG8_SB(0, 0), b2, voffB); PG8_STAGEB(PG8_SB(0, 1), b2 + hstep, voffB); PG8_STAGE(PG8_SA(0, 0), a2, voffA);
.LBB0_1604:
	ds_read_b128 v[158:161], v153
	ds_read_b128 v[162:165], v153 offset:1024
	ds_read_b128 v[166:169], v153 offset:2048
	ds_read_b128 v[170:173], v153 offset:3072
	ds_read_b128 v[174:177], v154
	ds_read_b128 v[178:181], v154 offset:1024
	ds_read_b128 v[182:185], v154 offset:2048
	ds_read_b128 v[186:189], v154 offset:3072
	s_add_u32 s30, s28, 0xfffc0080
	s_addc_u32 s31, s29, -1
	s_cmp_eq_u32 s53, 12
	s_cselect_b32 s35, s17, s31
	s_cselect_b32 s34, s25, s30
	s_cselect_b32 s31, s19, s52
	s_cselect_b32 s30, s50, s51
	v_lshl_add_u64 v[148:149], s[28:29], 0, v[140:141]
	s_add_i32 m0, s27, 0xc000
	ds_read_b128 v[192:195], v155
	ds_read_b128 v[196:199], v155 offset:1024
	ds_read_b128 v[200:203], v155 offset:2048
	ds_read_b128 v[204:207], v155 offset:3072
	ds_read_b128 v[208:211], v155 offset:4096
	ds_read_b128 v[212:215], v155 offset:5120
	ds_read_b128 v[216:219], v155 offset:6144
	ds_read_b128 v[220:223], v155 offset:7168
	global_load_lds_dwordx4 v[148:149], off
	v_lshl_add_u64 v[148:149], s[28:29], 0, v[142:143]
	s_add_i32 m0, s27, 0xe000
	s_nop 0
	global_load_lds_dwordx4 v[148:149], off
	s_waitcnt vmcnt(8)
	s_waitcnt lgkmcnt(0)
	s_barrier
	s_setprio 1
	s_waitcnt lgkmcnt(0)
	v_mfma_f32_16x16x32_bf16 v[126:129], v[158:161], v[192:195], v[126:129]
	v_mfma_f32_16x16x32_bf16 v[122:125], v[166:169], v[192:195], v[122:125]
	v_mfma_f32_16x16x32_bf16 v[110:113], v[158:161], v[200:203], v[110:113]
	v_mfma_f32_16x16x32_bf16 v[106:109], v[166:169], v[200:203], v[106:109]
	v_mfma_f32_16x16x32_bf16 v[94:97], v[158:161], v[208:211], v[94:97]
	v_mfma_f32_16x16x32_bf16 v[90:93], v[166:169], v[208:211], v[90:93]
	v_mfma_f32_16x16x32_bf16 v[78:81], v[158:161], v[216:219], v[78:81]
	v_mfma_f32_16x16x32_bf16 v[74:77], v[166:169], v[216:219], v[74:77]
	v_mfma_f32_16x16x32_bf16 v[126:129], v[162:165], v[196:199], v[126:129]
	v_mfma_f32_16x16x32_bf16 v[122:125], v[170:173], v[196:199], v[122:125]
	v_mfma_f32_16x16x32_bf16 v[110:113], v[162:165], v[204:207], v[110:113]
	v_mfma_f32_16x16x32_bf16 v[106:109], v[170:173], v[204:207], v[106:109]
	v_mfma_f32_16x16x32_bf16 v[94:97], v[162:165], v[212:215], v[94:97]
	v_mfma_f32_16x16x32_bf16 v[90:93], v[170:173], v[212:215], v[90:93]
	v_mfma_f32_16x16x32_bf16 v[78:81], v[162:165], v[220:223], v[78:81]
	v_mfma_f32_16x16x32_bf16 v[74:77], v[170:173], v[220:223], v[74:77]
	s_setprio 0
	s_setprio 1
	v_mfma_f32_16x16x32_bf16 v[118:121], v[174:177], v[192:195], v[118:121]
	v_mfma_f32_16x16x32_bf16 v[114:117], v[182:185], v[192:195], v[114:117]
	v_mfma_f32_16x16x32_bf16 v[102:105], v[174:177], v[200:203], v[102:105]
	v_mfma_f32_16x16x32_bf16 v[98:101], v[182:185], v[200:203], v[98:101]
	v_mfma_f32_16x16x32_bf16 v[86:89], v[174:177], v[208:211], v[86:89]
	v_mfma_f32_16x16x32_bf16 v[82:85], v[182:185], v[208:211], v[82:85]
	v_mfma_f32_16x16x32_bf16 v[70:73], v[174:177], v[216:219], v[70:73]
	v_mfma_f32_16x16x32_bf16 v[66:69], v[182:185], v[216:219], v[66:69]
	v_mfma_f32_16x16x32_bf16 v[118:121], v[178:181], v[196:199], v[118:121]
	v_mfma_f32_16x16x32_bf16 v[114:117], v[186:189], v[196:199], v[114:117]
	v_mfma_f32_16x16x32_bf16 v[102:105], v[178:181], v[204:207], v[102:105]
	v_mfma_f32_16x16x32_bf16 v[98:101], v[186:189], v[204:207], v[98:101]
	v_mfma_f32_16x16x32_bf16 v[86:89], v[178:181], v[212:215], v[86:89]
	v_mfma_f32_16x16x32_bf16 v[82:85], v[186:189], v[212:215], v[82:85]
	v_mfma_f32_16x16x32_bf16 v[70:73], v[178:181], v[220:223], v[70:73]
	v_mfma_f32_16x16x32_bf16 v[66:69], v[186:189], v[220:223], v[66:69]
	s_setprio 0
	s_barrier
	s_add_i32 s54, s48, s39
	v_lshl_add_u64 v[148:149], s[30:31], 0, v[132:133]
	s_mov_b32 m0, s54
	ds_read_b128 v[192:195], v155 offset:16384
	ds_read_b128 v[196:199], v155 offset:17408
	ds_read_b128 v[200:203], v155 offset:18432
	ds_read_b128 v[204:207], v155 offset:19456
	ds_read_b128 v[208:211], v155 offset:20480
	ds_read_b128 v[212:215], v155 offset:21504
	ds_read_b128 v[216:219], v155 offset:22528
	ds_read_b128 v[220:223], v155 offset:23552
	global_load_lds_dwordx4 v[148:149], off
	s_add_i32 m0, s54, 0x2000
	s_add_u32 s54, s30, 0x40000
	v_lshl_add_u64 v[224:225], s[30:31], 0, v[136:137]
	s_addc_u32 s55, s31, 0
	s_add_i32 s56, s49, s39
	global_load_lds_dwordx4 v[224:225], off
	v_lshl_add_u64 v[226:227], s[54:55], 0, v[132:133]
	s_mov_b32 m0, s56
	v_lshl_add_u64 v[228:229], s[34:35], 0, v[134:135]
	global_load_lds_dwordx4 v[226:227], off
	v_lshl_add_u64 v[226:227], s[54:55], 0, v[136:137]
	s_add_i32 m0, s56, 0x2000
	s_nop 0
	global_load_lds_dwordx4 v[226:227], off
	v_lshl_add_u64 v[226:227], s[34:35], 0, v[130:131]
	s_mov_b32 m0, s27
	s_nop 0
	global_load_lds_dwordx4 v[226:227], off
	s_mov_b32 m0, s40
	s_nop 0
	global_load_lds_dwordx4 v[228:229], off
	s_waitcnt vmcnt(8)
	s_waitcnt lgkmcnt(0)
	s_barrier
; #define PG8_STAGE(bufoff, gbase, voff) do { _Pragma("unroll") for (int _i = 0; _i < 2; ++_i) \
;         __builtin_amdgcn_global_load_lds((const unsigned*)((const char*)(gbase) + (voff)[_i]), (PG8_LAS unsigned*)(lds + (bufoff) + ldsw + _i * 8192), 16, 0, 0); } while (0)
; #define PG8_LDA(dst, b, h) do { _Pragma("unroll") for (int m = 0; m < 4; ++m) _Pragma("unroll") for (int k = 0; k < 2; ++k) dst[m][k] = *(const PG8_LAS bf16x8*)(lds + PG8_SA(b, h) + aoff + m * 2048 + k * 1024); } while (0)
; #define PG8_LDB(dst, b, h) do { _Pragma("unroll") for (int n = 0; n < 2; ++n) _Pragma("unroll") for (int k = 0; k < 2; ++k) dst[n][k] = *(const PG8_LAS bf16x8*)(lds + PG8_SB(b, h) + boff + n * 2048 + k * 1024); } while (0)
; #define PG8_MMA(ai, bj, At, Bt) do { __builtin_amdgcn_s_setprio(1); _Pragma("unroll") for (int m = 0; m < 4; ++m) _Pragma("unroll") for (int n = 0; n < 2; ++n) _Pragma("unroll") for (int k = 0; k < 2; ++k) \
;         acc[ai][bj][m][n] = __builtin_amdgcn_mfma_f32_16x16x32_bf16(Bt[n][k], At[m][k], acc[ai][bj][m][n], 0, 0, 0); __builtin_amdgcn_s_setprio(0); } while (0)
; #define PG8_WAIT_V(n) asm volatile("s_waitcnt vmcnt(" #n ")" ::: "memory")
; #define PG8_WAIT_L(n) asm volatile("s_waitcnt lgkmcnt(" #n ")" ::: "memory")
; #define PG8_BAR __builtin_amdgcn_s_barrier()
; #define PG8_SCHED __builtin_amdgcn_sched_barrier(0)
; template <class Epi, class Sched, bool ALIGN_EPI = false, bool SP2 = false>
; __device__ __forceinline__ void gemm_phase(PG8_LAS unsigned char* lds, const Gemm g, const Sched& S, const Epi& E) {
;     ...
;             PG8_WAIT_V(8); PG8_WAIT_L(0); PG8_BAR; PG8_MMA(1, 0, At, B0); PG8_MMA(1, 1, At, B1); PG8_BAR; PG8_SCHED;
;             PG8_LDB(B0, 1, 0); PG8_LDB(B1, 1, 1); PG8_SCHED; PG8_LDA(At, 1, 0); PG8_STAGE(PG8_SA(0, 1), a2 + hstep, voffA);
;             PG8_WAIT_V(8); PG8_WAIT_L(0); PG8_BAR; PG8_MMA(0, 0, At, B0); PG8_MMA(0, 1, At, B1); PG8_BAR; PG8_SCHED;
	s_setprio 1
	s_waitcnt lgkmcnt(0)
	v_mfma_f32_16x16x32_bf16 v[62:65], v[158:161], v[192:195], v[62:65]
	v_mfma_f32_16x16x32_bf16 v[58:61], v[166:169], v[192:195], v[58:61]
	v_mfma_f32_16x16x32_bf16 v[46:49], v[158:161], v[200:203], v[46:49]
	v_mfma_f32_16x16x32_bf16 v[42:45], v[166:169], v[200:203], v[42:45]
	v_mfma_f32_16x16x32_bf16 v[30:33], v[158:161], v[208:211], v[30:33]
	v_mfma_f32_16x16x32_bf16 v[26:29], v[166:169], v[208:211], v[26:29]
	v_mfma_f32_16x16x32_bf16 v[14:17], v[158:161], v[216:219], v[14:17]
	v_mfma_f32_16x16x32_bf16 v[10:13], v[166:169], v[216:219], v[10:13]
	v_mfma_f32_16x16x32_bf16 v[62:65], v[162:165], v[196:199], v[62:65]
	v_mfma_f32_16x16x32_bf16 v[58:61], v[170:173], v[196:199], v[58:61]
	v_mfma_f32_16x16x32_bf16 v[46:49], v[162:165], v[204:207], v[46:49]
	v_mfma_f32_16x16x32_bf16 v[42:45], v[170:173], v[204:207], v[42:45]
	v_mfma_f32_16x16x32_bf16 v[30:33], v[162:165], v[212:215], v[30:33]
	v_mfma_f32_16x16x32_bf16 v[26:29], v[170:173], v[212:215], v[26:29]
	v_mfma_f32_16x16x32_bf16 v[14:17], v[162:165], v[220:223], v[14:17]
	v_mfma_f32_16x16x32_bf16 v[10:13], v[170:173], v[220:223], v[10:13]
	s_setprio 0
	s_setprio 1
	v_mfma_f32_16x16x32_bf16 v[54:57], v[174:177], v[192:195], v[54:57]
	v_mfma_f32_16x16x32_bf16 v[50:53], v[182:185], v[192:195], v[50:53]
	v_mfma_f32_16x16x32_bf16 v[38:41], v[174:177], v[200:203], v[38:41]
	v_mfma_f32_16x16x32_bf16 v[34:37], v[182:185], v[200:203], v[34:37]
	v_mfma_f32_16x16x32_bf16 v[22:25], v[174:177], v[208:211], v[22:25]
	v_mfma_f32_16x16x32_bf16 v[18:21], v[182:185], v[208:211], v[18:21]
	v_mfma_f32_16x16x32_bf16 v[6:9], v[174:177], v[216:219], v[6:9]
	v_mfma_f32_16x16x32_bf16 v[2:5], v[182:185], v[216:219], v[2:5]
	v_mfma_f32_16x16x32_bf16 v[54:57], v[178:181], v[196:199], v[54:57]
	v_mfma_f32_16x16x32_bf16 v[50:53], v[186:189], v[196:199], v[50:53]
	v_mfma_f32_16x16x32_bf16 v[38:41], v[178:181], v[204:207], v[38:41]
	v_mfma_f32_16x16x32_bf16 v[34:37], v[186:189], v[204:207], v[34:37]
	v_mfma_f32_16x16x32_bf16 v[22:25], v[178:181], v[212:215], v[22:25]
	v_mfma_f32_16x16x32_bf16 v[18:21], v[186:189], v[212:215], v[18:21]
	v_mfma_f32_16x16x32_bf16 v[6:9], v[178:181], v[220:223], v[6:9]
	v_mfma_f32_16x16x32_bf16 v[2:5], v[186:189], v[220:223], v[2:5]
	s_setprio 0
	s_barrier
	s_add_i32 s54, 0, 0x18000
	v_add_u32_e32 v138, s54, v151
	s_add_i32 s55, 0, 0x1c000
	ds_read_b128 v[158:161], v138
	ds_read_b128 v[162:165], v138 offset:1024
	ds_read_b128 v[166:169], v138 offset:2048
	ds_read_b128 v[170:173], v138 offset:3072
	v_add_u32_e32 v138, s55, v151
	ds_read_b128 v[174:177], v138
	ds_read_b128 v[178:181], v138 offset:1024
	ds_read_b128 v[182:185], v138 offset:2048
	ds_read_b128 v[186:189], v138 offset:3072
	s_add_u32 s34, s34, 0x40000
	s_addc_u32 s35, s35, 0
	s_mov_b32 m0, s41
	v_lshl_add_u64 v[230:231], s[34:35], 0, v[130:131]
	ds_read_b128 v[192:195], v155 offset:32768
	ds_read_b128 v[196:199], v155 offset:33792
	ds_read_b128 v[200:203], v155 offset:34816
	ds_read_b128 v[204:207], v155 offset:35840
	ds_read_b128 v[208:211], v155 offset:36864
	ds_read_b128 v[212:215], v155 offset:37888
	ds_read_b128 v[216:219], v155 offset:38912
	ds_read_b128 v[220:223], v155 offset:39936
	global_load_lds_dwordx4 v[230:231], off
	v_lshl_add_u64 v[230:231], s[34:35], 0, v[134:135]
	s_mov_b32 m0, s42
	s_nop 0
	global_load_lds_dwordx4 v[230:231], off
	s_waitcnt vmcnt(8)
	s_waitcnt lgkmcnt(0)
	s_barrier
	s_setprio 1
	s_waitcnt lgkmcnt(0)
	v_mfma_f32_16x16x32_bf16 v[126:129], v[158:161], v[192:195], v[126:129]
	v_mfma_f32_16x16x32_bf16 v[122:125], v[166:169], v[192:195], v[122:125]
	v_mfma_f32_16x16x32_bf16 v[110:113], v[158:161], v[200:203], v[110:113]
	v_mfma_f32_16x16x32_bf16 v[106:109], v[166:169], v[200:203], v[106:109]
	v_mfma_f32_16x16x32_bf16 v[94:97], v[158:161], v[208:211], v[94:97]
	v_mfma_f32_16x16x32_bf16 v[90:93], v[166:169], v[208:211], v[90:93]
	v_mfma_f32_16x16x32_bf16 v[78:81], v[158:161], v[216:219], v[78:81]
	v_mfma_f32_16x16x32_bf16 v[74:77], v[166:169], v[216:219], v[74:77]
	v_mfma_f32_16x16x32_bf16 v[126:129], v[162:165], v[196:199], v[126:129]
	v_mfma_f32_16x16x32_bf16 v[122:125], v[170:173], v[196:199], v[122:125]
	v_mfma_f32_16x16x32_bf16 v[110:113], v[162:165], v[204:207], v[110:113]
	v_mfma_f32_16x16x32_bf16 v[106:109], v[170:173], v[204:207], v[106:109]
	v_mfma_f32_16x16x32_bf16 v[94:97], v[162:165], v[212:215], v[94:97]
	v_mfma_f32_16x16x32_bf16 v[90:93], v[170:173], v[212:215], v[90:93]
	v_mfma_f32_16x16x32_bf16 v[78:81], v[162:165], v[220:223], v[78:81]
	v_mfma_f32_16x16x32_bf16 v[74:77], v[170:173], v[220:223], v[74:77]
	s_setprio 0
	s_setprio 1
	v_mfma_f32_16x16x32_bf16 v[118:121], v[174:177], v[192:195], v[118:121]
	v_mfma_f32_16x16x32_bf16 v[114:117], v[182:185], v[192:195], v[114:117]
	v_mfma_f32_16x16x32_bf16 v[102:105], v[174:177], v[200:203], v[102:105]
	v_mfma_f32_16x16x32_bf16 v[98:101], v[182:185], v[200:203], v[98:101]
	v_mfma_f32_16x16x32_bf16 v[86:89], v[174:177], v[208:211], v[86:89]
	v_mfma_f32_16x16x32_bf16 v[82:85], v[182:185], v[208:211], v[82:85]
	v_mfma_f32_16x16x32_bf16 v[70:73], v[174:177], v[216:219], v[70:73]
	v_mfma_f32_16x16x32_bf16 v[66:69], v[182:185], v[216:219], v[66:69]
	v_mfma_f32_16x16x32_bf16 v[118:121], v[178:181], v[196:199], v[118:121]
	v_mfma_f32_16x16x32_bf16 v[114:117], v[186:189], v[196:199], v[114:117]
	v_mfma_f32_16x16x32_bf16 v[102:105], v[178:181], v[204:207], v[102:105]
	v_mfma_f32_16x16x32_bf16 v[98:101], v[186:189], v[204:207], v[98:101]
	v_mfma_f32_16x16x32_bf16 v[86:89], v[178:181], v[212:215], v[86:89]
	v_mfma_f32_16x16x32_bf16 v[82:85], v[186:189], v[212:215], v[82:85]
	v_mfma_f32_16x16x32_bf16 v[70:73], v[178:181], v[220:223], v[70:73]
	v_mfma_f32_16x16x32_bf16 v[66:69], v[186:189], v[220:223], v[66:69]
	s_setprio 0
	s_barrier
; #define PG8_STAGE(bufoff, gbase, voff) do { _Pragma("unroll") for (int _i = 0; _i < 2; ++_i) \
;         __builtin_amdgcn_global_load_lds((const unsigned*)((const char*)(gbase) + (voff)[_i]), (PG8_LAS unsigned*)(lds + (bufoff) + ldsw + _i * 8192), 16, 0, 0); } while (0)
; #define PG8_STAGEB(bufoff, gbase, voff) do { _Pragma("unroll") for (int _i = 0; _i < 2; ++_i) \
;         __builtin_amdgcn_global_load_lds((const unsigned*)((const char*)(gbase) + (voff)[_i]), (PG8_LAS unsigned*)(lds + (bufoff) + ldsw + _i * 8192), 16, 0, PG8_BAUX); } while (0)
; #define PG8_LDA(dst, b, h) do { _Pragma("unroll") for (int m = 0; m < 4; ++m) _Pragma("unroll") for (int k = 0; k < 2; ++k) dst[m][k] = *(const PG8_LAS bf16x8*)(lds + PG8_SA(b, h) + aoff + m * 2048 + k * 1024); } while (0)
; #define PG8_MMA(ai, bj, At, Bt) do { __builtin_amdgcn_s_setprio(1); _Pragma("unroll") for (int m = 0; m < 4; ++m) _Pragma("unroll") for (int n = 0; n < 2; ++n) _Pragma("unroll") for (int k = 0; k < 2; ++k) \
;         acc[ai][bj][m][n] = __builtin_amdgcn_mfma_f32_16x16x32_bf16(Bt[n][k], At[m][k], acc[ai][bj][m][n], 0, 0, 0); __builtin_amdgcn_s_setprio(0); } while (0)
; #define PG8_WAIT_V(n) asm volatile("s_waitcnt vmcnt(" #n ")" ::: "memory")
; #define PG8_WAIT_L(n) asm volatile("s_waitcnt lgkmcnt(" #n ")" ::: "memory")
; #define PG8_BAR __builtin_amdgcn_s_barrier()
; #define PG8_SCHED __builtin_amdgcn_sched_barrier(0)
; template <class Epi, class Sched, bool ALIGN_EPI = false, bool SP2 = false>
; __device__ __forceinline__ void gemm_phase(PG8_LAS unsigned char* lds, const Gemm g, const Sched& S, const Epi& E) {
;     ...
;         for (int t = 0; t < nt; t += 2) {
;     ...
;             PG8_LDA(At, 1, 1); PG8_STAGEB(PG8_SB(1, 0), b3, voffB); PG8_STAGEB(PG8_SB(1, 1), b3 + hstep, voffB); PG8_STAGE(PG8_SA(1, 0), a3, voffA);
;             PG8_WAIT_V(8); PG8_WAIT_L(0); PG8_BAR; PG8_MMA(1, 0, At, B0); PG8_MMA(1, 1, At, B1); PG8_BAR; PG8_SCHED;
	s_add_i32 s34, s54, s39
	v_lshl_add_u64 v[148:149], v[148:149], 0, s[12:13]
	s_mov_b32 m0, s34
	ds_read_b128 v[192:195], v155 offset:49152
	ds_read_b128 v[196:199], v155 offset:50176
	ds_read_b128 v[200:203], v155 offset:51200
	ds_read_b128 v[204:207], v155 offset:52224
	ds_read_b128 v[208:211], v155 offset:53248
	ds_read_b128 v[212:215], v155 offset:54272
	ds_read_b128 v[216:219], v155 offset:55296
	ds_read_b128 v[220:223], v155 offset:56320
	global_load_lds_dwordx4 v[148:149], off
	s_add_i32 m0, s34, 0x2000
	s_add_u32 s30, s30, 0x40080
	v_lshl_add_u64 v[148:149], v[224:225], 0, s[12:13]
	s_addc_u32 s31, s31, 0
	s_add_i32 s34, s55, s39
	global_load_lds_dwordx4 v[148:149], off
	v_lshl_add_u64 v[148:149], s[30:31], 0, v[132:133]
	s_mov_b32 m0, s34
	s_nop 0
	global_load_lds_dwordx4 v[148:149], off
	v_lshl_add_u64 v[148:149], s[30:31], 0, v[136:137]
	s_add_i32 m0, s34, 0x2000
	s_nop 0
	global_load_lds_dwordx4 v[148:149], off
	v_lshl_add_u64 v[148:149], v[226:227], 0, s[12:13]
	s_mov_b32 m0, s44
	s_nop 0
	global_load_lds_dwordx4 v[148:149], off
	v_lshl_add_u64 v[148:149], v[228:229], 0, s[12:13]
	s_mov_b32 m0, s45
	s_nop 0
	global_load_lds_dwordx4 v[148:149], off
	s_waitcnt vmcnt(8)
	s_waitcnt lgkmcnt(0)
	s_barrier
	s_setprio 1
	s_waitcnt lgkmcnt(0)
	v_mfma_f32_16x16x32_bf16 v[62:65], v[158:161], v[192:195], v[62:65]
	v_mfma_f32_16x16x32_bf16 v[58:61], v[166:169], v[192:195], v[58:61]
	v_mfma_f32_16x16x32_bf16 v[46:49], v[158:161], v[200:203], v[46:49]
	v_mfma_f32_16x16x32_bf16 v[42:45], v[166:169], v[200:203], v[42:45]
	v_mfma_f32_16x16x32_bf16 v[30:33], v[158:161], v[208:211], v[30:33]
	v_mfma_f32_16x16x32_bf16 v[26:29], v[166:169], v[208:211], v[26:29]
	v_mfma_f32_16x16x32_bf16 v[14:17], v[158:161], v[216:219], v[14:17]
	v_mfma_f32_16x16x32_bf16 v[10:13], v[166:169], v[216:219], v[10:13]
	v_mfma_f32_16x16x32_bf16 v[62:65], v[162:165], v[196:199], v[62:65]
	v_mfma_f32_16x16x32_bf16 v[58:61], v[170:173], v[196:199], v[58:61]
	v_mfma_f32_16x16x32_bf16 v[46:49], v[162:165], v[204:207], v[46:49]
	v_mfma_f32_16x16x32_bf16 v[42:45], v[170:173], v[204:207], v[42:45]
	v_mfma_f32_16x16x32_bf16 v[30:33], v[162:165], v[212:215], v[30:33]
	v_mfma_f32_16x16x32_bf16 v[26:29], v[170:173], v[212:215], v[26:29]
	v_mfma_f32_16x16x32_bf16 v[14:17], v[162:165], v[220:223], v[14:17]
	v_mfma_f32_16x16x32_bf16 v[10:13], v[170:173], v[220:223], v[10:13]
	s_setprio 0
	s_setprio 1
	v_mfma_f32_16x16x32_bf16 v[54:57], v[174:177], v[192:195], v[54:57]
	v_mfma_f32_16x16x32_bf16 v[50:53], v[182:185], v[192:195], v[50:53]
	v_mfma_f32_16x16x32_bf16 v[38:41], v[174:177], v[200:203], v[38:41]
	v_mfma_f32_16x16x32_bf16 v[34:37], v[182:185], v[200:203], v[34:37]
	v_mfma_f32_16x16x32_bf16 v[22:25], v[174:177], v[208:211], v[22:25]
	v_mfma_f32_16x16x32_bf16 v[18:21], v[182:185], v[208:211], v[18:21]
	v_mfma_f32_16x16x32_bf16 v[6:9], v[174:177], v[216:219], v[6:9]
	v_mfma_f32_16x16x32_bf16 v[2:5], v[182:185], v[216:219], v[2:5]
	v_mfma_f32_16x16x32_bf16 v[54:57], v[178:181], v[196:199], v[54:57]
	v_mfma_f32_16x16x32_bf16 v[50:53], v[186:189], v[196:199], v[50:53]
	v_mfma_f32_16x16x32_bf16 v[38:41], v[178:181], v[204:207], v[38:41]
	v_mfma_f32_16x16x32_bf16 v[34:37], v[186:189], v[204:207], v[34:37]
	v_mfma_f32_16x16x32_bf16 v[22:25], v[178:181], v[212:215], v[22:25]
	v_mfma_f32_16x16x32_bf16 v[18:21], v[186:189], v[212:215], v[18:21]
	v_mfma_f32_16x16x32_bf16 v[6:9], v[178:181], v[220:223], v[6:9]
	v_mfma_f32_16x16x32_bf16 v[2:5], v[186:189], v[220:223], v[2:5]
	s_setprio 0
	s_add_i32 s53, s53, 2
	s_add_u32 s28, s28, 0x100
	s_addc_u32 s29, s29, 0
	s_add_u32 s51, s51, 0x100
	s_addc_u32 s52, s52, 0
	s_cmp_gt_u32 s53, 13
	s_barrier
	s_cbranch_scc0 .LBB0_1604
	s_and_b64 vcc, exec, s[14:15]
	s_cbranch_vccz .LBB0_1607
	s_barrier

; #define PG8_STAGE(bufoff, gbase, voff) do { _Pragma("unroll") for (int _i = 0; _i < 2; ++_i) \
;         __builtin_amdgcn_global_load_lds((const unsigned*)((const char*)(gbase) + (voff)[_i]), (PG8_LAS unsigned*)(lds + (bufoff) + ldsw + _i * 8192), 16, 0, 0); } while (0)
; #define PG8_STAGEB(bufoff, gbase, voff) do { _Pragma("unroll") for (int _i = 0; _i < 2; ++_i) \
;         __builtin_amdgcn_global_load_lds((const unsigned*)((const char*)(gbase) + (voff)[_i]), (PG8_LAS unsigned*)(lds + (bufoff) + ldsw + _i * 8192), 16, 0, PG8_BAUX); } while (0)
; #define PG8_LDA(dst, b, h) do { _Pragma("unroll") for (int m = 0; m < 4; ++m) _Pragma("unroll") for (int k = 0; k < 2; ++k) dst[m][k] = *(const PG8_LAS bf16x8*)(lds + PG8_SA(b, h) + aoff + m * 2048 + k * 1024); } while (0)
; #define PG8_LDB(dst, b, h) do { _Pragma("unroll") for (int n = 0; n < 2; ++n) _Pragma("unroll") for (int k = 0; k < 2; ++k) dst[n][k] = *(const PG8_LAS bf16x8*)(lds + PG8_SB(b, h) + boff + n * 2048 + k * 1024); } while (0)
; #define PG8_MMA(ai, bj, At, Bt) do { __builtin_amdgcn_s_setprio(1); _Pragma("unroll") for (int m = 0; m < 4; ++m) _Pragma("unroll") for (int n = 0; n < 2; ++n) _Pragma("unroll") for (int k = 0; k < 2; ++k) \
;         acc[ai][bj][m][n] = __builtin_amdgcn_mfma_f32_16x16x32_bf16(Bt[n][k], At[m][k], acc[ai][bj][m][n], 0, 0, 0); __builtin_amdgcn_s_setprio(0); } while (0)
; template <class Epi, class Sched, bool ALIGN_EPI = false, bool SP2 = false>
; __device__ __forceinline__ void gemm_phase(PG8_LAS unsigned char* lds, const Gemm g, const Sched& S, const Epi& E) {
;     ...
;             const bool last = (t == nt - 2);
;             const char* a1 = cA + (size_t)(t + 1) * kstep;
;             const char* a2 = last ? nA : cA + (size_t)(t + 2) * kstep; const char* b2 = last ? nB : cB + (size_t)(t + 2) * kstep;
;             const char* a3 = a2 + kstep; const char* b3 = b2 + kstep;
;             if (last && has_next) S.a_ready(nxt);
;             if constexpr (SP2) {
;             PG8_LDB(B0, 0, 0); PG8_LDB(B1, 0, 1); PG8_SCHED; PG8_LDA(At, 0, 0); PG8_STAGE(PG8_SA(1, 1), a1 + hstep, voffA);
;             PG8_WAIT_V(8); PG8_WAIT_L(0); PG8_BAR; PG8_MMA(0, 0, At, B0); PG8_MMA(0, 1, At, B1); PG8_BAR; PG8_SCHED;
;             PG8_LDA(At, 0, 1); PG8_STAGEB(PG8_SB(0, 0), b2, voffB); PG8_STAGEB(PG8_SB(0, 1), b2 + hstep, voffB); PG8_STAGE(PG8_SA(0, 0), a2, voffA);
.LBB0_1703:
	ds_read_b128 v[154:157], v150
	ds_read_b128 v[158:161], v150 offset:1024
	ds_read_b128 v[162:165], v150 offset:2048
	ds_read_b128 v[166:169], v150 offset:3072
	ds_read_b128 v[170:173], v151
	ds_read_b128 v[174:177], v151 offset:1024
	ds_read_b128 v[178:181], v151 offset:2048
	ds_read_b128 v[182:185], v151 offset:3072
	s_add_u32 s24, s22, 0xfff80080
	s_addc_u32 s25, s23, -1
	s_cmp_eq_u32 s51, 28
	s_cselect_b32 s27, s15, s25
	s_cselect_b32 s26, s47, s24
	s_cselect_b32 s25, s13, s50
	s_cselect_b32 s24, s48, s49
	v_lshl_add_u64 v[220:221], s[22:23], 0, v[138:139]
	s_add_i32 m0, s21, 0xc000
	ds_read_b128 v[186:189], v152
	ds_read_b128 v[192:195], v152 offset:1024
	ds_read_b128 v[196:199], v152 offset:2048
	ds_read_b128 v[200:203], v152 offset:3072
	ds_read_b128 v[204:207], v152 offset:4096
	ds_read_b128 v[208:211], v152 offset:5120
	ds_read_b128 v[212:215], v152 offset:6144
	ds_read_b128 v[216:219], v152 offset:7168
	global_load_lds_dwordx4 v[220:221], off
	v_lshl_add_u64 v[220:221], s[22:23], 0, v[140:141]
	s_add_i32 m0, s21, 0xe000
	s_nop 0
	global_load_lds_dwordx4 v[220:221], off
	s_waitcnt vmcnt(8)
	s_waitcnt lgkmcnt(0)
	s_barrier
	s_setprio 1
	s_waitcnt lgkmcnt(0)
	v_mfma_f32_16x16x32_bf16 v[126:129], v[154:157], v[186:189], v[126:129]
	v_mfma_f32_16x16x32_bf16 v[118:121], v[162:165], v[186:189], v[118:121]
	v_mfma_f32_16x16x32_bf16 v[110:113], v[154:157], v[196:199], v[110:113]
	v_mfma_f32_16x16x32_bf16 v[102:105], v[162:165], v[196:199], v[102:105]
	v_mfma_f32_16x16x32_bf16 v[94:97], v[154:157], v[204:207], v[94:97]
	v_mfma_f32_16x16x32_bf16 v[86:89], v[162:165], v[204:207], v[86:89]
	v_mfma_f32_16x16x32_bf16 v[78:81], v[154:157], v[212:215], v[78:81]
	v_mfma_f32_16x16x32_bf16 v[70:73], v[162:165], v[212:215], v[70:73]
	v_mfma_f32_16x16x32_bf16 v[126:129], v[158:161], v[192:195], v[126:129]
	v_mfma_f32_16x16x32_bf16 v[118:121], v[166:169], v[192:195], v[118:121]
	v_mfma_f32_16x16x32_bf16 v[110:113], v[158:161], v[200:203], v[110:113]
	v_mfma_f32_16x16x32_bf16 v[102:105], v[166:169], v[200:203], v[102:105]
	v_mfma_f32_16x16x32_bf16 v[94:97], v[158:161], v[208:211], v[94:97]
	v_mfma_f32_16x16x32_bf16 v[86:89], v[166:169], v[208:211], v[86:89]
	v_mfma_f32_16x16x32_bf16 v[78:81], v[158:161], v[216:219], v[78:81]
	v_mfma_f32_16x16x32_bf16 v[70:73], v[166:169], v[216:219], v[70:73]
	s_setprio 0
	s_setprio 1
	v_mfma_f32_16x16x32_bf16 v[122:125], v[170:173], v[186:189], v[122:125]
	v_mfma_f32_16x16x32_bf16 v[114:117], v[178:181], v[186:189], v[114:117]
	v_mfma_f32_16x16x32_bf16 v[106:109], v[170:173], v[196:199], v[106:109]
	v_mfma_f32_16x16x32_bf16 v[98:101], v[178:181], v[196:199], v[98:101]
	v_mfma_f32_16x16x32_bf16 v[90:93], v[170:173], v[204:207], v[90:93]
	v_mfma_f32_16x16x32_bf16 v[82:85], v[178:181], v[204:207], v[82:85]
	v_mfma_f32_16x16x32_bf16 v[74:77], v[170:173], v[212:215], v[74:77]
	v_mfma_f32_16x16x32_bf16 v[66:69], v[178:181], v[212:215], v[66:69]
	v_mfma_f32_16x16x32_bf16 v[122:125], v[174:177], v[192:195], v[122:125]
	v_mfma_f32_16x16x32_bf16 v[114:117], v[182:185], v[192:195], v[114:117]
	v_mfma_f32_16x16x32_bf16 v[106:109], v[174:177], v[200:203], v[106:109]
	v_mfma_f32_16x16x32_bf16 v[98:101], v[182:185], v[200:203], v[98:101]
	v_mfma_f32_16x16x32_bf16 v[90:93], v[174:177], v[208:211], v[90:93]
	v_mfma_f32_16x16x32_bf16 v[82:85], v[182:185], v[208:211], v[82:85]
	v_mfma_f32_16x16x32_bf16 v[74:77], v[174:177], v[216:219], v[74:77]
	v_mfma_f32_16x16x32_bf16 v[66:69], v[182:185], v[216:219], v[66:69]
	s_setprio 0
	s_barrier
	s_add_i32 s52, s43, s28
	v_lshl_add_u64 v[220:221], s[24:25], 0, v[134:135]
	s_mov_b32 m0, s52
	ds_read_b128 v[186:189], v152 offset:16384
	ds_read_b128 v[192:195], v152 offset:17408
	ds_read_b128 v[196:199], v152 offset:18432
	ds_read_b128 v[200:203], v152 offset:19456
	ds_read_b128 v[204:207], v152 offset:20480
	ds_read_b128 v[208:211], v152 offset:21504
	ds_read_b128 v[212:215], v152 offset:22528
	ds_read_b128 v[216:219], v152 offset:23552
	global_load_lds_dwordx4 v[220:221], off
	s_add_i32 m0, s52, 0x2000
	s_add_u32 s52, s24, 0x80000
	v_lshl_add_u64 v[222:223], s[24:25], 0, v[130:131]
	s_addc_u32 s53, s25, 0
	s_add_i32 s54, s44, s28
	global_load_lds_dwordx4 v[222:223], off
	v_lshl_add_u64 v[224:225], s[52:53], 0, v[134:135]
	s_mov_b32 m0, s54
	v_lshl_add_u64 v[226:227], s[26:27], 0, v[132:133]
	global_load_lds_dwordx4 v[224:225], off
	v_lshl_add_u64 v[224:225], s[52:53], 0, v[130:131]
	s_add_i32 m0, s54, 0x2000
	s_nop 0
	global_load_lds_dwordx4 v[224:225], off
	v_lshl_add_u64 v[224:225], s[26:27], 0, v[136:137]
	s_mov_b32 m0, s21
	s_nop 0
	global_load_lds_dwordx4 v[224:225], off
	s_mov_b32 m0, s34
	s_nop 0
	global_load_lds_dwordx4 v[226:227], off
	s_waitcnt vmcnt(8)
	s_waitcnt lgkmcnt(0)
	s_barrier
; #define PG8_STAGE(bufoff, gbase, voff) do { _Pragma("unroll") for (int _i = 0; _i < 2; ++_i) \
;         __builtin_amdgcn_global_load_lds((const unsigned*)((const char*)(gbase) + (voff)[_i]), (PG8_LAS unsigned*)(lds + (bufoff) + ldsw + _i * 8192), 16, 0, 0); } while (0)
; #define PG8_LDA(dst, b, h) do { _Pragma("unroll") for (int m = 0; m < 4; ++m) _Pragma("unroll") for (int k = 0; k < 2; ++k) dst[m][k] = *(const PG8_LAS bf16x8*)(lds + PG8_SA(b, h) + aoff + m * 2048 + k * 1024); } while (0)
; #define PG8_LDB(dst, b, h) do { _Pragma("unroll") for (int n = 0; n < 2; ++n) _Pragma("unroll") for (int k = 0; k < 2; ++k) dst[n][k] = *(const PG8_LAS bf16x8*)(lds + PG8_SB(b, h) + boff + n * 2048 + k * 1024); } while (0)
; #define PG8_MMA(ai, bj, At, Bt) do { __builtin_amdgcn_s_setprio(1); _Pragma("unroll") for (int m = 0; m < 4; ++m) _Pragma("unroll") for (int n = 0; n < 2; ++n) _Pragma("unroll") for (int k = 0; k < 2; ++k) \
;         acc[ai][bj][m][n] = __builtin_amdgcn_mfma_f32_16x16x32_bf16(Bt[n][k], At[m][k], acc[ai][bj][m][n], 0, 0, 0); __builtin_amdgcn_s_setprio(0); } while (0)
; #define PG8_WAIT_V(n) asm volatile("s_waitcnt vmcnt(" #n ")" ::: "memory")
; #define PG8_WAIT_L(n) asm volatile("s_waitcnt lgkmcnt(" #n ")" ::: "memory")
; #define PG8_BAR __builtin_amdgcn_s_barrier()
; #define PG8_SCHED __builtin_amdgcn_sched_barrier(0)
; template <class Epi, class Sched, bool ALIGN_EPI = false, bool SP2 = false>
; __device__ __forceinline__ void gemm_phase(PG8_LAS unsigned char* lds, const Gemm g, const Sched& S, const Epi& E) {
;     ...
;             PG8_WAIT_V(8); PG8_WAIT_L(0); PG8_BAR; PG8_MMA(1, 0, At, B0); PG8_MMA(1, 1, At, B1); PG8_BAR; PG8_SCHED;
;             PG8_LDB(B0, 1, 0); PG8_LDB(B1, 1, 1); PG8_SCHED; PG8_LDA(At, 1, 0); PG8_STAGE(PG8_SA(0, 1), a2 + hstep, voffA);
;             PG8_WAIT_V(8); PG8_WAIT_L(0); PG8_BAR; PG8_MMA(0, 0, At, B0); PG8_MMA(0, 1, At, B1); PG8_BAR; PG8_SCHED;
	s_setprio 1
	s_waitcnt lgkmcnt(0)
	v_mfma_f32_16x16x32_bf16 v[62:65], v[154:157], v[186:189], v[62:65]
	v_mfma_f32_16x16x32_bf16 v[54:57], v[162:165], v[186:189], v[54:57]
	v_mfma_f32_16x16x32_bf16 v[46:49], v[154:157], v[196:199], v[46:49]
	v_mfma_f32_16x16x32_bf16 v[38:41], v[162:165], v[196:199], v[38:41]
	v_mfma_f32_16x16x32_bf16 v[30:33], v[154:157], v[204:207], v[30:33]
	v_mfma_f32_16x16x32_bf16 v[22:25], v[162:165], v[204:207], v[22:25]
	v_mfma_f32_16x16x32_bf16 v[14:17], v[154:157], v[212:215], v[14:17]
	v_mfma_f32_16x16x32_bf16 v[6:9], v[162:165], v[212:215], v[6:9]
	v_mfma_f32_16x16x32_bf16 v[62:65], v[158:161], v[192:195], v[62:65]
	v_mfma_f32_16x16x32_bf16 v[54:57], v[166:169], v[192:195], v[54:57]
	v_mfma_f32_16x16x32_bf16 v[46:49], v[158:161], v[200:203], v[46:49]
	v_mfma_f32_16x16x32_bf16 v[38:41], v[166:169], v[200:203], v[38:41]
	v_mfma_f32_16x16x32_bf16 v[30:33], v[158:161], v[208:211], v[30:33]
	v_mfma_f32_16x16x32_bf16 v[22:25], v[166:169], v[208:211], v[22:25]
	v_mfma_f32_16x16x32_bf16 v[14:17], v[158:161], v[216:219], v[14:17]
	v_mfma_f32_16x16x32_bf16 v[6:9], v[166:169], v[216:219], v[6:9]
	s_setprio 0
	s_setprio 1
	v_mfma_f32_16x16x32_bf16 v[58:61], v[170:173], v[186:189], v[58:61]
	v_mfma_f32_16x16x32_bf16 v[50:53], v[178:181], v[186:189], v[50:53]
	v_mfma_f32_16x16x32_bf16 v[42:45], v[170:173], v[196:199], v[42:45]
	v_mfma_f32_16x16x32_bf16 v[34:37], v[178:181], v[196:199], v[34:37]
	v_mfma_f32_16x16x32_bf16 v[26:29], v[170:173], v[204:207], v[26:29]
	v_mfma_f32_16x16x32_bf16 v[18:21], v[178:181], v[204:207], v[18:21]
	v_mfma_f32_16x16x32_bf16 v[10:13], v[170:173], v[212:215], v[10:13]
	v_mfma_f32_16x16x32_bf16 v[2:5], v[178:181], v[212:215], v[2:5]
	v_mfma_f32_16x16x32_bf16 v[58:61], v[174:177], v[192:195], v[58:61]
	v_mfma_f32_16x16x32_bf16 v[50:53], v[182:185], v[192:195], v[50:53]
	v_mfma_f32_16x16x32_bf16 v[42:45], v[174:177], v[200:203], v[42:45]
	v_mfma_f32_16x16x32_bf16 v[34:37], v[182:185], v[200:203], v[34:37]
	v_mfma_f32_16x16x32_bf16 v[26:29], v[174:177], v[208:211], v[26:29]
	v_mfma_f32_16x16x32_bf16 v[18:21], v[182:185], v[208:211], v[18:21]
	v_mfma_f32_16x16x32_bf16 v[10:13], v[174:177], v[216:219], v[10:13]
	v_mfma_f32_16x16x32_bf16 v[2:5], v[182:185], v[216:219], v[2:5]
	s_setprio 0
	s_barrier
	s_add_i32 s52, 0, 0x18000
	v_add_u32_e32 v153, s52, v147
	s_add_i32 s53, 0, 0x1c000
	ds_read_b128 v[154:157], v153
	ds_read_b128 v[158:161], v153 offset:1024
	ds_read_b128 v[162:165], v153 offset:2048
	ds_read_b128 v[166:169], v153 offset:3072
	v_add_u32_e32 v153, s53, v147
	ds_read_b128 v[170:173], v153
	ds_read_b128 v[174:177], v153 offset:1024
	ds_read_b128 v[178:181], v153 offset:2048
	ds_read_b128 v[182:185], v153 offset:3072
	s_add_u32 s26, s26, 0x80000
	s_addc_u32 s27, s27, 0
	s_mov_b32 m0, s35
	v_lshl_add_u64 v[228:229], s[26:27], 0, v[136:137]
	ds_read_b128 v[186:189], v152 offset:32768
	ds_read_b128 v[192:195], v152 offset:33792
	ds_read_b128 v[196:199], v152 offset:34816
	ds_read_b128 v[200:203], v152 offset:35840
	ds_read_b128 v[204:207], v152 offset:36864
	ds_read_b128 v[208:211], v152 offset:37888
	ds_read_b128 v[212:215], v152 offset:38912
	ds_read_b128 v[216:219], v152 offset:39936
	global_load_lds_dwordx4 v[228:229], off
	v_lshl_add_u64 v[228:229], s[26:27], 0, v[132:133]
	s_mov_b32 m0, s38
	s_nop 0
	global_load_lds_dwordx4 v[228:229], off
	s_waitcnt vmcnt(8)
	s_waitcnt lgkmcnt(0)
	s_barrier
	s_setprio 1
	s_waitcnt lgkmcnt(0)
	v_mfma_f32_16x16x32_bf16 v[126:129], v[154:157], v[186:189], v[126:129]
	v_mfma_f32_16x16x32_bf16 v[118:121], v[162:165], v[186:189], v[118:121]
	v_mfma_f32_16x16x32_bf16 v[110:113], v[154:157], v[196:199], v[110:113]
	v_mfma_f32_16x16x32_bf16 v[102:105], v[162:165], v[196:199], v[102:105]
	v_mfma_f32_16x16x32_bf16 v[94:97], v[154:157], v[204:207], v[94:97]
	v_mfma_f32_16x16x32_bf16 v[86:89], v[162:165], v[204:207], v[86:89]
	v_mfma_f32_16x16x32_bf16 v[78:81], v[154:157], v[212:215], v[78:81]
	v_mfma_f32_16x16x32_bf16 v[70:73], v[162:165], v[212:215], v[70:73]
	v_mfma_f32_16x16x32_bf16 v[126:129], v[158:161], v[192:195], v[126:129]
	v_mfma_f32_16x16x32_bf16 v[118:121], v[166:169], v[192:195], v[118:121]
	v_mfma_f32_16x16x32_bf16 v[110:113], v[158:161], v[200:203], v[110:113]
	v_mfma_f32_16x16x32_bf16 v[102:105], v[166:169], v[200:203], v[102:105]
	v_mfma_f32_16x16x32_bf16 v[94:97], v[158:161], v[208:211], v[94:97]
	v_mfma_f32_16x16x32_bf16 v[86:89], v[166:169], v[208:211], v[86:89]
	v_mfma_f32_16x16x32_bf16 v[78:81], v[158:161], v[216:219], v[78:81]
	v_mfma_f32_16x16x32_bf16 v[70:73], v[166:169], v[216:219], v[70:73]
	s_setprio 0
	s_setprio 1
	v_mfma_f32_16x16x32_bf16 v[122:125], v[170:173], v[186:189], v[122:125]
	v_mfma_f32_16x16x32_bf16 v[114:117], v[178:181], v[186:189], v[114:117]
	v_mfma_f32_16x16x32_bf16 v[106:109], v[170:173], v[196:199], v[106:109]
	v_mfma_f32_16x16x32_bf16 v[98:101], v[178:181], v[196:199], v[98:101]
	v_mfma_f32_16x16x32_bf16 v[90:93], v[170:173], v[204:207], v[90:93]
	v_mfma_f32_16x16x32_bf16 v[82:85], v[178:181], v[204:207], v[82:85]
	v_mfma_f32_16x16x32_bf16 v[74:77], v[170:173], v[212:215], v[74:77]
	v_mfma_f32_16x16x32_bf16 v[66:69], v[178:181], v[212:215], v[66:69]
	v_mfma_f32_16x16x32_bf16 v[122:125], v[174:177], v[192:195], v[122:125]
	v_mfma_f32_16x16x32_bf16 v[114:117], v[182:185], v[192:195], v[114:117]
	v_mfma_f32_16x16x32_bf16 v[106:109], v[174:177], v[200:203], v[106:109]
	v_mfma_f32_16x16x32_bf16 v[98:101], v[182:185], v[200:203], v[98:101]
	v_mfma_f32_16x16x32_bf16 v[90:93], v[174:177], v[208:211], v[90:93]
	v_mfma_f32_16x16x32_bf16 v[82:85], v[182:185], v[208:211], v[82:85]
	v_mfma_f32_16x16x32_bf16 v[74:77], v[174:177], v[216:219], v[74:77]
	v_mfma_f32_16x16x32_bf16 v[66:69], v[182:185], v[216:219], v[66:69]
	s_setprio 0
	s_barrier
; #define PG8_STAGE(bufoff, gbase, voff) do { _Pragma("unroll") for (int _i = 0; _i < 2; ++_i) \
;         __builtin_amdgcn_global_load_lds((const unsigned*)((const char*)(gbase) + (voff)[_i]), (PG8_LAS unsigned*)(lds + (bufoff) + ldsw + _i * 8192), 16, 0, 0); } while (0)
; #define PG8_STAGEB(bufoff, gbase, voff) do { _Pragma("unroll") for (int _i = 0; _i < 2; ++_i) \
;         __builtin_amdgcn_global_load_lds((const unsigned*)((const char*)(gbase) + (voff)[_i]), (PG8_LAS unsigned*)(lds + (bufoff) + ldsw + _i * 8192), 16, 0, PG8_BAUX); } while (0)
; #define PG8_LDA(dst, b, h) do { _Pragma("unroll") for (int m = 0; m < 4; ++m) _Pragma("unroll") for (int k = 0; k < 2; ++k) dst[m][k] = *(const PG8_LAS bf16x8*)(lds + PG8_SA(b, h) + aoff + m * 2048 + k * 1024); } while (0)
; #define PG8_MMA(ai, bj, At, Bt) do { __builtin_amdgcn_s_setprio(1); _Pragma("unroll") for (int m = 0; m < 4; ++m) _Pragma("unroll") for (int n = 0; n < 2; ++n) _Pragma("unroll") for (int k = 0; k < 2; ++k) \
;         acc[ai][bj][m][n] = __builtin_amdgcn_mfma_f32_16x16x32_bf16(Bt[n][k], At[m][k], acc[ai][bj][m][n], 0, 0, 0); __builtin_amdgcn_s_setprio(0); } while (0)
; #define PG8_WAIT_V(n) asm volatile("s_waitcnt vmcnt(" #n ")" ::: "memory")
; #define PG8_WAIT_L(n) asm volatile("s_waitcnt lgkmcnt(" #n ")" ::: "memory")
; #define PG8_BAR __builtin_amdgcn_s_barrier()
; #define PG8_SCHED __builtin_amdgcn_sched_barrier(0)
; template <class Epi, class Sched, bool ALIGN_EPI = false, bool SP2 = false>
; __device__ __forceinline__ void gemm_phase(PG8_LAS unsigned char* lds, const Gemm g, const Sched& S, const Epi& E) {
;     ...
;         for (int t = 0; t < nt; t += 2) {
;     ...
;             PG8_LDA(At, 1, 1); PG8_STAGEB(PG8_SB(1, 0), b3, voffB); PG8_STAGEB(PG8_SB(1, 1), b3 + hstep, voffB); PG8_STAGE(PG8_SA(1, 0), a3, voffA);
;             PG8_WAIT_V(8); PG8_WAIT_L(0); PG8_BAR; PG8_MMA(1, 0, At, B0); PG8_MMA(1, 1, At, B1); PG8_BAR; PG8_SCHED;
	s_add_i32 s26, s52, s28
	v_lshl_add_u64 v[220:221], v[220:221], 0, s[8:9]
	s_mov_b32 m0, s26
	ds_read_b128 v[186:189], v152 offset:49152
	ds_read_b128 v[192:195], v152 offset:50176
	ds_read_b128 v[196:199], v152 offset:51200
	ds_read_b128 v[200:203], v152 offset:52224
	ds_read_b128 v[204:207], v152 offset:53248
	ds_read_b128 v[208:211], v152 offset:54272
	ds_read_b128 v[212:215], v152 offset:55296
	ds_read_b128 v[216:219], v152 offset:56320
	global_load_lds_dwordx4 v[220:221], off
	s_add_i32 m0, s26, 0x2000
	s_add_u32 s24, s24, 0x80080
	v_lshl_add_u64 v[220:221], v[222:223], 0, s[8:9]
	s_addc_u32 s25, s25, 0
	s_add_i32 s26, s53, s28
	global_load_lds_dwordx4 v[220:221], off
	v_lshl_add_u64 v[220:221], s[24:25], 0, v[134:135]
	s_mov_b32 m0, s26
	s_nop 0
	global_load_lds_dwordx4 v[220:221], off
	v_lshl_add_u64 v[220:221], s[24:25], 0, v[130:131]
	s_add_i32 m0, s26, 0x2000
	s_nop 0
	global_load_lds_dwordx4 v[220:221], off
	v_lshl_add_u64 v[220:221], v[224:225], 0, s[8:9]
	s_mov_b32 m0, s40
	s_nop 0
	global_load_lds_dwordx4 v[220:221], off
	v_lshl_add_u64 v[220:221], v[226:227], 0, s[8:9]
	s_mov_b32 m0, s41
	s_nop 0
	global_load_lds_dwordx4 v[220:221], off
	s_waitcnt vmcnt(8)
	s_waitcnt lgkmcnt(0)
	s_barrier
	s_setprio 1
	s_waitcnt lgkmcnt(0)
	v_mfma_f32_16x16x32_bf16 v[62:65], v[154:157], v[186:189], v[62:65]
	v_mfma_f32_16x16x32_bf16 v[54:57], v[162:165], v[186:189], v[54:57]
	v_mfma_f32_16x16x32_bf16 v[46:49], v[154:157], v[196:199], v[46:49]
	v_mfma_f32_16x16x32_bf16 v[38:41], v[162:165], v[196:199], v[38:41]
	v_mfma_f32_16x16x32_bf16 v[30:33], v[154:157], v[204:207], v[30:33]
	v_mfma_f32_16x16x32_bf16 v[22:25], v[162:165], v[204:207], v[22:25]
	v_mfma_f32_16x16x32_bf16 v[14:17], v[154:157], v[212:215], v[14:17]
	v_mfma_f32_16x16x32_bf16 v[6:9], v[162:165], v[212:215], v[6:9]
	v_mfma_f32_16x16x32_bf16 v[62:65], v[158:161], v[192:195], v[62:65]
	v_mfma_f32_16x16x32_bf16 v[54:57], v[166:169], v[192:195], v[54:57]
	v_mfma_f32_16x16x32_bf16 v[46:49], v[158:161], v[200:203], v[46:49]
	v_mfma_f32_16x16x32_bf16 v[38:41], v[166:169], v[200:203], v[38:41]
	v_mfma_f32_16x16x32_bf16 v[30:33], v[158:161], v[208:211], v[30:33]
	v_mfma_f32_16x16x32_bf16 v[22:25], v[166:169], v[208:211], v[22:25]
	v_mfma_f32_16x16x32_bf16 v[14:17], v[158:161], v[216:219], v[14:17]
	v_mfma_f32_16x16x32_bf16 v[6:9], v[166:169], v[216:219], v[6:9]
	s_setprio 0
	s_setprio 1
	v_mfma_f32_16x16x32_bf16 v[58:61], v[170:173], v[186:189], v[58:61]
	v_mfma_f32_16x16x32_bf16 v[50:53], v[178:181], v[186:189], v[50:53]
	v_mfma_f32_16x16x32_bf16 v[42:45], v[170:173], v[196:199], v[42:45]
	v_mfma_f32_16x16x32_bf16 v[34:37], v[178:181], v[196:199], v[34:37]
	v_mfma_f32_16x16x32_bf16 v[26:29], v[170:173], v[204:207], v[26:29]
	v_mfma_f32_16x16x32_bf16 v[18:21], v[178:181], v[204:207], v[18:21]
	v_mfma_f32_16x16x32_bf16 v[10:13], v[170:173], v[212:215], v[10:13]
	v_mfma_f32_16x16x32_bf16 v[2:5], v[178:181], v[212:215], v[2:5]
	v_mfma_f32_16x16x32_bf16 v[58:61], v[174:177], v[192:195], v[58:61]
	v_mfma_f32_16x16x32_bf16 v[50:53], v[182:185], v[192:195], v[50:53]
	v_mfma_f32_16x16x32_bf16 v[42:45], v[174:177], v[200:203], v[42:45]
	v_mfma_f32_16x16x32_bf16 v[34:37], v[182:185], v[200:203], v[34:37]
	v_mfma_f32_16x16x32_bf16 v[26:29], v[174:177], v[208:211], v[26:29]
	v_mfma_f32_16x16x32_bf16 v[18:21], v[182:185], v[208:211], v[18:21]
	v_mfma_f32_16x16x32_bf16 v[10:13], v[174:177], v[216:219], v[10:13]
	v_mfma_f32_16x16x32_bf16 v[2:5], v[182:185], v[216:219], v[2:5]
	s_setprio 0
	s_add_i32 s51, s51, 2
	s_add_u32 s22, s22, 0x100
	s_addc_u32 s23, s23, 0
	s_add_u32 s49, s49, 0x100
	s_addc_u32 s50, s50, 0
	s_cmp_gt_u32 s51, 29
	s_barrier
	s_cbranch_scc0 .LBB0_1703
	s_and_b64 vcc, exec, s[10:11]
	s_cbranch_vccz .LBB0_1706
	s_barrier

; #define PG8_STAGE(bufoff, gbase, voff) do { _Pragma("unroll") for (int _i = 0; _i < 2; ++_i) \
;         __builtin_amdgcn_global_load_lds((const unsigned*)((const char*)(gbase) + (voff)[_i]), (PG8_LAS unsigned*)(lds + (bufoff) + ldsw + _i * 8192), 16, 0, 0); } while (0)
; #define PG8_STAGEB(bufoff, gbase, voff) do { _Pragma("unroll") for (int _i = 0; _i < 2; ++_i) \
;         __builtin_amdgcn_global_load_lds((const unsigned*)((const char*)(gbase) + (voff)[_i]), (PG8_LAS unsigned*)(lds + (bufoff) + ldsw + _i * 8192), 16, 0, PG8_BAUX); } while (0)
; #define PG8_LDA(dst, b, h) do { _Pragma("unroll") for (int m = 0; m < 4; ++m) _Pragma("unroll") for (int k = 0; k < 2; ++k) dst[m][k] = *(const PG8_LAS bf16x8*)(lds + PG8_SA(b, h) + aoff + m * 2048 + k * 1024); } while (0)
; #define PG8_LDB(dst, b, h) do { _Pragma("unroll") for (int n = 0; n < 2; ++n) _Pragma("unroll") for (int k = 0; k < 2; ++k) dst[n][k] = *(const PG8_LAS bf16x8*)(lds + PG8_SB(b, h) + boff + n * 2048 + k * 1024); } while (0)
; #define PG8_MMA(ai, bj, At, Bt) do { __builtin_amdgcn_s_setprio(1); _Pragma("unroll") for (int m = 0; m < 4; ++m) _Pragma("unroll") for (int n = 0; n < 2; ++n) _Pragma("unroll") for (int k = 0; k < 2; ++k) \
;         acc[ai][bj][m][n] = __builtin_amdgcn_mfma_f32_16x16x32_bf16(Bt[n][k], At[m][k], acc[ai][bj][m][n], 0, 0, 0); __builtin_amdgcn_s_setprio(0); } while (0)
; template <class Epi, class Sched, bool ALIGN_EPI = false, bool SP2 = false>
; __device__ __forceinline__ void gemm_phase(PG8_LAS unsigned char* lds, const Gemm g, const Sched& S, const Epi& E) {
;     ...
;             const bool last = (t == nt - 2);
;             const char* a1 = cA + (size_t)(t + 1) * kstep;
;             const char* a2 = last ? nA : cA + (size_t)(t + 2) * kstep; const char* b2 = last ? nB : cB + (size_t)(t + 2) * kstep;
;             const char* a3 = a2 + kstep; const char* b3 = b2 + kstep;
;             if (last && has_next) S.a_ready(nxt);
;             if constexpr (SP2) {
;             PG8_LDB(B0, 0, 0); PG8_LDB(B1, 0, 1); PG8_SCHED; PG8_LDA(At, 0, 0); PG8_STAGE(PG8_SA(1, 1), a1 + hstep, voffA);
;             PG8_WAIT_V(8); PG8_WAIT_L(0); PG8_BAR; PG8_MMA(0, 0, At, B0); PG8_MMA(0, 1, At, B1); PG8_BAR; PG8_SCHED;
;             PG8_LDA(At, 0, 1); PG8_STAGEB(PG8_SB(0, 0), b2, voffB); PG8_STAGEB(PG8_SB(0, 1), b2 + hstep, voffB); PG8_STAGE(PG8_SA(0, 0), a2, voffA);
.LBB0_1906:
	v_add_u32_e32 v153, s43, v151
	ds_read_b128 v[154:157], v153
	ds_read_b128 v[158:161], v153 offset:1024
	ds_read_b128 v[166:169], v153 offset:2048
	ds_read_b128 v[170:173], v153 offset:3072
	v_add_u32_e32 v153, s44, v151
	s_add_u32 s22, s12, s20
	ds_read_b128 v[174:177], v153
	ds_read_b128 v[178:181], v153 offset:1024
	ds_read_b128 v[182:185], v153 offset:2048
	ds_read_b128 v[186:189], v153 offset:3072
	s_addc_u32 s23, s13, s21
	s_add_u32 s22, s22, 0x100
	s_addc_u32 s23, s23, 0
	s_add_u32 s49, s17, s20
	s_addc_u32 s50, s47, s21
	s_cmpk_eq_i32 s20, 0x2b00
	s_cselect_b32 s25, s19, s23
	s_cselect_b32 s24, s18, s22
	s_cselect_b32 s23, s5, s50
	s_cselect_b32 s22, s4, s49
	v_lshl_add_u64 v[162:163], v[146:147], 0, s[20:21]
	s_add_i32 m0, s34, 0xc000
	ds_read_b128 v[192:195], v152
	ds_read_b128 v[196:199], v152 offset:1024
	ds_read_b128 v[200:203], v152 offset:2048
	ds_read_b128 v[204:207], v152 offset:3072
	ds_read_b128 v[208:211], v152 offset:4096
	ds_read_b128 v[212:215], v152 offset:5120
	ds_read_b128 v[216:219], v152 offset:6144
	ds_read_b128 v[220:223], v152 offset:7168
	global_load_lds_dwordx4 v[162:163], off
	v_lshl_add_u64 v[162:163], v[148:149], 0, s[20:21]
	s_add_i32 m0, s34, 0xe000
	s_nop 0
	global_load_lds_dwordx4 v[162:163], off
	s_waitcnt vmcnt(8)
	s_waitcnt lgkmcnt(0)
	s_barrier
	s_setprio 1
	s_waitcnt lgkmcnt(0)
	v_mfma_f32_16x16x32_bf16 v[126:129], v[154:157], v[192:195], v[126:129]
	v_mfma_f32_16x16x32_bf16 v[122:125], v[166:169], v[192:195], v[122:125]
	v_mfma_f32_16x16x32_bf16 v[110:113], v[154:157], v[200:203], v[110:113]
	v_mfma_f32_16x16x32_bf16 v[106:109], v[166:169], v[200:203], v[106:109]
	v_mfma_f32_16x16x32_bf16 v[94:97], v[154:157], v[208:211], v[94:97]
	v_mfma_f32_16x16x32_bf16 v[90:93], v[166:169], v[208:211], v[90:93]
	v_mfma_f32_16x16x32_bf16 v[78:81], v[154:157], v[216:219], v[78:81]
	v_mfma_f32_16x16x32_bf16 v[74:77], v[166:169], v[216:219], v[74:77]
	v_mfma_f32_16x16x32_bf16 v[126:129], v[158:161], v[196:199], v[126:129]
	v_mfma_f32_16x16x32_bf16 v[122:125], v[170:173], v[196:199], v[122:125]
	v_mfma_f32_16x16x32_bf16 v[110:113], v[158:161], v[204:207], v[110:113]
	v_mfma_f32_16x16x32_bf16 v[106:109], v[170:173], v[204:207], v[106:109]
	v_mfma_f32_16x16x32_bf16 v[94:97], v[158:161], v[212:215], v[94:97]
	v_mfma_f32_16x16x32_bf16 v[90:93], v[170:173], v[212:215], v[90:93]
	v_mfma_f32_16x16x32_bf16 v[78:81], v[158:161], v[220:223], v[78:81]
	v_mfma_f32_16x16x32_bf16 v[74:77], v[170:173], v[220:223], v[74:77]
	s_setprio 0
	s_setprio 1
	v_mfma_f32_16x16x32_bf16 v[118:121], v[174:177], v[192:195], v[118:121]
	v_mfma_f32_16x16x32_bf16 v[114:117], v[182:185], v[192:195], v[114:117]
	v_mfma_f32_16x16x32_bf16 v[102:105], v[174:177], v[200:203], v[102:105]
	v_mfma_f32_16x16x32_bf16 v[98:101], v[182:185], v[200:203], v[98:101]
	v_mfma_f32_16x16x32_bf16 v[86:89], v[174:177], v[208:211], v[86:89]
	v_mfma_f32_16x16x32_bf16 v[82:85], v[182:185], v[208:211], v[82:85]
	v_mfma_f32_16x16x32_bf16 v[70:73], v[174:177], v[216:219], v[70:73]
	v_mfma_f32_16x16x32_bf16 v[66:69], v[182:185], v[216:219], v[66:69]
	v_mfma_f32_16x16x32_bf16 v[118:121], v[178:181], v[196:199], v[118:121]
	v_mfma_f32_16x16x32_bf16 v[114:117], v[186:189], v[196:199], v[114:117]
	v_mfma_f32_16x16x32_bf16 v[102:105], v[178:181], v[204:207], v[102:105]
	v_mfma_f32_16x16x32_bf16 v[98:101], v[186:189], v[204:207], v[98:101]
	v_mfma_f32_16x16x32_bf16 v[86:89], v[178:181], v[212:215], v[86:89]
	v_mfma_f32_16x16x32_bf16 v[82:85], v[186:189], v[212:215], v[82:85]
	v_mfma_f32_16x16x32_bf16 v[70:73], v[178:181], v[220:223], v[70:73]
	v_mfma_f32_16x16x32_bf16 v[66:69], v[186:189], v[220:223], v[66:69]
	s_setprio 0
	s_barrier
	s_add_i32 s49, s43, s30
	v_lshl_add_u64 v[162:163], s[22:23], 0, v[132:133]
	s_mov_b32 m0, s49
	ds_read_b128 v[192:195], v152 offset:16384
	ds_read_b128 v[196:199], v152 offset:17408
	ds_read_b128 v[200:203], v152 offset:18432
	ds_read_b128 v[204:207], v152 offset:19456
	ds_read_b128 v[208:211], v152 offset:20480
	ds_read_b128 v[212:215], v152 offset:21504
	ds_read_b128 v[216:219], v152 offset:22528
	ds_read_b128 v[220:223], v152 offset:23552
	global_load_lds_dwordx4 v[162:163], off
	s_add_i32 m0, s49, 0x2000
	s_add_u32 s50, s22, 0x160000
	v_lshl_add_u64 v[224:225], s[22:23], 0, v[136:137]
	s_addc_u32 s51, s23, 0
	s_add_i32 s49, s44, s30
	global_load_lds_dwordx4 v[224:225], off
	v_lshl_add_u64 v[226:227], s[50:51], 0, v[132:133]
	s_mov_b32 m0, s49
	v_lshl_add_u64 v[228:229], s[24:25], 0, v[134:135]
	global_load_lds_dwordx4 v[226:227], off
	v_lshl_add_u64 v[226:227], s[50:51], 0, v[136:137]
	s_add_i32 m0, s49, 0x2000
	s_nop 0
	global_load_lds_dwordx4 v[226:227], off
	v_lshl_add_u64 v[226:227], s[24:25], 0, v[130:131]
	s_mov_b32 m0, s34
	s_nop 0
	global_load_lds_dwordx4 v[226:227], off
	s_mov_b32 m0, s35
	s_nop 0
	global_load_lds_dwordx4 v[228:229], off
	s_waitcnt vmcnt(8)
	s_waitcnt lgkmcnt(0)
	s_barrier
; #define PG8_STAGE(bufoff, gbase, voff) do { _Pragma("unroll") for (int _i = 0; _i < 2; ++_i) \
;         __builtin_amdgcn_global_load_lds((const unsigned*)((const char*)(gbase) + (voff)[_i]), (PG8_LAS unsigned*)(lds + (bufoff) + ldsw + _i * 8192), 16, 0, 0); } while (0)
; #define PG8_LDA(dst, b, h) do { _Pragma("unroll") for (int m = 0; m < 4; ++m) _Pragma("unroll") for (int k = 0; k < 2; ++k) dst[m][k] = *(const PG8_LAS bf16x8*)(lds + PG8_SA(b, h) + aoff + m * 2048 + k * 1024); } while (0)
; #define PG8_LDB(dst, b, h) do { _Pragma("unroll") for (int n = 0; n < 2; ++n) _Pragma("unroll") for (int k = 0; k < 2; ++k) dst[n][k] = *(const PG8_LAS bf16x8*)(lds + PG8_SB(b, h) + boff + n * 2048 + k * 1024); } while (0)
; #define PG8_MMA(ai, bj, At, Bt) do { __builtin_amdgcn_s_setprio(1); _Pragma("unroll") for (int m = 0; m < 4; ++m) _Pragma("unroll") for (int n = 0; n < 2; ++n) _Pragma("unroll") for (int k = 0; k < 2; ++k) \
;         acc[ai][bj][m][n] = __builtin_amdgcn_mfma_f32_16x16x32_bf16(Bt[n][k], At[m][k], acc[ai][bj][m][n], 0, 0, 0); __builtin_amdgcn_s_setprio(0); } while (0)
; #define PG8_WAIT_V(n) asm volatile("s_waitcnt vmcnt(" #n ")" ::: "memory")
; #define PG8_WAIT_L(n) asm volatile("s_waitcnt lgkmcnt(" #n ")" ::: "memory")
; #define PG8_BAR __builtin_amdgcn_s_barrier()
; #define PG8_SCHED __builtin_amdgcn_sched_barrier(0)
; template <class Epi, class Sched, bool ALIGN_EPI = false, bool SP2 = false>
; __device__ __forceinline__ void gemm_phase(PG8_LAS unsigned char* lds, const Gemm g, const Sched& S, const Epi& E) {
;     ...
;             PG8_WAIT_V(8); PG8_WAIT_L(0); PG8_BAR; PG8_MMA(1, 0, At, B0); PG8_MMA(1, 1, At, B1); PG8_BAR; PG8_SCHED;
;             PG8_LDB(B0, 1, 0); PG8_LDB(B1, 1, 1); PG8_SCHED; PG8_LDA(At, 1, 0); PG8_STAGE(PG8_SA(0, 1), a2 + hstep, voffA);
;             PG8_WAIT_V(8); PG8_WAIT_L(0); PG8_BAR; PG8_MMA(0, 0, At, B0); PG8_MMA(0, 1, At, B1); PG8_BAR; PG8_SCHED;
	s_setprio 1
	s_waitcnt lgkmcnt(0)
	v_mfma_f32_16x16x32_bf16 v[62:65], v[154:157], v[192:195], v[62:65]
	v_mfma_f32_16x16x32_bf16 v[58:61], v[166:169], v[192:195], v[58:61]
	v_mfma_f32_16x16x32_bf16 v[46:49], v[154:157], v[200:203], v[46:49]
	v_mfma_f32_16x16x32_bf16 v[42:45], v[166:169], v[200:203], v[42:45]
	v_mfma_f32_16x16x32_bf16 v[30:33], v[154:157], v[208:211], v[30:33]
	v_mfma_f32_16x16x32_bf16 v[26:29], v[166:169], v[208:211], v[26:29]
	v_mfma_f32_16x16x32_bf16 v[14:17], v[154:157], v[216:219], v[14:17]
	v_mfma_f32_16x16x32_bf16 v[10:13], v[166:169], v[216:219], v[10:13]
	v_mfma_f32_16x16x32_bf16 v[62:65], v[158:161], v[196:199], v[62:65]
	v_mfma_f32_16x16x32_bf16 v[58:61], v[170:173], v[196:199], v[58:61]
	v_mfma_f32_16x16x32_bf16 v[46:49], v[158:161], v[204:207], v[46:49]
	v_mfma_f32_16x16x32_bf16 v[42:45], v[170:173], v[204:207], v[42:45]
	v_mfma_f32_16x16x32_bf16 v[30:33], v[158:161], v[212:215], v[30:33]
	v_mfma_f32_16x16x32_bf16 v[26:29], v[170:173], v[212:215], v[26:29]
	v_mfma_f32_16x16x32_bf16 v[14:17], v[158:161], v[220:223], v[14:17]
	v_mfma_f32_16x16x32_bf16 v[10:13], v[170:173], v[220:223], v[10:13]
	s_setprio 0
	s_setprio 1
	v_mfma_f32_16x16x32_bf16 v[54:57], v[174:177], v[192:195], v[54:57]
	v_mfma_f32_16x16x32_bf16 v[50:53], v[182:185], v[192:195], v[50:53]
	v_mfma_f32_16x16x32_bf16 v[38:41], v[174:177], v[200:203], v[38:41]
	v_mfma_f32_16x16x32_bf16 v[34:37], v[182:185], v[200:203], v[34:37]
	v_mfma_f32_16x16x32_bf16 v[22:25], v[174:177], v[208:211], v[22:25]
	v_mfma_f32_16x16x32_bf16 v[18:21], v[182:185], v[208:211], v[18:21]
	v_mfma_f32_16x16x32_bf16 v[6:9], v[174:177], v[216:219], v[6:9]
	v_mfma_f32_16x16x32_bf16 v[2:5], v[182:185], v[216:219], v[2:5]
	v_mfma_f32_16x16x32_bf16 v[54:57], v[178:181], v[196:199], v[54:57]
	v_mfma_f32_16x16x32_bf16 v[50:53], v[186:189], v[196:199], v[50:53]
	v_mfma_f32_16x16x32_bf16 v[38:41], v[178:181], v[204:207], v[38:41]
	v_mfma_f32_16x16x32_bf16 v[34:37], v[186:189], v[204:207], v[34:37]
	v_mfma_f32_16x16x32_bf16 v[22:25], v[178:181], v[212:215], v[22:25]
	v_mfma_f32_16x16x32_bf16 v[18:21], v[186:189], v[212:215], v[18:21]
	v_mfma_f32_16x16x32_bf16 v[6:9], v[178:181], v[220:223], v[6:9]
	v_mfma_f32_16x16x32_bf16 v[2:5], v[186:189], v[220:223], v[2:5]
	s_setprio 0
	s_barrier
	s_add_i32 s49, 0, 0x18000
	v_add_u32_e32 v153, s49, v151
	s_add_i32 s50, 0, 0x1c000
	ds_read_b128 v[154:157], v153
	ds_read_b128 v[158:161], v153 offset:1024
	ds_read_b128 v[166:169], v153 offset:2048
	ds_read_b128 v[170:173], v153 offset:3072
	v_add_u32_e32 v153, s50, v151
	ds_read_b128 v[174:177], v153
	ds_read_b128 v[178:181], v153 offset:1024
	ds_read_b128 v[182:185], v153 offset:2048
	ds_read_b128 v[186:189], v153 offset:3072
	s_add_u32 s24, s24, 0x160000
	s_addc_u32 s25, s25, 0
	s_mov_b32 m0, s38
	v_lshl_add_u64 v[230:231], s[24:25], 0, v[130:131]
	ds_read_b128 v[192:195], v152 offset:32768
	ds_read_b128 v[196:199], v152 offset:33792
	ds_read_b128 v[200:203], v152 offset:34816
	ds_read_b128 v[204:207], v152 offset:35840
	ds_read_b128 v[208:211], v152 offset:36864
	ds_read_b128 v[212:215], v152 offset:37888
	ds_read_b128 v[216:219], v152 offset:38912
	ds_read_b128 v[220:223], v152 offset:39936
	global_load_lds_dwordx4 v[230:231], off
	v_lshl_add_u64 v[230:231], s[24:25], 0, v[134:135]
	s_mov_b32 m0, s39
	s_nop 0
	global_load_lds_dwordx4 v[230:231], off
	s_waitcnt vmcnt(8)
	s_waitcnt lgkmcnt(0)
	s_barrier
	s_setprio 1
	s_waitcnt lgkmcnt(0)
	v_mfma_f32_16x16x32_bf16 v[126:129], v[154:157], v[192:195], v[126:129]
	v_mfma_f32_16x16x32_bf16 v[122:125], v[166:169], v[192:195], v[122:125]
	v_mfma_f32_16x16x32_bf16 v[110:113], v[154:157], v[200:203], v[110:113]
	v_mfma_f32_16x16x32_bf16 v[106:109], v[166:169], v[200:203], v[106:109]
	v_mfma_f32_16x16x32_bf16 v[94:97], v[154:157], v[208:211], v[94:97]
	v_mfma_f32_16x16x32_bf16 v[90:93], v[166:169], v[208:211], v[90:93]
	v_mfma_f32_16x16x32_bf16 v[78:81], v[154:157], v[216:219], v[78:81]
	v_mfma_f32_16x16x32_bf16 v[74:77], v[166:169], v[216:219], v[74:77]
	v_mfma_f32_16x16x32_bf16 v[126:129], v[158:161], v[196:199], v[126:129]
	v_mfma_f32_16x16x32_bf16 v[122:125], v[170:173], v[196:199], v[122:125]
	v_mfma_f32_16x16x32_bf16 v[110:113], v[158:161], v[204:207], v[110:113]
	v_mfma_f32_16x16x32_bf16 v[106:109], v[170:173], v[204:207], v[106:109]
	v_mfma_f32_16x16x32_bf16 v[94:97], v[158:161], v[212:215], v[94:97]
	v_mfma_f32_16x16x32_bf16 v[90:93], v[170:173], v[212:215], v[90:93]
	v_mfma_f32_16x16x32_bf16 v[78:81], v[158:161], v[220:223], v[78:81]
	v_mfma_f32_16x16x32_bf16 v[74:77], v[170:173], v[220:223], v[74:77]
	s_setprio 0
	s_setprio 1
	v_mfma_f32_16x16x32_bf16 v[118:121], v[174:177], v[192:195], v[118:121]
	v_mfma_f32_16x16x32_bf16 v[114:117], v[182:185], v[192:195], v[114:117]
	v_mfma_f32_16x16x32_bf16 v[102:105], v[174:177], v[200:203], v[102:105]
	v_mfma_f32_16x16x32_bf16 v[98:101], v[182:185], v[200:203], v[98:101]
	v_mfma_f32_16x16x32_bf16 v[86:89], v[174:177], v[208:211], v[86:89]
	v_mfma_f32_16x16x32_bf16 v[82:85], v[182:185], v[208:211], v[82:85]
	v_mfma_f32_16x16x32_bf16 v[70:73], v[174:177], v[216:219], v[70:73]
	v_mfma_f32_16x16x32_bf16 v[66:69], v[182:185], v[216:219], v[66:69]
	v_mfma_f32_16x16x32_bf16 v[118:121], v[178:181], v[196:199], v[118:121]
	v_mfma_f32_16x16x32_bf16 v[114:117], v[186:189], v[196:199], v[114:117]
	v_mfma_f32_16x16x32_bf16 v[102:105], v[178:181], v[204:207], v[102:105]
	v_mfma_f32_16x16x32_bf16 v[98:101], v[186:189], v[204:207], v[98:101]
	v_mfma_f32_16x16x32_bf16 v[86:89], v[178:181], v[212:215], v[86:89]
	v_mfma_f32_16x16x32_bf16 v[82:85], v[186:189], v[212:215], v[82:85]
	v_mfma_f32_16x16x32_bf16 v[70:73], v[178:181], v[220:223], v[70:73]
	v_mfma_f32_16x16x32_bf16 v[66:69], v[186:189], v[220:223], v[66:69]
	s_setprio 0
	s_barrier
; #define PG8_STAGE(bufoff, gbase, voff) do { _Pragma("unroll") for (int _i = 0; _i < 2; ++_i) \
;         __builtin_amdgcn_global_load_lds((const unsigned*)((const char*)(gbase) + (voff)[_i]), (PG8_LAS unsigned*)(lds + (bufoff) + ldsw + _i * 8192), 16, 0, 0); } while (0)
; #define PG8_STAGEB(bufoff, gbase, voff) do { _Pragma("unroll") for (int _i = 0; _i < 2; ++_i) \
;         __builtin_amdgcn_global_load_lds((const unsigned*)((const char*)(gbase) + (voff)[_i]), (PG8_LAS unsigned*)(lds + (bufoff) + ldsw + _i * 8192), 16, 0, PG8_BAUX); } while (0)
; #define PG8_LDA(dst, b, h) do { _Pragma("unroll") for (int m = 0; m < 4; ++m) _Pragma("unroll") for (int k = 0; k < 2; ++k) dst[m][k] = *(const PG8_LAS bf16x8*)(lds + PG8_SA(b, h) + aoff + m * 2048 + k * 1024); } while (0)
; #define PG8_MMA(ai, bj, At, Bt) do { __builtin_amdgcn_s_setprio(1); _Pragma("unroll") for (int m = 0; m < 4; ++m) _Pragma("unroll") for (int n = 0; n < 2; ++n) _Pragma("unroll") for (int k = 0; k < 2; ++k) \
;         acc[ai][bj][m][n] = __builtin_amdgcn_mfma_f32_16x16x32_bf16(Bt[n][k], At[m][k], acc[ai][bj][m][n], 0, 0, 0); __builtin_amdgcn_s_setprio(0); } while (0)
; #define PG8_WAIT_V(n) asm volatile("s_waitcnt vmcnt(" #n ")" ::: "memory")
; #define PG8_WAIT_L(n) asm volatile("s_waitcnt lgkmcnt(" #n ")" ::: "memory")
; #define PG8_BAR __builtin_amdgcn_s_barrier()
; #define PG8_SCHED __builtin_amdgcn_sched_barrier(0)
; template <class Epi, class Sched, bool ALIGN_EPI = false, bool SP2 = false>
; __device__ __forceinline__ void gemm_phase(PG8_LAS unsigned char* lds, const Gemm g, const Sched& S, const Epi& E) {
;     ...
;             PG8_LDA(At, 1, 1); PG8_STAGEB(PG8_SB(1, 0), b3, voffB); PG8_STAGEB(PG8_SB(1, 1), b3 + hstep, voffB); PG8_STAGE(PG8_SA(1, 0), a3, voffA);
;             PG8_WAIT_V(8); PG8_WAIT_L(0); PG8_BAR; PG8_MMA(1, 0, At, B0); PG8_MMA(1, 1, At, B1); PG8_BAR; PG8_SCHED;
;     ...
;         if (!has_next) break;
; #pragma unroll
;         for (int a = 0; a < 2; ++a)
; #pragma unroll
;             for (int b = 0; b < 2; ++b)
; #pragma unroll
;                 for (int m = 0; m < 4; ++m)
; #pragma unroll
;                     for (int n = 0; n < 2; ++n) acc[a][b][m][n] = (f32x4){0.f, 0.f, 0.f, 0.f};
;         cur = nxt; cA = nA; cB = nB; ++ui;
	s_add_i32 s24, s49, s30
	v_lshl_add_u64 v[162:163], v[162:163], 0, s[14:15]
	s_mov_b32 m0, s24
	ds_read_b128 v[192:195], v152 offset:49152
	ds_read_b128 v[196:199], v152 offset:50176
	ds_read_b128 v[200:203], v152 offset:51200
	ds_read_b128 v[204:207], v152 offset:52224
	ds_read_b128 v[208:211], v152 offset:53248
	ds_read_b128 v[212:215], v152 offset:54272
	ds_read_b128 v[216:219], v152 offset:55296
	ds_read_b128 v[220:223], v152 offset:56320
	global_load_lds_dwordx4 v[162:163], off
	s_add_i32 m0, s24, 0x2000
	s_add_u32 s22, s22, 0x160080
	v_lshl_add_u64 v[162:163], v[224:225], 0, s[14:15]
	s_addc_u32 s23, s23, 0
	s_add_i32 s24, s50, s30
	global_load_lds_dwordx4 v[162:163], off
	v_lshl_add_u64 v[162:163], s[22:23], 0, v[132:133]
	s_mov_b32 m0, s24
	s_nop 0
	global_load_lds_dwordx4 v[162:163], off
	v_lshl_add_u64 v[162:163], s[22:23], 0, v[136:137]
	s_add_i32 m0, s24, 0x2000
	s_nop 0
	global_load_lds_dwordx4 v[162:163], off
	v_lshl_add_u64 v[162:163], v[226:227], 0, s[14:15]
	s_mov_b32 m0, s40
	s_nop 0
	global_load_lds_dwordx4 v[162:163], off
	v_lshl_add_u64 v[162:163], v[228:229], 0, s[14:15]
	s_mov_b32 m0, s41
	s_nop 0
	global_load_lds_dwordx4 v[162:163], off
	s_waitcnt vmcnt(8)
	s_waitcnt lgkmcnt(0)
	s_barrier
	s_setprio 1
	s_waitcnt lgkmcnt(0)
	v_mfma_f32_16x16x32_bf16 v[62:65], v[154:157], v[192:195], v[62:65]
	v_mfma_f32_16x16x32_bf16 v[58:61], v[166:169], v[192:195], v[58:61]
	v_mfma_f32_16x16x32_bf16 v[46:49], v[154:157], v[200:203], v[46:49]
	v_mfma_f32_16x16x32_bf16 v[42:45], v[166:169], v[200:203], v[42:45]
	v_mfma_f32_16x16x32_bf16 v[30:33], v[154:157], v[208:211], v[30:33]
	v_mfma_f32_16x16x32_bf16 v[26:29], v[166:169], v[208:211], v[26:29]
	v_mfma_f32_16x16x32_bf16 v[14:17], v[154:157], v[216:219], v[14:17]
	v_mfma_f32_16x16x32_bf16 v[10:13], v[166:169], v[216:219], v[10:13]
	v_mfma_f32_16x16x32_bf16 v[62:65], v[158:161], v[196:199], v[62:65]
	v_mfma_f32_16x16x32_bf16 v[58:61], v[170:173], v[196:199], v[58:61]
	v_mfma_f32_16x16x32_bf16 v[46:49], v[158:161], v[204:207], v[46:49]
	v_mfma_f32_16x16x32_bf16 v[42:45], v[170:173], v[204:207], v[42:45]
	v_mfma_f32_16x16x32_bf16 v[30:33], v[158:161], v[212:215], v[30:33]
	v_mfma_f32_16x16x32_bf16 v[26:29], v[170:173], v[212:215], v[26:29]
	v_mfma_f32_16x16x32_bf16 v[14:17], v[158:161], v[220:223], v[14:17]
	v_mfma_f32_16x16x32_bf16 v[10:13], v[170:173], v[220:223], v[10:13]
	s_setprio 0
	s_setprio 1
	v_mfma_f32_16x16x32_bf16 v[54:57], v[174:177], v[192:195], v[54:57]
	v_mfma_f32_16x16x32_bf16 v[50:53], v[182:185], v[192:195], v[50:53]
	v_mfma_f32_16x16x32_bf16 v[38:41], v[174:177], v[200:203], v[38:41]
	v_mfma_f32_16x16x32_bf16 v[34:37], v[182:185], v[200:203], v[34:37]
	v_mfma_f32_16x16x32_bf16 v[22:25], v[174:177], v[208:211], v[22:25]
	v_mfma_f32_16x16x32_bf16 v[18:21], v[182:185], v[208:211], v[18:21]
	v_mfma_f32_16x16x32_bf16 v[6:9], v[174:177], v[216:219], v[6:9]
	v_mfma_f32_16x16x32_bf16 v[2:5], v[182:185], v[216:219], v[2:5]
	v_mfma_f32_16x16x32_bf16 v[54:57], v[178:181], v[196:199], v[54:57]
	v_mfma_f32_16x16x32_bf16 v[50:53], v[186:189], v[196:199], v[50:53]
	v_mfma_f32_16x16x32_bf16 v[38:41], v[178:181], v[204:207], v[38:41]
	v_mfma_f32_16x16x32_bf16 v[34:37], v[186:189], v[204:207], v[34:37]
	v_mfma_f32_16x16x32_bf16 v[22:25], v[178:181], v[212:215], v[22:25]
	v_mfma_f32_16x16x32_bf16 v[18:21], v[186:189], v[212:215], v[18:21]
	v_mfma_f32_16x16x32_bf16 v[6:9], v[178:181], v[220:223], v[6:9]
	v_mfma_f32_16x16x32_bf16 v[2:5], v[186:189], v[220:223], v[2:5]
	s_setprio 0
	s_add_i32 s48, s48, 2
	s_add_u32 s20, s20, 0x100
	s_addc_u32 s21, s21, 0
	s_cmpk_gt_u32 s48, 0x55
	s_barrier
	s_cbranch_scc0 .LBB0_1906
	s_add_u32 s20, s17, 0xffffff00
	s_addc_u32 s21, s47, -1
	s_and_b64 vcc, exec, s[2:3]
	s_cbranch_vccnz .LBB0_1893
	v_mov_b32_e32 v2, 0
	s_mov_b32 s10, s45
	s_mov_b32 s27, s46
	s_mov_b64 s[12:13], s[18:19]
	s_mov_b32 s42, s16
	v_mov_b32_e32 v3, v2
	v_mov_b32_e32 v4, v2
	v_mov_b32_e32 v5, v2
	v_mov_b32_e32 v6, v2
	v_mov_b32_e32 v7, v2
	v_mov_b32_e32 v8, v2
	v_mov_b32_e32 v9, v2
	v_mov_b32_e32 v18, v2
	v_mov_b32_e32 v19, v2
	v_mov_b32_e32 v20, v2
	v_mov_b32_e32 v21, v2
	v_mov_b32_e32 v22, v2
	v_mov_b32_e32 v23, v2
	v_mov_b32_e32 v24, v2
	v_mov_b32_e32 v25, v2
	v_mov_b32_e32 v34, v2
	v_mov_b32_e32 v35, v2
	v_mov_b32_e32 v36, v2
	v_mov_b32_e32 v37, v2
	v_mov_b32_e32 v38, v2
	v_mov_b32_e32 v39, v2
	v_mov_b32_e32 v40, v2
	v_mov_b32_e32 v41, v2
	v_mov_b32_e32 v50, v2
	v_mov_b32_e32 v51, v2
	v_mov_b32_e32 v52, v2
	v_mov_b32_e32 v53, v2
	v_mov_b32_e32 v54, v2
	v_mov_b32_e32 v55, v2
	v_mov_b32_e32 v56, v2
	v_mov_b32_e32 v57, v2
	v_mov_b32_e32 v10, v2
	v_mov_b32_e32 v11, v2
	v_mov_b32_e32 v12, v2
	v_mov_b32_e32 v13, v2
	v_mov_b32_e32 v14, v2
	v_mov_b32_e32 v15, v2
	v_mov_b32_e32 v16, v2
	v_mov_b32_e32 v17, v2
	v_mov_b32_e32 v26, v2
	v_mov_b32_e32 v27, v2
	v_mov_b32_e32 v28, v2
	v_mov_b32_e32 v29, v2
	v_mov_b32_e32 v30, v2
	v_mov_b32_e32 v31, v2
	v_mov_b32_e32 v32, v2
	v_mov_b32_e32 v33, v2
	v_mov_b32_e32 v42, v2
	v_mov_b32_e32 v43, v2
	v_mov_b32_e32 v44, v2
	v_mov_b32_e32 v45, v2
	v_mov_b32_e32 v46, v2
	v_mov_b32_e32 v47, v2
	v_mov_b32_e32 v48, v2
	v_mov_b32_e32 v49, v2
	v_mov_b32_e32 v58, v2
	v_mov_b32_e32 v59, v2
	v_mov_b32_e32 v60, v2
	v_mov_b32_e32 v61, v2
	v_mov_b32_e32 v62, v2
	v_mov_b32_e32 v63, v2
	v_mov_b32_e32 v64, v2
	v_mov_b32_e32 v65, v2
	v_mov_b32_e32 v66, v2
	v_mov_b32_e32 v67, v2
	v_mov_b32_e32 v68, v2
	v_mov_b32_e32 v69, v2
	v_mov_b32_e32 v70, v2
	v_mov_b32_e32 v71, v2
	v_mov_b32_e32 v72, v2
	v_mov_b32_e32 v73, v2
	v_mov_b32_e32 v82, v2
	v_mov_b32_e32 v83, v2
	v_mov_b32_e32 v84, v2
	v_mov_b32_e32 v85, v2
	v_mov_b32_e32 v86, v2
	v_mov_b32_e32 v87, v2
	v_mov_b32_e32 v88, v2
	v_mov_b32_e32 v89, v2
	v_mov_b32_e32 v98, v2
	v_mov_b32_e32 v99, v2
	v_mov_b32_e32 v100, v2
	v_mov_b32_e32 v101, v2
	v_mov_b32_e32 v102, v2
	v_mov_b32_e32 v103, v2
	v_mov_b32_e32 v104, v2
	v_mov_b32_e32 v105, v2
	v_mov_b32_e32 v114, v2
	v_mov_b32_e32 v115, v2
	v_mov_b32_e32 v116, v2
	v_mov_b32_e32 v117, v2
	v_mov_b32_e32 v118, v2
	v_mov_b32_e32 v119, v2
	v_mov_b32_e32 v120, v2
	v_mov_b32_e32 v121, v2
	v_mov_b32_e32 v74, v2
	v_mov_b32_e32 v75, v2
	v_mov_b32_e32 v76, v2
	v_mov_b32_e32 v77, v2
	v_mov_b32_e32 v78, v2
	v_mov_b32_e32 v79, v2
	v_mov_b32_e32 v80, v2
	v_mov_b32_e32 v81, v2
	v_mov_b32_e32 v90, v2
	v_mov_b32_e32 v91, v2
	v_mov_b32_e32 v92, v2
	v_mov_b32_e32 v93, v2
	v_mov_b32_e32 v94, v2
	v_mov_b32_e32 v95, v2
	v_mov_b32_e32 v96, v2
	v_mov_b32_e32 v97, v2
	v_mov_b32_e32 v106, v2
	v_mov_b32_e32 v107, v2
	v_mov_b32_e32 v108, v2
	v_mov_b32_e32 v109, v2
	v_mov_b32_e32 v110, v2
	v_mov_b32_e32 v111, v2
	v_mov_b32_e32 v112, v2
	v_mov_b32_e32 v113, v2
	v_mov_b32_e32 v122, v2
	v_mov_b32_e32 v123, v2
	v_mov_b32_e32 v124, v2
	v_mov_b32_e32 v125, v2
	v_mov_b32_e32 v126, v2
	v_mov_b32_e32 v127, v2
	v_mov_b32_e32 v128, v2
	v_mov_b32_e32 v129, v2
	s_andn2_b64 vcc, exec, s[0:1]
	s_cbranch_vccnz .LBB0_1894
